# variant of v18: the moved tail instructions spread one per MFMA gap starting after the 9th MFMA
# speedup vs baseline: 1.0083x; 1.0083x over previous
; #define PG8_STAGE(bufoff, gbase) do { _Pragma("unroll") for (int _i = 0; _i < 2; ++_i) \
;         __builtin_amdgcn_global_load_lds((const unsigned*)((const char*)(gbase) + voff[_i]), (LAS unsigned*)(lds + (bufoff) + ldsw + _i * 8192), 16, 0, 0); } while (0)
; #define PG8_LDA(dst, b, h) do { _Pragma("unroll") for (int m = 0; m < 4; ++m) _Pragma("unroll") for (int k = 0; k < 2; ++k) dst[m][k] = *(const LAS bf16x8*)(lds + PG8_SA(b, h) + aoff + m * 2048 + k * 1024); } while (0)
; #define PG8_LDB(dst, b, h) do { _Pragma("unroll") for (int n = 0; n < 2; ++n) _Pragma("unroll") for (int k = 0; k < 2; ++k) dst[n][k] = *(const LAS bf16x8*)(lds + PG8_SB(b, h) + boff + n * 2048 + k * 1024); } while (0)
; #define PG8_MMA(ai, bj, At, Bt) do { __builtin_amdgcn_s_setprio(1); _Pragma("unroll") for (int m = 0; m < 4; ++m) _Pragma("unroll") for (int n = 0; n < 2; ++n) _Pragma("unroll") for (int k = 0; k < 2; ++k) \
;         acc[ai][bj][m][n] = __builtin_amdgcn_mfma_f32_16x16x32_bf16(Bt[n][k], At[m][k], acc[ai][bj][m][n], 0, 0, 0); __builtin_amdgcn_s_setprio(0); } while (0)
; #define PG8_WAIT_V(n) asm volatile("s_waitcnt vmcnt(" #n ")" ::: "memory")
; #define PG8_WAIT_L(n) asm volatile("s_waitcnt lgkmcnt(" #n ")" ::: "memory")
; #define PG8_BAR __builtin_amdgcn_s_barrier()
; #define PG8_SCHED __builtin_amdgcn_sched_barrier(0)
; template <class Epi>
; DI void gemm_phase(LAS unsigned char* lds, const Gemm g, const StaticOrder& S, const Epi& E) {
;     ...
;         for (int t = 0; t < nt; t += 2) {
;             const bool last = (t == nt - 2);
;             const char* a1 = cA + (size_t)(t + 1) * kstep;
;             const char* a2 = last ? nA : cA + (size_t)(t + 2) * kstep; const char* b2 = last ? nB : cB + (size_t)(t + 2) * kstep;
;             const char* a3 = a2 + kstep; const char* b3 = b2 + kstep;
;             PG8_LDB(B0, 0, 0); PG8_SCHED; PG8_LDA(At, 0, 0); PG8_STAGE(PG8_SA(1, 1), a1 + hstep);
;             PG8_WAIT_L(8); PG8_BAR; PG8_WAIT_L(0); PG8_MMA(0, 0, At, B0); PG8_BAR; PG8_SCHED;
;             PG8_LDB(B1, 0, 1); PG8_STAGE(PG8_SB(0, 0), b2);
;             PG8_BAR; PG8_WAIT_L(0); PG8_MMA(0, 1, At, B1); PG8_BAR;
;             PG8_LDA(At, 0, 1); PG8_STAGE(PG8_SA(0, 0), a2);
;             PG8_BAR; PG8_WAIT_L(0); PG8_MMA(1, 0, At, B0); PG8_BAR; PG8_SCHED;
;             PG8_STAGE(PG8_SB(0, 1), b2 + hstep);
;             PG8_WAIT_V(6); PG8_BAR; PG8_MMA(1, 1, At, B1); PG8_BAR;
.LBB0_37:
	s_add_u32 s20, s18, 0xfff80080
	s_addc_u32 s21, s19, -1
	s_add_i32 s39, 0, 0x10000
	v_add_u32_e32 v150, s39, v135
	ds_read_b128 v[138:141], v150
	ds_read_b128 v[142:145], v150 offset:1024
	ds_read_b128 v[146:149], v150 offset:2048
	ds_read_b128 v[150:153], v150 offset:3072
	s_cmp_eq_u32 s38, 28
	s_cselect_b32 s23, s4, s21
	s_cselect_b32 s22, s5, s20
	s_cselect_b32 s21, s9, s37
	s_cselect_b32 s20, s11, s33
	v_lshl_add_u64 v[154:155], s[18:19], 0, v[130:131]
	s_add_i32 m0, s28, 0xc000
	ds_read_b128 v[186:189], v137
	ds_read_b128 v[190:193], v137 offset:1024
	ds_read_b128 v[194:197], v137 offset:2048
	ds_read_b128 v[198:201], v137 offset:3072
	ds_read_b128 v[202:205], v137 offset:4096
	ds_read_b128 v[206:209], v137 offset:5120
	ds_read_b128 v[210:213], v137 offset:6144
	ds_read_b128 v[214:217], v137 offset:7168
	global_load_lds_dwordx4 v[154:155], off
	v_lshl_add_u64 v[154:155], s[18:19], 0, v[132:133]
	s_add_i32 m0, s28, 0xe000
	s_nop 0
	global_load_lds_dwordx4 v[154:155], off
	s_waitcnt lgkmcnt(8)
	s_setprio 1
	s_barrier
	s_waitcnt lgkmcnt(0)
	v_mfma_f32_16x16x32_bf16 v[124:127], v[138:141], v[186:189], v[124:127]
	v_mfma_f32_16x16x32_bf16 v[120:123], v[146:149], v[186:189], v[120:123]
	v_mfma_f32_16x16x32_bf16 v[108:111], v[138:141], v[194:197], v[108:111]
	v_mfma_f32_16x16x32_bf16 v[104:107], v[146:149], v[194:197], v[104:107]
	v_mfma_f32_16x16x32_bf16 v[92:95], v[138:141], v[202:205], v[92:95]
	v_mfma_f32_16x16x32_bf16 v[88:91], v[146:149], v[202:205], v[88:91]
	v_mfma_f32_16x16x32_bf16 v[76:79], v[138:141], v[210:213], v[76:79]
	v_mfma_f32_16x16x32_bf16 v[72:75], v[146:149], v[210:213], v[72:75]
	v_mfma_f32_16x16x32_bf16 v[124:127], v[142:145], v[190:193], v[124:127]
	v_mfma_f32_16x16x32_bf16 v[120:123], v[150:153], v[190:193], v[120:123]
	v_mfma_f32_16x16x32_bf16 v[108:111], v[142:145], v[198:201], v[108:111]
	v_mfma_f32_16x16x32_bf16 v[104:107], v[150:153], v[198:201], v[104:107]
	v_mfma_f32_16x16x32_bf16 v[92:95], v[142:145], v[206:209], v[92:95]
	v_mfma_f32_16x16x32_bf16 v[88:91], v[150:153], v[206:209], v[88:91]
	v_mfma_f32_16x16x32_bf16 v[76:79], v[142:145], v[214:217], v[76:79]
	v_mfma_f32_16x16x32_bf16 v[72:75], v[150:153], v[214:217], v[72:75]
	s_setprio 0
	s_barrier
	s_add_i32 s42, 0, 0x14000
	v_add_u32_e32 v154, s42, v135
	s_add_i32 s39, s39, s27
	ds_read_b128 v[226:229], v154
	ds_read_b128 v[230:233], v154 offset:1024
	ds_read_b128 v[234:237], v154 offset:2048
	ds_read_b128 v[238:241], v154 offset:3072
	v_lshl_add_u64 v[154:155], s[20:21], 0, v[158:159]
	s_mov_b32 m0, s39
	v_lshl_add_u64 v[218:219], s[20:21], 0, v[128:129]
	global_load_lds_dwordx4 v[154:155], off
	s_add_i32 m0, s39, 0x2000
	s_nop 0
	global_load_lds_dwordx4 v[218:219], off
	s_waitcnt lgkmcnt(0)
	s_setprio 1
	s_barrier
	v_mfma_f32_16x16x32_bf16 v[116:119], v[226:229], v[186:189], v[116:119]
	v_mfma_f32_16x16x32_bf16 v[112:115], v[234:237], v[186:189], v[112:115]
	v_mfma_f32_16x16x32_bf16 v[100:103], v[226:229], v[194:197], v[100:103]
	v_mfma_f32_16x16x32_bf16 v[96:99], v[234:237], v[194:197], v[96:99]
	v_mfma_f32_16x16x32_bf16 v[84:87], v[226:229], v[202:205], v[84:87]
	v_mfma_f32_16x16x32_bf16 v[80:83], v[234:237], v[202:205], v[80:83]
	v_mfma_f32_16x16x32_bf16 v[68:71], v[226:229], v[210:213], v[68:71]
	v_mfma_f32_16x16x32_bf16 v[64:67], v[234:237], v[210:213], v[64:67]
	v_mfma_f32_16x16x32_bf16 v[116:119], v[230:233], v[190:193], v[116:119]
	s_mov_b32 m0, s28
	v_mfma_f32_16x16x32_bf16 v[112:115], v[238:241], v[190:193], v[112:115]
	v_lshl_add_u64 v[220:221], s[22:23], 0, v[158:159]
	v_mfma_f32_16x16x32_bf16 v[100:103], v[230:233], v[198:201], v[100:103]
	v_mfma_f32_16x16x32_bf16 v[96:99], v[238:241], v[198:201], v[96:99]
	v_mfma_f32_16x16x32_bf16 v[84:87], v[230:233], v[206:209], v[84:87]
	v_mfma_f32_16x16x32_bf16 v[80:83], v[238:241], v[206:209], v[80:83]
	v_mfma_f32_16x16x32_bf16 v[68:71], v[230:233], v[214:217], v[68:71]
	v_mfma_f32_16x16x32_bf16 v[64:67], v[238:241], v[214:217], v[64:67]
	s_setprio 0
	s_barrier
	ds_read_b128 v[186:189], v137 offset:16384
	ds_read_b128 v[190:193], v137 offset:17408
	ds_read_b128 v[194:197], v137 offset:18432
	ds_read_b128 v[198:201], v137 offset:19456
	ds_read_b128 v[202:205], v137 offset:20480
	ds_read_b128 v[206:209], v137 offset:21504
	ds_read_b128 v[210:213], v137 offset:22528
	ds_read_b128 v[214:217], v137 offset:23552
	global_load_lds_dwordx4 v[220:221], off
	v_lshl_add_u64 v[242:243], s[22:23], 0, v[128:129]
	s_mov_b32 m0, s29
	s_nop 0
	global_load_lds_dwordx4 v[242:243], off
	s_waitcnt lgkmcnt(0)
	s_setprio 1
	s_barrier
	v_mfma_f32_16x16x32_bf16 v[60:63], v[138:141], v[186:189], v[60:63]
	v_mfma_f32_16x16x32_bf16 v[56:59], v[146:149], v[186:189], v[56:59]
	v_mfma_f32_16x16x32_bf16 v[44:47], v[138:141], v[194:197], v[44:47]
	v_mfma_f32_16x16x32_bf16 v[40:43], v[146:149], v[194:197], v[40:43]
	v_mfma_f32_16x16x32_bf16 v[28:31], v[138:141], v[202:205], v[28:31]
	v_mfma_f32_16x16x32_bf16 v[24:27], v[146:149], v[202:205], v[24:27]
	v_mfma_f32_16x16x32_bf16 v[12:15], v[138:141], v[210:213], v[12:15]
	v_mfma_f32_16x16x32_bf16 v[8:11], v[146:149], v[210:213], v[8:11]
	v_mfma_f32_16x16x32_bf16 v[60:63], v[142:145], v[190:193], v[60:63]
	v_mfma_f32_16x16x32_bf16 v[56:59], v[150:153], v[190:193], v[56:59]
	v_mfma_f32_16x16x32_bf16 v[44:47], v[142:145], v[198:201], v[44:47]
	v_mfma_f32_16x16x32_bf16 v[40:43], v[150:153], v[198:201], v[40:43]
	v_mfma_f32_16x16x32_bf16 v[28:31], v[142:145], v[206:209], v[28:31]
	v_mfma_f32_16x16x32_bf16 v[24:27], v[150:153], v[206:209], v[24:27]
	v_mfma_f32_16x16x32_bf16 v[12:15], v[142:145], v[214:217], v[12:15]
	v_mfma_f32_16x16x32_bf16 v[8:11], v[150:153], v[214:217], v[8:11]
	s_setprio 0
	s_barrier
; #define PG8_STAGE(bufoff, gbase) do { _Pragma("unroll") for (int _i = 0; _i < 2; ++_i) \
;         __builtin_amdgcn_global_load_lds((const unsigned*)((const char*)(gbase) + voff[_i]), (LAS unsigned*)(lds + (bufoff) + ldsw + _i * 8192), 16, 0, 0); } while (0)
; #define PG8_LDA(dst, b, h) do { _Pragma("unroll") for (int m = 0; m < 4; ++m) _Pragma("unroll") for (int k = 0; k < 2; ++k) dst[m][k] = *(const LAS bf16x8*)(lds + PG8_SA(b, h) + aoff + m * 2048 + k * 1024); } while (0)
; #define PG8_LDB(dst, b, h) do { _Pragma("unroll") for (int n = 0; n < 2; ++n) _Pragma("unroll") for (int k = 0; k < 2; ++k) dst[n][k] = *(const LAS bf16x8*)(lds + PG8_SB(b, h) + boff + n * 2048 + k * 1024); } while (0)
; #define PG8_MMA(ai, bj, At, Bt) do { __builtin_amdgcn_s_setprio(1); _Pragma("unroll") for (int m = 0; m < 4; ++m) _Pragma("unroll") for (int n = 0; n < 2; ++n) _Pragma("unroll") for (int k = 0; k < 2; ++k) \
;         acc[ai][bj][m][n] = __builtin_amdgcn_mfma_f32_16x16x32_bf16(Bt[n][k], At[m][k], acc[ai][bj][m][n], 0, 0, 0); __builtin_amdgcn_s_setprio(0); } while (0)
; #define PG8_WAIT_V(n) asm volatile("s_waitcnt vmcnt(" #n ")" ::: "memory")
; #define PG8_WAIT_L(n) asm volatile("s_waitcnt lgkmcnt(" #n ")" ::: "memory")
; #define PG8_BAR __builtin_amdgcn_s_barrier()
; #define PG8_SCHED __builtin_amdgcn_sched_barrier(0)
; template <class Epi>
; DI void gemm_phase(LAS unsigned char* lds, const Gemm g, const StaticOrder& S, const Epi& E) {
;     ...
;             PG8_STAGE(PG8_SB(0, 1), b2 + hstep);
;             PG8_WAIT_V(6); PG8_BAR; PG8_MMA(1, 1, At, B1); PG8_BAR;
;             PG8_LDB(B0, 1, 0); PG8_SCHED; PG8_LDA(At, 1, 0); PG8_STAGE(PG8_SA(0, 1), a2 + hstep);
;             PG8_WAIT_L(8); PG8_BAR; PG8_WAIT_L(0); PG8_MMA(0, 0, At, B0); PG8_BAR; PG8_SCHED;
;             PG8_LDB(B1, 1, 1); PG8_STAGE(PG8_SB(1, 0), b3);
;             PG8_BAR; PG8_WAIT_L(0); PG8_MMA(0, 1, At, B1); PG8_BAR;
;             PG8_LDA(At, 1, 1); PG8_STAGE(PG8_SA(1, 0), a3);
	s_add_u32 s40, s20, 0x80000
	s_addc_u32 s41, s21, 0
	s_add_i32 s39, s42, s27
	v_lshl_add_u64 v[138:139], s[40:41], 0, v[158:159]
	s_mov_b32 m0, s39
	s_nop 0
	global_load_lds_dwordx4 v[138:139], off
	v_lshl_add_u64 v[138:139], s[40:41], 0, v[128:129]
	s_add_i32 m0, s39, 0x2000
	s_nop 0
	global_load_lds_dwordx4 v[138:139], off
	s_waitcnt vmcnt(6)
	s_setprio 1
	s_barrier
	v_mfma_f32_16x16x32_bf16 v[52:55], v[226:229], v[186:189], v[52:55]
	v_mfma_f32_16x16x32_bf16 v[48:51], v[234:237], v[186:189], v[48:51]
	v_mfma_f32_16x16x32_bf16 v[36:39], v[226:229], v[194:197], v[36:39]
	v_mfma_f32_16x16x32_bf16 v[32:35], v[234:237], v[194:197], v[32:35]
	v_mfma_f32_16x16x32_bf16 v[20:23], v[226:229], v[202:205], v[20:23]
	v_mfma_f32_16x16x32_bf16 v[16:19], v[234:237], v[202:205], v[16:19]
	v_mfma_f32_16x16x32_bf16 v[4:7], v[226:229], v[210:213], v[4:7]
	v_mfma_f32_16x16x32_bf16 v[0:3], v[234:237], v[210:213], v[0:3]
	v_mfma_f32_16x16x32_bf16 v[52:55], v[230:233], v[190:193], v[52:55]
	s_add_i32 s39, 0, 0x18000
	v_mfma_f32_16x16x32_bf16 v[48:51], v[238:241], v[190:193], v[48:51]
	v_add_u32_e32 v150, s39, v135
	v_mfma_f32_16x16x32_bf16 v[36:39], v[230:233], v[198:201], v[36:39]
	v_mfma_f32_16x16x32_bf16 v[32:35], v[238:241], v[198:201], v[32:35]
	v_mfma_f32_16x16x32_bf16 v[20:23], v[230:233], v[206:209], v[20:23]
	v_mfma_f32_16x16x32_bf16 v[16:19], v[238:241], v[206:209], v[16:19]
	v_mfma_f32_16x16x32_bf16 v[4:7], v[230:233], v[214:217], v[4:7]
	v_mfma_f32_16x16x32_bf16 v[0:3], v[238:241], v[214:217], v[0:3]
	s_setprio 0
	s_barrier
	ds_read_b128 v[138:141], v150
	ds_read_b128 v[142:145], v150 offset:1024
	ds_read_b128 v[146:149], v150 offset:2048
	ds_read_b128 v[150:153], v150 offset:3072
	s_add_u32 s22, s22, 0x80000
	s_addc_u32 s23, s23, 0
	s_mov_b32 m0, s30
	v_lshl_add_u64 v[226:227], s[22:23], 0, v[158:159]
	ds_read_b128 v[186:189], v137 offset:32768
	ds_read_b128 v[190:193], v137 offset:33792
	ds_read_b128 v[194:197], v137 offset:34816
	ds_read_b128 v[198:201], v137 offset:35840
	ds_read_b128 v[202:205], v137 offset:36864
	ds_read_b128 v[206:209], v137 offset:37888
	ds_read_b128 v[210:213], v137 offset:38912
	ds_read_b128 v[214:217], v137 offset:39936
	global_load_lds_dwordx4 v[226:227], off
	v_lshl_add_u64 v[226:227], s[22:23], 0, v[128:129]
	s_mov_b32 m0, s31
	s_nop 0
	global_load_lds_dwordx4 v[226:227], off
	s_waitcnt lgkmcnt(8)
	s_setprio 1
	s_barrier
	s_waitcnt lgkmcnt(0)
	v_mfma_f32_16x16x32_bf16 v[124:127], v[138:141], v[186:189], v[124:127]
	v_mfma_f32_16x16x32_bf16 v[120:123], v[146:149], v[186:189], v[120:123]
	v_mfma_f32_16x16x32_bf16 v[108:111], v[138:141], v[194:197], v[108:111]
	v_mfma_f32_16x16x32_bf16 v[104:107], v[146:149], v[194:197], v[104:107]
	v_mfma_f32_16x16x32_bf16 v[92:95], v[138:141], v[202:205], v[92:95]
	v_mfma_f32_16x16x32_bf16 v[88:91], v[146:149], v[202:205], v[88:91]
	v_mfma_f32_16x16x32_bf16 v[76:79], v[138:141], v[210:213], v[76:79]
	v_mfma_f32_16x16x32_bf16 v[72:75], v[146:149], v[210:213], v[72:75]
	v_mfma_f32_16x16x32_bf16 v[124:127], v[142:145], v[190:193], v[124:127]
	v_mfma_f32_16x16x32_bf16 v[120:123], v[150:153], v[190:193], v[120:123]
	v_mfma_f32_16x16x32_bf16 v[108:111], v[142:145], v[198:201], v[108:111]
	v_mfma_f32_16x16x32_bf16 v[104:107], v[150:153], v[198:201], v[104:107]
	v_mfma_f32_16x16x32_bf16 v[92:95], v[142:145], v[206:209], v[92:95]
	v_mfma_f32_16x16x32_bf16 v[88:91], v[150:153], v[206:209], v[88:91]
	v_mfma_f32_16x16x32_bf16 v[76:79], v[142:145], v[214:217], v[76:79]
	v_mfma_f32_16x16x32_bf16 v[72:75], v[150:153], v[214:217], v[72:75]
	s_setprio 0
	s_barrier
	s_add_i32 s22, 0, 0x1c000
	s_add_i32 s23, s39, s27
	v_add_u32_e32 v225, s22, v135
	v_lshl_add_u64 v[154:155], v[154:155], 0, s[94:95]
	s_mov_b32 m0, s23
	ds_read_b128 v[226:229], v225
	ds_read_b128 v[230:233], v225 offset:1024
	ds_read_b128 v[234:237], v225 offset:2048
	ds_read_b128 v[238:241], v225 offset:3072
	global_load_lds_dwordx4 v[154:155], off
	v_lshl_add_u64 v[154:155], v[218:219], 0, s[94:95]
	s_add_i32 m0, s23, 0x2000
	s_nop 0
	global_load_lds_dwordx4 v[154:155], off
	s_waitcnt lgkmcnt(0)
	s_setprio 1
	s_barrier
	v_mfma_f32_16x16x32_bf16 v[116:119], v[226:229], v[186:189], v[116:119]
	v_mfma_f32_16x16x32_bf16 v[112:115], v[234:237], v[186:189], v[112:115]
	v_mfma_f32_16x16x32_bf16 v[100:103], v[226:229], v[194:197], v[100:103]
	v_mfma_f32_16x16x32_bf16 v[96:99], v[234:237], v[194:197], v[96:99]
	v_mfma_f32_16x16x32_bf16 v[84:87], v[226:229], v[202:205], v[84:87]
	v_mfma_f32_16x16x32_bf16 v[80:83], v[234:237], v[202:205], v[80:83]
	v_mfma_f32_16x16x32_bf16 v[68:71], v[226:229], v[210:213], v[68:71]
	v_mfma_f32_16x16x32_bf16 v[64:67], v[234:237], v[210:213], v[64:67]
	v_mfma_f32_16x16x32_bf16 v[116:119], v[230:233], v[190:193], v[116:119]
	s_mov_b32 m0, s34
	v_mfma_f32_16x16x32_bf16 v[112:115], v[238:241], v[190:193], v[112:115]
	v_lshl_add_u64 v[154:155], v[220:221], 0, s[94:95]
	v_mfma_f32_16x16x32_bf16 v[100:103], v[230:233], v[198:201], v[100:103]
	v_mfma_f32_16x16x32_bf16 v[96:99], v[238:241], v[198:201], v[96:99]
	v_mfma_f32_16x16x32_bf16 v[84:87], v[230:233], v[206:209], v[84:87]
	v_mfma_f32_16x16x32_bf16 v[80:83], v[238:241], v[206:209], v[80:83]
	v_mfma_f32_16x16x32_bf16 v[68:71], v[230:233], v[214:217], v[68:71]
	v_mfma_f32_16x16x32_bf16 v[64:67], v[238:241], v[214:217], v[64:67]
	s_setprio 0
	s_barrier
	ds_read_b128 v[186:189], v137 offset:49152
	ds_read_b128 v[190:193], v137 offset:50176
	ds_read_b128 v[194:197], v137 offset:51200
	ds_read_b128 v[198:201], v137 offset:52224
	ds_read_b128 v[202:205], v137 offset:53248
	ds_read_b128 v[206:209], v137 offset:54272
	ds_read_b128 v[210:213], v137 offset:55296
	ds_read_b128 v[214:217], v137 offset:56320
	global_load_lds_dwordx4 v[154:155], off
	v_lshl_add_u64 v[154:155], v[242:243], 0, s[94:95]
	s_mov_b32 m0, s35
	s_nop 0
	global_load_lds_dwordx4 v[154:155], off
	s_waitcnt lgkmcnt(0)
	s_setprio 1
	s_barrier
; #define PG8_STAGE(bufoff, gbase) do { _Pragma("unroll") for (int _i = 0; _i < 2; ++_i) \
;         __builtin_amdgcn_global_load_lds((const unsigned*)((const char*)(gbase) + voff[_i]), (LAS unsigned*)(lds + (bufoff) + ldsw + _i * 8192), 16, 0, 0); } while (0)
; #define PG8_LDA(dst, b, h) do { _Pragma("unroll") for (int m = 0; m < 4; ++m) _Pragma("unroll") for (int k = 0; k < 2; ++k) dst[m][k] = *(const LAS bf16x8*)(lds + PG8_SA(b, h) + aoff + m * 2048 + k * 1024); } while (0)
; #define PG8_MMA(ai, bj, At, Bt) do { __builtin_amdgcn_s_setprio(1); _Pragma("unroll") for (int m = 0; m < 4; ++m) _Pragma("unroll") for (int n = 0; n < 2; ++n) _Pragma("unroll") for (int k = 0; k < 2; ++k) \
;         acc[ai][bj][m][n] = __builtin_amdgcn_mfma_f32_16x16x32_bf16(Bt[n][k], At[m][k], acc[ai][bj][m][n], 0, 0, 0); __builtin_amdgcn_s_setprio(0); } while (0)
; #define PG8_WAIT_V(n) asm volatile("s_waitcnt vmcnt(" #n ")" ::: "memory")
; #define PG8_WAIT_L(n) asm volatile("s_waitcnt lgkmcnt(" #n ")" ::: "memory")
; #define PG8_BAR __builtin_amdgcn_s_barrier()
; #define PG8_SCHED __builtin_amdgcn_sched_barrier(0)
; template <class Epi>
; DI void gemm_phase(LAS unsigned char* lds, const Gemm g, const StaticOrder& S, const Epi& E) {
;     ...
;             PG8_LDA(At, 1, 1); PG8_STAGE(PG8_SA(1, 0), a3);
;             PG8_BAR; PG8_WAIT_L(0); PG8_MMA(1, 0, At, B0); PG8_BAR; PG8_SCHED;
;             PG8_STAGE(PG8_SB(1, 1), b3 + hstep);
;             PG8_WAIT_V(6); PG8_BAR; PG8_MMA(1, 1, At, B1); PG8_BAR;
;     DI void operator()(const f32x4 (&acc)[2][2][4][2], const Unit& u, int wr, int wc, int fr, int fq) const {
;         const int row0 = u.pm * BM + wr * 64 + fr, col0 = u.pn * HALF + wc * 32 + 8 * fq;
; #pragma unroll
;         for (int ai = 0; ai < 2; ++ai)
; #pragma unroll
;             for (int m = 0; m < 4; ++m) { float hv[8];
; #pragma unroll
;                 for (int n = 0; n < 2; ++n)
; #pragma unroll
;                     for (int e = 0; e < 4; ++e) { const float gt = acc[ai][0][m][n][e], up = acc[ai][1][m][n][e];
;                         hv[n * 4 + e] = gt * __builtin_amdgcn_rcpf(1.f + __builtin_amdgcn_exp2f(-1.4426950408889634f * gt)) * up; }
;                 *(u32x4*)(H + (size_t)(row0 + ai * HALF + m * 16) * DFF + col0) = (u32x4){pk(hv[0], hv[1]), pk(hv[2], hv[3]), pk(hv[4], hv[5]), pk(hv[6], hv[7])}; }
	v_mfma_f32_16x16x32_bf16 v[60:63], v[138:141], v[186:189], v[60:63]
	v_mfma_f32_16x16x32_bf16 v[56:59], v[146:149], v[186:189], v[56:59]
	v_mfma_f32_16x16x32_bf16 v[44:47], v[138:141], v[194:197], v[44:47]
	v_mfma_f32_16x16x32_bf16 v[40:43], v[146:149], v[194:197], v[40:43]
	v_mfma_f32_16x16x32_bf16 v[28:31], v[138:141], v[202:205], v[28:31]
	v_mfma_f32_16x16x32_bf16 v[24:27], v[146:149], v[202:205], v[24:27]
	v_mfma_f32_16x16x32_bf16 v[12:15], v[138:141], v[210:213], v[12:15]
	v_mfma_f32_16x16x32_bf16 v[8:11], v[146:149], v[210:213], v[8:11]
	v_mfma_f32_16x16x32_bf16 v[60:63], v[142:145], v[190:193], v[60:63]
	v_mfma_f32_16x16x32_bf16 v[56:59], v[150:153], v[190:193], v[56:59]
	v_mfma_f32_16x16x32_bf16 v[44:47], v[142:145], v[198:201], v[44:47]
	v_mfma_f32_16x16x32_bf16 v[40:43], v[150:153], v[198:201], v[40:43]
	v_mfma_f32_16x16x32_bf16 v[28:31], v[142:145], v[206:209], v[28:31]
	v_mfma_f32_16x16x32_bf16 v[24:27], v[150:153], v[206:209], v[24:27]
	v_mfma_f32_16x16x32_bf16 v[12:15], v[142:145], v[214:217], v[12:15]
	v_mfma_f32_16x16x32_bf16 v[8:11], v[150:153], v[214:217], v[8:11]
	s_setprio 0
	s_barrier
	s_add_u32 s20, s20, 0x80080
	s_addc_u32 s21, s21, 0
	s_add_i32 s22, s22, s27
	v_lshl_add_u64 v[138:139], s[20:21], 0, v[158:159]
	s_mov_b32 m0, s22
	s_nop 0
	global_load_lds_dwordx4 v[138:139], off
	v_lshl_add_u64 v[138:139], s[20:21], 0, v[128:129]
	s_add_i32 m0, s22, 0x2000
	s_nop 0
	global_load_lds_dwordx4 v[138:139], off
	s_waitcnt vmcnt(6)
	s_setprio 1
	s_barrier
	v_mfma_f32_16x16x32_bf16 v[52:55], v[226:229], v[186:189], v[52:55]
	v_mfma_f32_16x16x32_bf16 v[48:51], v[234:237], v[186:189], v[48:51]
	v_mfma_f32_16x16x32_bf16 v[36:39], v[226:229], v[194:197], v[36:39]
	v_mfma_f32_16x16x32_bf16 v[32:35], v[234:237], v[194:197], v[32:35]
	v_mfma_f32_16x16x32_bf16 v[20:23], v[226:229], v[202:205], v[20:23]
	v_mfma_f32_16x16x32_bf16 v[16:19], v[234:237], v[202:205], v[16:19]
	v_mfma_f32_16x16x32_bf16 v[4:7], v[226:229], v[210:213], v[4:7]
	v_mfma_f32_16x16x32_bf16 v[0:3], v[234:237], v[210:213], v[0:3]
	v_mfma_f32_16x16x32_bf16 v[52:55], v[230:233], v[190:193], v[52:55]
	s_add_i32 s38, s38, 2
	v_mfma_f32_16x16x32_bf16 v[48:51], v[238:241], v[190:193], v[48:51]
	s_add_u32 s18, s18, 0x100
	v_mfma_f32_16x16x32_bf16 v[36:39], v[230:233], v[198:201], v[36:39]
	s_addc_u32 s19, s19, 0
	v_mfma_f32_16x16x32_bf16 v[32:35], v[238:241], v[198:201], v[32:35]
	s_add_u32 s33, s33, 0x100
	v_mfma_f32_16x16x32_bf16 v[20:23], v[230:233], v[206:209], v[20:23]
	s_addc_u32 s37, s37, 0
	v_mfma_f32_16x16x32_bf16 v[16:19], v[238:241], v[206:209], v[16:19]
	s_cmp_gt_u32 s38, 29
	v_mfma_f32_16x16x32_bf16 v[4:7], v[230:233], v[214:217], v[4:7]
	v_mfma_f32_16x16x32_bf16 v[0:3], v[238:241], v[214:217], v[0:3]
	s_setprio 0
	s_barrier
	s_cbranch_scc0 .LBB0_37
	v_mul_f32_e32 v139, 0xbfb8aa3b, v124
	v_exp_f32_e32 v139, v139
	v_lshl_or_b32 v140, s2, 7, v136
	v_lshl_add_u32 v138, s3, 8, v134
	v_ashrrev_i32_e32 v141, 31, v140
	v_add_f32_e32 v139, 1.0, v139
	v_rcp_f32_e32 v142, v139
	v_mul_f32_e32 v139, 0xbfb8aa3b, v125
	v_exp_f32_e32 v139, v139
	s_movk_i32 s4, 0x2c00
	s_and_b64 vcc, exec, s[6:7]
	s_mov_b64 s[20:21], s[16:17]
	v_add_f32_e32 v139, 1.0, v139
	v_rcp_f32_e32 v143, v139
	v_mul_f32_e32 v139, 0xbfb8aa3b, v126
	v_exp_f32_e32 v139, v139
	s_mov_b64 s[18:19], s[14:15]
	v_pk_mul_f32 v[124:125], v[124:125], v[142:143]
	v_add_f32_e32 v139, 1.0, v139
	v_rcp_f32_e32 v144, v139
	v_mul_f32_e32 v139, 0xbfb8aa3b, v127
	v_exp_f32_e32 v139, v139
	v_pk_mul_f32 v[116:117], v[124:125], v[116:117]
	v_add_f32_e32 v139, 1.0, v139
	v_rcp_f32_e32 v145, v139
	v_mul_f32_e32 v139, 0xbfb8aa3b, v120
	v_exp_f32_e32 v139, v139
	v_cvt_pk_bf16_f32 v116, v116, v117
	v_pk_mul_f32 v[124:125], v[126:127], v[144:145]
	v_add_f32_e32 v139, 1.0, v139
	v_rcp_f32_e32 v146, v139
	v_mul_f32_e32 v139, 0xbfb8aa3b, v121
	v_exp_f32_e32 v139, v139
	v_pk_mul_f32 v[118:119], v[124:125], v[118:119]
	v_add_f32_e32 v139, 1.0, v139
	v_rcp_f32_e32 v147, v139
	v_mul_f32_e32 v139, 0xbfb8aa3b, v122
	v_exp_f32_e32 v139, v139
	v_cvt_pk_bf16_f32 v117, v118, v119
	v_pk_mul_f32 v[118:119], v[120:121], v[146:147]
	v_add_f32_e32 v139, 1.0, v139
	v_rcp_f32_e32 v148, v139
	v_mul_f32_e32 v139, 0xbfb8aa3b, v123
	v_exp_f32_e32 v139, v139
	v_pk_mul_f32 v[112:113], v[118:119], v[112:113]
	v_add_f32_e32 v139, 1.0, v139
	v_rcp_f32_e32 v149, v139
	v_cvt_pk_bf16_f32 v118, v112, v113
	v_pk_mul_f32 v[112:113], v[122:123], v[148:149]
	s_nop 0
	v_pk_mul_f32 v[112:113], v[112:113], v[114:115]
	v_lshlrev_b64 v[114:115], 1, v[140:141]
	v_cvt_pk_bf16_f32 v119, v112, v113
	v_mov_b64_e32 v[112:113], s[54:55]
	v_mad_i64_i32 v[120:121], s[2:3], v138, s4, v[112:113]
	v_lshl_add_u64 v[120:121], v[120:121], 0, v[114:115]
	global_store_dwordx4 v[120:121], v[116:119], off
	v_mul_f32_e32 v120, 0xbfb8aa3b, v104
	v_mul_f32_e32 v121, 0xbfb8aa3b, v105
	v_mul_f32_e32 v116, 0xbfb8aa3b, v108
	v_mul_f32_e32 v117, 0xbfb8aa3b, v109
	v_exp_f32_e32 v116, v116
	v_exp_f32_e32 v117, v117
	v_mul_f32_e32 v118, 0xbfb8aa3b, v110
	v_mul_f32_e32 v119, 0xbfb8aa3b, v111
	v_exp_f32_e32 v118, v118
	v_exp_f32_e32 v119, v119
	v_exp_f32_e32 v120, v120
	v_exp_f32_e32 v121, v121
	v_add_f32_e32 v116, 1.0, v116
	v_add_f32_e32 v117, 1.0, v117
	v_mul_f32_e32 v122, 0xbfb8aa3b, v106
	v_mul_f32_e32 v123, 0xbfb8aa3b, v107
	v_rcp_f32_e32 v116, v116
	v_rcp_f32_e32 v117, v117
	v_add_f32_e32 v118, 1.0, v118
	v_add_f32_e32 v119, 1.0, v119
	v_exp_f32_e32 v122, v122
	v_exp_f32_e32 v123, v123
	v_rcp_f32_e32 v118, v118
	v_rcp_f32_e32 v119, v119
	v_add_f32_e32 v120, 1.0, v120
	v_add_f32_e32 v121, 1.0, v121
	v_rcp_f32_e32 v120, v120
	v_rcp_f32_e32 v121, v121
	v_add_f32_e32 v122, 1.0, v122
;     DI void operator()(const f32x4 (&acc)[2][2][4][2], const Unit& u, int wr, int wc, int fr, int fq) const {
;         const int row0 = u.pm * BM + wr * 64 + fr, col0 = u.pn * HALF + wc * 32 + 8 * fq;
; #pragma unroll
;         for (int ai = 0; ai < 2; ++ai)
; #pragma unroll
;             for (int m = 0; m < 4; ++m) { float hv[8];
; #pragma unroll
;                 for (int n = 0; n < 2; ++n)
; #pragma unroll
;                     for (int e = 0; e < 4; ++e) { const float gt = acc[ai][0][m][n][e], up = acc[ai][1][m][n][e];
;                         hv[n * 4 + e] = gt * __builtin_amdgcn_rcpf(1.f + __builtin_amdgcn_exp2f(-1.4426950408889634f * gt)) * up; }
;                 *(u32x4*)(H + (size_t)(row0 + ai * HALF + m * 16) * DFF + col0) = (u32x4){pk(hv[0], hv[1]), pk(hv[2], hv[3]), pk(hv[4], hv[5]), pk(hv[6], hv[7])}; }
	v_add_f32_e32 v123, 1.0, v123
	v_pk_mul_f32 v[108:109], v[108:109], v[116:117]
	v_rcp_f32_e32 v122, v122
	v_rcp_f32_e32 v123, v123
	v_pk_mul_f32 v[100:101], v[108:109], v[100:101]
	v_pk_mul_f32 v[108:109], v[110:111], v[118:119]
	v_cvt_pk_bf16_f32 v100, v100, v101
	v_pk_mul_f32 v[102:103], v[108:109], v[102:103]
	s_nop 0
	v_cvt_pk_bf16_f32 v101, v102, v103
	v_pk_mul_f32 v[102:103], v[104:105], v[120:121]
	s_nop 0
	v_pk_mul_f32 v[96:97], v[102:103], v[96:97]
	s_nop 0
	v_cvt_pk_bf16_f32 v102, v96, v97
	v_pk_mul_f32 v[96:97], v[106:107], v[122:123]
	s_nop 0
	v_pk_mul_f32 v[96:97], v[96:97], v[98:99]
	v_mul_f32_e32 v98, 0xbfb8aa3b, v94
	v_cvt_pk_bf16_f32 v103, v96, v97
	v_or_b32_e32 v96, 16, v138
	v_mad_i64_i32 v[96:97], s[2:3], v96, s4, v[112:113]
	v_lshl_add_u64 v[96:97], v[96:97], 0, v[114:115]
	global_store_dwordx4 v[96:97], v[100:103], off
	v_mul_f32_e32 v96, 0xbfb8aa3b, v92
	v_mul_f32_e32 v97, 0xbfb8aa3b, v93
	v_exp_f32_e32 v96, v96
	v_exp_f32_e32 v97, v97
	v_mul_f32_e32 v99, 0xbfb8aa3b, v95
	v_exp_f32_e32 v98, v98
	v_exp_f32_e32 v99, v99
	v_mul_f32_e32 v100, 0xbfb8aa3b, v88
	v_mul_f32_e32 v101, 0xbfb8aa3b, v89
	v_exp_f32_e32 v100, v100
	v_exp_f32_e32 v101, v101
	v_add_f32_e32 v96, 1.0, v96
	v_add_f32_e32 v97, 1.0, v97
	v_mul_f32_e32 v102, 0xbfb8aa3b, v90
	v_mul_f32_e32 v103, 0xbfb8aa3b, v91
	v_rcp_f32_e32 v96, v96
	v_rcp_f32_e32 v97, v97
	v_add_f32_e32 v98, 1.0, v98
	v_add_f32_e32 v99, 1.0, v99
	v_exp_f32_e32 v102, v102
	v_exp_f32_e32 v103, v103
	v_rcp_f32_e32 v98, v98
	v_rcp_f32_e32 v99, v99
	v_add_f32_e32 v100, 1.0, v100
	v_add_f32_e32 v101, 1.0, v101
	v_rcp_f32_e32 v100, v100
	v_rcp_f32_e32 v101, v101
	v_add_f32_e32 v102, 1.0, v102
	v_add_f32_e32 v103, 1.0, v103
	v_pk_mul_f32 v[92:93], v[92:93], v[96:97]
	v_rcp_f32_e32 v102, v102
	v_rcp_f32_e32 v103, v103
	v_pk_mul_f32 v[84:85], v[92:93], v[84:85]
	v_pk_mul_f32 v[92:93], v[94:95], v[98:99]
	v_cvt_pk_bf16_f32 v84, v84, v85
	v_pk_mul_f32 v[86:87], v[92:93], v[86:87]
	s_nop 0
	v_cvt_pk_bf16_f32 v85, v86, v87
	v_pk_mul_f32 v[86:87], v[88:89], v[100:101]
	s_nop 0
	v_pk_mul_f32 v[80:81], v[86:87], v[80:81]
	s_nop 0
	v_cvt_pk_bf16_f32 v86, v80, v81
	v_pk_mul_f32 v[80:81], v[90:91], v[102:103]
	s_nop 0
	v_pk_mul_f32 v[80:81], v[80:81], v[82:83]
	v_mul_f32_e32 v82, 0xbfb8aa3b, v78
	v_cvt_pk_bf16_f32 v87, v80, v81
	v_or_b32_e32 v80, 32, v138
	v_mad_i64_i32 v[80:81], s[2:3], v80, s4, v[112:113]
	v_lshl_add_u64 v[80:81], v[80:81], 0, v[114:115]
	global_store_dwordx4 v[80:81], v[84:87], off
	v_mul_f32_e32 v80, 0xbfb8aa3b, v76
	v_mul_f32_e32 v81, 0xbfb8aa3b, v77
	v_exp_f32_e32 v80, v80
	v_exp_f32_e32 v81, v81
	v_mul_f32_e32 v83, 0xbfb8aa3b, v79
	v_exp_f32_e32 v82, v82
	v_exp_f32_e32 v83, v83
	v_mul_f32_e32 v84, 0xbfb8aa3b, v72
	v_mul_f32_e32 v85, 0xbfb8aa3b, v73
	v_exp_f32_e32 v84, v84
	v_exp_f32_e32 v85, v85
	v_add_f32_e32 v80, 1.0, v80
	v_add_f32_e32 v81, 1.0, v81
	v_mul_f32_e32 v86, 0xbfb8aa3b, v74
	v_mul_f32_e32 v87, 0xbfb8aa3b, v75
	v_rcp_f32_e32 v80, v80
	v_rcp_f32_e32 v81, v81
	v_add_f32_e32 v82, 1.0, v82
	v_add_f32_e32 v83, 1.0, v83
	v_exp_f32_e32 v86, v86
	v_exp_f32_e32 v87, v87
	v_rcp_f32_e32 v82, v82
	v_rcp_f32_e32 v83, v83
	v_add_f32_e32 v84, 1.0, v84
	v_add_f32_e32 v85, 1.0, v85
	v_rcp_f32_e32 v84, v84
	v_rcp_f32_e32 v85, v85
	v_add_f32_e32 v86, 1.0, v86
	v_add_f32_e32 v87, 1.0, v87
	v_pk_mul_f32 v[76:77], v[76:77], v[80:81]
	v_rcp_f32_e32 v86, v86
	v_rcp_f32_e32 v87, v87
	v_pk_mul_f32 v[68:69], v[76:77], v[68:69]
	v_pk_mul_f32 v[76:77], v[78:79], v[82:83]
	v_cvt_pk_bf16_f32 v68, v68, v69
	v_pk_mul_f32 v[70:71], v[76:77], v[70:71]
	s_nop 0
	v_cvt_pk_bf16_f32 v69, v70, v71
	v_pk_mul_f32 v[70:71], v[72:73], v[84:85]
	v_add_u32_e32 v72, 0x80, v138
	v_pk_mul_f32 v[64:65], v[70:71], v[64:65]
	s_nop 0
	v_cvt_pk_bf16_f32 v70, v64, v65
	v_pk_mul_f32 v[64:65], v[74:75], v[86:87]
	s_nop 0
	v_pk_mul_f32 v[64:65], v[64:65], v[66:67]
	v_mul_f32_e32 v66, 0xbfb8aa3b, v62
	v_cvt_pk_bf16_f32 v71, v64, v65
	v_or_b32_e32 v64, 48, v138
	v_mad_i64_i32 v[64:65], s[2:3], v64, s4, v[112:113]
	v_lshl_add_u64 v[64:65], v[64:65], 0, v[114:115]
	global_store_dwordx4 v[64:65], v[68:71], off
	v_mul_f32_e32 v64, 0xbfb8aa3b, v60
	v_mul_f32_e32 v65, 0xbfb8aa3b, v61
	v_exp_f32_e32 v64, v64
	v_exp_f32_e32 v65, v65
	v_mul_f32_e32 v67, 0xbfb8aa3b, v63
	v_exp_f32_e32 v66, v66
	v_exp_f32_e32 v67, v67
	v_mul_f32_e32 v68, 0xbfb8aa3b, v56
	v_mul_f32_e32 v69, 0xbfb8aa3b, v57
	v_exp_f32_e32 v68, v68
	v_exp_f32_e32 v69, v69
	v_add_f32_e32 v64, 1.0, v64
	v_add_f32_e32 v65, 1.0, v65
	v_mul_f32_e32 v70, 0xbfb8aa3b, v58
	v_mul_f32_e32 v71, 0xbfb8aa3b, v59
	v_rcp_f32_e32 v64, v64
	v_rcp_f32_e32 v65, v65
	v_add_f32_e32 v66, 1.0, v66
	v_add_f32_e32 v67, 1.0, v67
	v_exp_f32_e32 v70, v70
	v_exp_f32_e32 v71, v71
	v_rcp_f32_e32 v66, v66
	v_rcp_f32_e32 v67, v67
	v_add_f32_e32 v68, 1.0, v68
	v_add_f32_e32 v69, 1.0, v69
	v_rcp_f32_e32 v68, v68
	v_rcp_f32_e32 v69, v69
	v_add_f32_e32 v70, 1.0, v70
	v_add_f32_e32 v71, 1.0, v71
	v_pk_mul_f32 v[60:61], v[60:61], v[64:65]
	v_rcp_f32_e32 v70, v70
	v_rcp_f32_e32 v71, v71
	v_pk_mul_f32 v[52:53], v[60:61], v[52:53]
	v_pk_mul_f32 v[60:61], v[62:63], v[66:67]
	v_cvt_pk_bf16_f32 v52, v52, v53
	v_pk_mul_f32 v[54:55], v[60:61], v[54:55]
	s_nop 0
	v_cvt_pk_bf16_f32 v53, v54, v55
	v_pk_mul_f32 v[54:55], v[56:57], v[68:69]
; #define PG8_WAIT_V(n) asm volatile("s_waitcnt vmcnt(" #n ")" ::: "memory")
; #define PG8_BAR __builtin_amdgcn_s_barrier()
; template <class Epi>
; DI void gemm_phase(LAS unsigned char* lds, const Gemm g, const StaticOrder& S, const Epi& E) {
;     ...
;         if (!has_next) break;
; #pragma unroll
;         for (int a = 0; a < 2; ++a)
; #pragma unroll
;             for (int b = 0; b < 2; ++b)
; #pragma unroll
;                 for (int m = 0; m < 4; ++m)
; #pragma unroll
;                     for (int n = 0; n < 2; ++n) acc[a][b][m][n] = (f32x4){0.f, 0.f, 0.f, 0.f};
;         cur = nxt; cA = nA; cB = nB; ++ui;
;     }
;     PG8_WAIT_V(0);
;     if (wr == 0) PG8_BAR;
;     PG8_BAR;
;     DI void operator()(const f32x4 (&acc)[2][2][4][2], const Unit& u, int wr, int wc, int fr, int fq) const {
;         const int row0 = u.pm * BM + wr * 64 + fr, col0 = u.pn * HALF + wc * 32 + 8 * fq;
; #pragma unroll
;         for (int ai = 0; ai < 2; ++ai)
; #pragma unroll
;             for (int m = 0; m < 4; ++m) { float hv[8];
; #pragma unroll
;                 for (int n = 0; n < 2; ++n)
; #pragma unroll
;                     for (int e = 0; e < 4; ++e) { const float gt = acc[ai][0][m][n][e], up = acc[ai][1][m][n][e];
;                         hv[n * 4 + e] = gt * __builtin_amdgcn_rcpf(1.f + __builtin_amdgcn_exp2f(-1.4426950408889634f * gt)) * up; }
;                 *(u32x4*)(H + (size_t)(row0 + ai * HALF + m * 16) * DFF + col0) = (u32x4){pk(hv[0], hv[1]), pk(hv[2], hv[3]), pk(hv[4], hv[5]), pk(hv[6], hv[7])}; }
	s_nop 0
	v_pk_mul_f32 v[48:49], v[54:55], v[48:49]
	s_nop 0
	v_cvt_pk_bf16_f32 v54, v48, v49
	v_pk_mul_f32 v[48:49], v[58:59], v[70:71]
	s_nop 0
	v_pk_mul_f32 v[48:49], v[48:49], v[50:51]
	v_mul_f32_e32 v50, 0xbfb8aa3b, v46
	v_cvt_pk_bf16_f32 v55, v48, v49
	v_mad_i64_i32 v[48:49], s[2:3], v72, s4, v[112:113]
	v_lshl_add_u64 v[48:49], v[48:49], 0, v[114:115]
	global_store_dwordx4 v[48:49], v[52:55], off
	v_mul_f32_e32 v48, 0xbfb8aa3b, v44
	v_mul_f32_e32 v49, 0xbfb8aa3b, v45
	v_exp_f32_e32 v48, v48
	v_exp_f32_e32 v49, v49
	v_mul_f32_e32 v51, 0xbfb8aa3b, v47
	v_exp_f32_e32 v50, v50
	v_exp_f32_e32 v51, v51
	v_mul_f32_e32 v52, 0xbfb8aa3b, v40
	v_mul_f32_e32 v53, 0xbfb8aa3b, v41
	v_exp_f32_e32 v52, v52
	v_exp_f32_e32 v53, v53
	v_add_f32_e32 v48, 1.0, v48
	v_add_f32_e32 v49, 1.0, v49
	v_mul_f32_e32 v54, 0xbfb8aa3b, v42
	v_mul_f32_e32 v55, 0xbfb8aa3b, v43
	v_rcp_f32_e32 v48, v48
	v_rcp_f32_e32 v49, v49
	v_add_f32_e32 v50, 1.0, v50
	v_add_f32_e32 v51, 1.0, v51
	v_exp_f32_e32 v54, v54
	v_exp_f32_e32 v55, v55
	v_rcp_f32_e32 v50, v50
	v_rcp_f32_e32 v51, v51
	v_add_f32_e32 v52, 1.0, v52
	v_add_f32_e32 v53, 1.0, v53
	v_rcp_f32_e32 v52, v52
	v_rcp_f32_e32 v53, v53
	v_add_f32_e32 v54, 1.0, v54
	v_add_f32_e32 v55, 1.0, v55
	v_pk_mul_f32 v[44:45], v[44:45], v[48:49]
	v_rcp_f32_e32 v54, v54
	v_rcp_f32_e32 v55, v55
	v_pk_mul_f32 v[36:37], v[44:45], v[36:37]
	v_pk_mul_f32 v[44:45], v[46:47], v[50:51]
	v_cvt_pk_bf16_f32 v36, v36, v37
	v_pk_mul_f32 v[38:39], v[44:45], v[38:39]
	s_nop 0
	v_cvt_pk_bf16_f32 v37, v38, v39
	v_pk_mul_f32 v[38:39], v[40:41], v[52:53]
	s_nop 0
	v_pk_mul_f32 v[32:33], v[38:39], v[32:33]
	s_nop 0
	v_cvt_pk_bf16_f32 v38, v32, v33
	v_pk_mul_f32 v[32:33], v[42:43], v[54:55]
	s_nop 0
	v_pk_mul_f32 v[32:33], v[32:33], v[34:35]
	v_mul_f32_e32 v34, 0xbfb8aa3b, v30
	v_cvt_pk_bf16_f32 v39, v32, v33
	v_add_u32_e32 v32, 0x90, v138
	v_mad_i64_i32 v[32:33], s[2:3], v32, s4, v[112:113]
	v_lshl_add_u64 v[32:33], v[32:33], 0, v[114:115]
	global_store_dwordx4 v[32:33], v[36:39], off
	v_mul_f32_e32 v32, 0xbfb8aa3b, v28
	v_mul_f32_e32 v33, 0xbfb8aa3b, v29
	v_exp_f32_e32 v32, v32
	v_exp_f32_e32 v33, v33
	v_mul_f32_e32 v35, 0xbfb8aa3b, v31
	v_exp_f32_e32 v34, v34
	v_exp_f32_e32 v35, v35
	v_mul_f32_e32 v36, 0xbfb8aa3b, v24
	v_mul_f32_e32 v37, 0xbfb8aa3b, v25
	v_exp_f32_e32 v36, v36
	v_exp_f32_e32 v37, v37
	v_add_f32_e32 v32, 1.0, v32
	v_add_f32_e32 v33, 1.0, v33
	v_mul_f32_e32 v38, 0xbfb8aa3b, v26
	v_mul_f32_e32 v39, 0xbfb8aa3b, v27
	v_rcp_f32_e32 v32, v32
	v_rcp_f32_e32 v33, v33
	v_add_f32_e32 v34, 1.0, v34
	v_add_f32_e32 v35, 1.0, v35
	v_exp_f32_e32 v38, v38
	v_exp_f32_e32 v39, v39
	v_rcp_f32_e32 v34, v34
	v_rcp_f32_e32 v35, v35
	v_add_f32_e32 v36, 1.0, v36
	v_add_f32_e32 v37, 1.0, v37
	v_rcp_f32_e32 v36, v36
	v_rcp_f32_e32 v37, v37
	v_add_f32_e32 v38, 1.0, v38
	v_add_f32_e32 v39, 1.0, v39
	v_pk_mul_f32 v[28:29], v[28:29], v[32:33]
	v_rcp_f32_e32 v38, v38
	v_rcp_f32_e32 v39, v39
	v_pk_mul_f32 v[20:21], v[28:29], v[20:21]
	v_pk_mul_f32 v[28:29], v[30:31], v[34:35]
	v_cvt_pk_bf16_f32 v20, v20, v21
	v_pk_mul_f32 v[22:23], v[28:29], v[22:23]
	s_nop 0
	v_cvt_pk_bf16_f32 v21, v22, v23
	v_pk_mul_f32 v[22:23], v[24:25], v[36:37]
	s_nop 0
	v_pk_mul_f32 v[16:17], v[22:23], v[16:17]
	s_nop 0
	v_cvt_pk_bf16_f32 v22, v16, v17
	v_pk_mul_f32 v[16:17], v[26:27], v[38:39]
	s_nop 0
	v_pk_mul_f32 v[16:17], v[16:17], v[18:19]
	v_mul_f32_e32 v18, 0xbfb8aa3b, v14
	v_cvt_pk_bf16_f32 v23, v16, v17
	v_add_u32_e32 v16, 0xa0, v138
	v_mad_i64_i32 v[16:17], s[2:3], v16, s4, v[112:113]
	v_lshl_add_u64 v[16:17], v[16:17], 0, v[114:115]
	global_store_dwordx4 v[16:17], v[20:23], off
	v_mul_f32_e32 v16, 0xbfb8aa3b, v12
	v_mul_f32_e32 v17, 0xbfb8aa3b, v13
	v_exp_f32_e32 v16, v16
	v_exp_f32_e32 v17, v17
	v_mul_f32_e32 v19, 0xbfb8aa3b, v15
	v_exp_f32_e32 v18, v18
	v_exp_f32_e32 v19, v19
	v_mul_f32_e32 v20, 0xbfb8aa3b, v8
	v_mul_f32_e32 v21, 0xbfb8aa3b, v9
	v_exp_f32_e32 v20, v20
	v_exp_f32_e32 v21, v21
	v_add_f32_e32 v16, 1.0, v16
	v_add_f32_e32 v17, 1.0, v17
	v_mul_f32_e32 v22, 0xbfb8aa3b, v10
	v_mul_f32_e32 v23, 0xbfb8aa3b, v11
	v_rcp_f32_e32 v16, v16
	v_rcp_f32_e32 v17, v17
	v_add_f32_e32 v18, 1.0, v18
	v_add_f32_e32 v19, 1.0, v19
	v_exp_f32_e32 v22, v22
	v_exp_f32_e32 v23, v23
	v_rcp_f32_e32 v18, v18
	v_rcp_f32_e32 v19, v19
	v_add_f32_e32 v20, 1.0, v20
	v_add_f32_e32 v21, 1.0, v21
	v_rcp_f32_e32 v20, v20
	v_rcp_f32_e32 v21, v21
	v_add_f32_e32 v22, 1.0, v22
	v_add_f32_e32 v23, 1.0, v23
	v_pk_mul_f32 v[12:13], v[12:13], v[16:17]
	v_rcp_f32_e32 v22, v22
	v_rcp_f32_e32 v23, v23
	v_pk_mul_f32 v[4:5], v[12:13], v[4:5]
	v_pk_mul_f32 v[12:13], v[14:15], v[18:19]
	v_cvt_pk_bf16_f32 v4, v4, v5
	v_pk_mul_f32 v[6:7], v[12:13], v[6:7]
	s_nop 0
	v_cvt_pk_bf16_f32 v5, v6, v7
	v_pk_mul_f32 v[6:7], v[8:9], v[20:21]
	s_nop 0
	v_pk_mul_f32 v[0:1], v[6:7], v[0:1]
	s_nop 0
	v_cvt_pk_bf16_f32 v6, v0, v1
	v_pk_mul_f32 v[0:1], v[10:11], v[22:23]
	s_nop 0
	v_pk_mul_f32 v[0:1], v[0:1], v[2:3]
	s_nop 0
	v_cvt_pk_bf16_f32 v7, v0, v1
	v_add_u32_e32 v0, 0xb0, v138
	v_mad_i64_i32 v[0:1], s[2:3], v0, s4, v[112:113]
	v_lshl_add_u64 v[0:1], v[0:1], 0, v[114:115]
	s_mov_b32 s2, s8
	s_mov_b32 s3, s10
	global_store_dwordx4 v[0:1], v[4:7], off
	s_cbranch_vccz .LBB0_34
	s_waitcnt vmcnt(0)
	s_cmpk_gt_u32 s24, 0xff
	s_cbranch_scc1 .LBB0_41
	s_barrier

; #define PG8_STAGE(bufoff, gbase) do { _Pragma("unroll") for (int _i = 0; _i < 2; ++_i) \
;         __builtin_amdgcn_global_load_lds((const unsigned*)((const char*)(gbase) + voff[_i]), (LAS unsigned*)(lds + (bufoff) + ldsw + _i * 8192), 16, 0, 0); } while (0)
; #define PG8_LDA(dst, b, h) do { _Pragma("unroll") for (int m = 0; m < 4; ++m) _Pragma("unroll") for (int k = 0; k < 2; ++k) dst[m][k] = *(const LAS bf16x8*)(lds + PG8_SA(b, h) + aoff + m * 2048 + k * 1024); } while (0)
; #define PG8_LDB(dst, b, h) do { _Pragma("unroll") for (int n = 0; n < 2; ++n) _Pragma("unroll") for (int k = 0; k < 2; ++k) dst[n][k] = *(const LAS bf16x8*)(lds + PG8_SB(b, h) + boff + n * 2048 + k * 1024); } while (0)
; #define PG8_MMA(ai, bj, At, Bt) do { __builtin_amdgcn_s_setprio(1); _Pragma("unroll") for (int m = 0; m < 4; ++m) _Pragma("unroll") for (int n = 0; n < 2; ++n) _Pragma("unroll") for (int k = 0; k < 2; ++k) \
;         acc[ai][bj][m][n] = __builtin_amdgcn_mfma_f32_16x16x32_bf16(Bt[n][k], At[m][k], acc[ai][bj][m][n], 0, 0, 0); __builtin_amdgcn_s_setprio(0); } while (0)
; #define PG8_WAIT_V(n) asm volatile("s_waitcnt vmcnt(" #n ")" ::: "memory")
; #define PG8_WAIT_L(n) asm volatile("s_waitcnt lgkmcnt(" #n ")" ::: "memory")
; #define PG8_BAR __builtin_amdgcn_s_barrier()
; #define PG8_SCHED __builtin_amdgcn_sched_barrier(0)
; template <class Epi>
; DI void gemm_phase(LAS unsigned char* lds, const Gemm g, const StaticOrder& S, const Epi& E) {
;     ...
;         for (int t = 0; t < nt; t += 2) {
;             const bool last = (t == nt - 2);
;             const char* a1 = cA + (size_t)(t + 1) * kstep;
;             const char* a2 = last ? nA : cA + (size_t)(t + 2) * kstep; const char* b2 = last ? nB : cB + (size_t)(t + 2) * kstep;
;             const char* a3 = a2 + kstep; const char* b3 = b2 + kstep;
;             PG8_LDB(B0, 0, 0); PG8_SCHED; PG8_LDA(At, 0, 0); PG8_STAGE(PG8_SA(1, 1), a1 + hstep);
;             PG8_WAIT_L(8); PG8_BAR; PG8_WAIT_L(0); PG8_MMA(0, 0, At, B0); PG8_BAR; PG8_SCHED;
;             PG8_LDB(B1, 0, 1); PG8_STAGE(PG8_SB(0, 0), b2);
;             PG8_BAR; PG8_WAIT_L(0); PG8_MMA(0, 1, At, B1); PG8_BAR;
;             PG8_LDA(At, 0, 1); PG8_STAGE(PG8_SA(0, 0), a2);
;             PG8_BAR; PG8_WAIT_L(0); PG8_MMA(1, 0, At, B0); PG8_BAR; PG8_SCHED;
;             PG8_STAGE(PG8_SB(0, 1), b2 + hstep);
;             PG8_WAIT_V(6); PG8_BAR; PG8_MMA(1, 1, At, B1); PG8_BAR;
.LBB0_77:
	s_add_u32 s22, s20, 0x100
	s_addc_u32 s23, s21, 0
	s_add_i32 s43, 0, 0x10000
	v_add_u32_e32 v140, s43, v226
	ds_read_b128 v[128:131], v140
	ds_read_b128 v[132:135], v140 offset:1024
	ds_read_b128 v[136:139], v140 offset:2048
	ds_read_b128 v[140:143], v140 offset:3072
	s_cmp_eq_u32 s33, 32
	s_cselect_b32 s27, s9, s23
	s_cselect_b32 s26, s8, s22
	s_cselect_b32 s25, s11, s5
	s_cselect_b32 s24, s10, s4
	v_lshl_add_u64 v[214:215], s[20:21], 0, v[190:191]
	s_add_i32 m0, s34, 0xc000
	ds_read_b128 v[144:147], v228
	ds_read_b128 v[148:151], v228 offset:1024
	ds_read_b128 v[152:155], v228 offset:2048
	ds_read_b128 v[194:197], v228 offset:3072
	ds_read_b128 v[198:201], v228 offset:4096
	ds_read_b128 v[202:205], v228 offset:5120
	ds_read_b128 v[206:209], v228 offset:6144
	ds_read_b128 v[210:213], v228 offset:7168
	global_load_lds_dwordx4 v[214:215], off
	v_lshl_add_u64 v[214:215], s[20:21], 0, v[192:193]
	s_add_i32 m0, s34, 0xe000
	s_nop 0
	global_load_lds_dwordx4 v[214:215], off
	s_waitcnt lgkmcnt(8)
	s_setprio 1
	s_barrier
	s_waitcnt lgkmcnt(0)
	v_mfma_f32_16x16x32_bf16 v[124:127], v[128:131], v[144:147], v[124:127]
	v_mfma_f32_16x16x32_bf16 v[120:123], v[136:139], v[144:147], v[120:123]
	v_mfma_f32_16x16x32_bf16 v[116:119], v[128:131], v[152:155], v[116:119]
	v_mfma_f32_16x16x32_bf16 v[112:115], v[136:139], v[152:155], v[112:115]
	v_mfma_f32_16x16x32_bf16 v[108:111], v[128:131], v[198:201], v[108:111]
	v_mfma_f32_16x16x32_bf16 v[104:107], v[136:139], v[198:201], v[104:107]
	v_mfma_f32_16x16x32_bf16 v[100:103], v[128:131], v[206:209], v[100:103]
	v_mfma_f32_16x16x32_bf16 v[96:99], v[136:139], v[206:209], v[96:99]
	v_mfma_f32_16x16x32_bf16 v[124:127], v[132:135], v[148:151], v[124:127]
	v_mfma_f32_16x16x32_bf16 v[120:123], v[140:143], v[148:151], v[120:123]
	v_mfma_f32_16x16x32_bf16 v[116:119], v[132:135], v[194:197], v[116:119]
	v_mfma_f32_16x16x32_bf16 v[112:115], v[140:143], v[194:197], v[112:115]
	v_mfma_f32_16x16x32_bf16 v[108:111], v[132:135], v[202:205], v[108:111]
	v_mfma_f32_16x16x32_bf16 v[104:107], v[140:143], v[202:205], v[104:107]
	v_mfma_f32_16x16x32_bf16 v[100:103], v[132:135], v[210:213], v[100:103]
	v_mfma_f32_16x16x32_bf16 v[96:99], v[140:143], v[210:213], v[96:99]
	s_setprio 0
	s_barrier
	s_add_i32 s44, 0, 0x14000
	s_add_i32 s20, s43, s31
	v_add_u32_e32 v158, s44, v226
	v_lshl_add_u64 v[218:219], s[24:25], 0, v[188:189]
	s_mov_b32 m0, s20
	ds_read_b128 v[214:217], v158
	ds_read_b128 v[230:233], v158 offset:1024
	ds_read_b128 v[234:237], v158 offset:2048
	ds_read_b128 v[238:241], v158 offset:3072
	global_load_lds_dwordx4 v[218:219], off
	v_lshl_add_u64 v[220:221], s[24:25], 0, v[186:187]
	s_add_i32 m0, s20, 0x2000
	s_nop 0
	global_load_lds_dwordx4 v[220:221], off
	s_waitcnt lgkmcnt(0)
	s_setprio 1
	s_barrier
	v_mfma_f32_16x16x32_bf16 v[60:63], v[214:217], v[144:147], v[60:63]
	v_mfma_f32_16x16x32_bf16 v[56:59], v[234:237], v[144:147], v[56:59]
	v_mfma_f32_16x16x32_bf16 v[52:55], v[214:217], v[152:155], v[52:55]
	v_mfma_f32_16x16x32_bf16 v[48:51], v[234:237], v[152:155], v[48:51]
	v_mfma_f32_16x16x32_bf16 v[44:47], v[214:217], v[198:201], v[44:47]
	v_mfma_f32_16x16x32_bf16 v[40:43], v[234:237], v[198:201], v[40:43]
	v_mfma_f32_16x16x32_bf16 v[36:39], v[214:217], v[206:209], v[36:39]
	v_mfma_f32_16x16x32_bf16 v[32:35], v[234:237], v[206:209], v[32:35]
	v_mfma_f32_16x16x32_bf16 v[60:63], v[230:233], v[148:151], v[60:63]
	s_mov_b32 m0, s34
	v_mfma_f32_16x16x32_bf16 v[56:59], v[238:241], v[148:151], v[56:59]
	v_lshl_add_u64 v[242:243], s[26:27], 0, v[188:189]
	v_mfma_f32_16x16x32_bf16 v[52:55], v[230:233], v[194:197], v[52:55]
	v_mfma_f32_16x16x32_bf16 v[48:51], v[238:241], v[194:197], v[48:51]
	v_mfma_f32_16x16x32_bf16 v[44:47], v[230:233], v[202:205], v[44:47]
	v_mfma_f32_16x16x32_bf16 v[40:43], v[238:241], v[202:205], v[40:43]
	v_mfma_f32_16x16x32_bf16 v[36:39], v[230:233], v[210:213], v[36:39]
	v_mfma_f32_16x16x32_bf16 v[32:35], v[238:241], v[210:213], v[32:35]
	s_setprio 0
	s_barrier
	ds_read_b128 v[144:147], v228 offset:16384
	ds_read_b128 v[148:151], v228 offset:17408
	ds_read_b128 v[152:155], v228 offset:18432
	ds_read_b128 v[194:197], v228 offset:19456
	ds_read_b128 v[198:201], v228 offset:20480
	ds_read_b128 v[202:205], v228 offset:21504
	ds_read_b128 v[206:209], v228 offset:22528
	ds_read_b128 v[210:213], v228 offset:23552
	global_load_lds_dwordx4 v[242:243], off
	v_lshl_add_u64 v[244:245], s[26:27], 0, v[186:187]
	s_mov_b32 m0, s35
	s_nop 0
	global_load_lds_dwordx4 v[244:245], off
	s_waitcnt lgkmcnt(0)
	s_setprio 1
	s_barrier
	v_mfma_f32_16x16x32_bf16 v[92:95], v[128:131], v[144:147], v[92:95]
	v_mfma_f32_16x16x32_bf16 v[88:91], v[136:139], v[144:147], v[88:91]
	v_mfma_f32_16x16x32_bf16 v[84:87], v[128:131], v[152:155], v[84:87]
	v_mfma_f32_16x16x32_bf16 v[80:83], v[136:139], v[152:155], v[80:83]
	v_mfma_f32_16x16x32_bf16 v[76:79], v[128:131], v[198:201], v[76:79]
	v_mfma_f32_16x16x32_bf16 v[72:75], v[136:139], v[198:201], v[72:75]
	v_mfma_f32_16x16x32_bf16 v[68:71], v[128:131], v[206:209], v[68:71]
	v_mfma_f32_16x16x32_bf16 v[64:67], v[136:139], v[206:209], v[64:67]
	v_mfma_f32_16x16x32_bf16 v[92:95], v[132:135], v[148:151], v[92:95]
	v_mfma_f32_16x16x32_bf16 v[88:91], v[140:143], v[148:151], v[88:91]
	v_mfma_f32_16x16x32_bf16 v[84:87], v[132:135], v[194:197], v[84:87]
	v_mfma_f32_16x16x32_bf16 v[80:83], v[140:143], v[194:197], v[80:83]
	v_mfma_f32_16x16x32_bf16 v[76:79], v[132:135], v[202:205], v[76:79]
	v_mfma_f32_16x16x32_bf16 v[72:75], v[140:143], v[202:205], v[72:75]
	v_mfma_f32_16x16x32_bf16 v[68:71], v[132:135], v[210:213], v[68:71]
	v_mfma_f32_16x16x32_bf16 v[64:67], v[140:143], v[210:213], v[64:67]
	s_setprio 0
	s_barrier
; #define PG8_STAGE(bufoff, gbase) do { _Pragma("unroll") for (int _i = 0; _i < 2; ++_i) \
;         __builtin_amdgcn_global_load_lds((const unsigned*)((const char*)(gbase) + voff[_i]), (LAS unsigned*)(lds + (bufoff) + ldsw + _i * 8192), 16, 0, 0); } while (0)
; #define PG8_LDA(dst, b, h) do { _Pragma("unroll") for (int m = 0; m < 4; ++m) _Pragma("unroll") for (int k = 0; k < 2; ++k) dst[m][k] = *(const LAS bf16x8*)(lds + PG8_SA(b, h) + aoff + m * 2048 + k * 1024); } while (0)
; #define PG8_LDB(dst, b, h) do { _Pragma("unroll") for (int n = 0; n < 2; ++n) _Pragma("unroll") for (int k = 0; k < 2; ++k) dst[n][k] = *(const LAS bf16x8*)(lds + PG8_SB(b, h) + boff + n * 2048 + k * 1024); } while (0)
; #define PG8_MMA(ai, bj, At, Bt) do { __builtin_amdgcn_s_setprio(1); _Pragma("unroll") for (int m = 0; m < 4; ++m) _Pragma("unroll") for (int n = 0; n < 2; ++n) _Pragma("unroll") for (int k = 0; k < 2; ++k) \
;         acc[ai][bj][m][n] = __builtin_amdgcn_mfma_f32_16x16x32_bf16(Bt[n][k], At[m][k], acc[ai][bj][m][n], 0, 0, 0); __builtin_amdgcn_s_setprio(0); } while (0)
; #define PG8_WAIT_V(n) asm volatile("s_waitcnt vmcnt(" #n ")" ::: "memory")
; #define PG8_WAIT_L(n) asm volatile("s_waitcnt lgkmcnt(" #n ")" ::: "memory")
; #define PG8_BAR __builtin_amdgcn_s_barrier()
; #define PG8_SCHED __builtin_amdgcn_sched_barrier(0)
; template <class Epi>
; DI void gemm_phase(LAS unsigned char* lds, const Gemm g, const StaticOrder& S, const Epi& E) {
;     ...
;             PG8_STAGE(PG8_SB(0, 1), b2 + hstep);
;             PG8_WAIT_V(6); PG8_BAR; PG8_MMA(1, 1, At, B1); PG8_BAR;
;             PG8_LDB(B0, 1, 0); PG8_SCHED; PG8_LDA(At, 1, 0); PG8_STAGE(PG8_SA(0, 1), a2 + hstep);
;             PG8_WAIT_L(8); PG8_BAR; PG8_WAIT_L(0); PG8_MMA(0, 0, At, B0); PG8_BAR; PG8_SCHED;
;             PG8_LDB(B1, 1, 1); PG8_STAGE(PG8_SB(1, 0), b3);
;             PG8_BAR; PG8_WAIT_L(0); PG8_MMA(0, 1, At, B1); PG8_BAR;
;             PG8_LDA(At, 1, 1); PG8_STAGE(PG8_SA(1, 0), a3);
	s_add_u32 s20, s24, 0x90000
	s_addc_u32 s21, s25, 0
	s_add_i32 s43, s44, s31
	v_lshl_add_u64 v[128:129], s[20:21], 0, v[188:189]
	s_mov_b32 m0, s43
	s_nop 0
	global_load_lds_dwordx4 v[128:129], off
	v_lshl_add_u64 v[128:129], s[20:21], 0, v[186:187]
	s_add_i32 m0, s43, 0x2000
	s_nop 0
	global_load_lds_dwordx4 v[128:129], off
	s_waitcnt vmcnt(6)
	s_setprio 1
	s_barrier
	v_mfma_f32_16x16x32_bf16 v[28:31], v[214:217], v[144:147], v[28:31]
	v_mfma_f32_16x16x32_bf16 v[24:27], v[234:237], v[144:147], v[24:27]
	v_mfma_f32_16x16x32_bf16 v[20:23], v[214:217], v[152:155], v[20:23]
	v_mfma_f32_16x16x32_bf16 v[16:19], v[234:237], v[152:155], v[16:19]
	v_mfma_f32_16x16x32_bf16 v[12:15], v[214:217], v[198:201], v[12:15]
	v_mfma_f32_16x16x32_bf16 v[8:11], v[234:237], v[198:201], v[8:11]
	v_mfma_f32_16x16x32_bf16 v[4:7], v[214:217], v[206:209], v[4:7]
	v_mfma_f32_16x16x32_bf16 v[0:3], v[234:237], v[206:209], v[0:3]
	v_mfma_f32_16x16x32_bf16 v[28:31], v[230:233], v[148:151], v[28:31]
	s_add_i32 s43, 0, 0x18000
	v_mfma_f32_16x16x32_bf16 v[24:27], v[238:241], v[148:151], v[24:27]
	v_add_u32_e32 v140, s43, v226
	v_mfma_f32_16x16x32_bf16 v[20:23], v[230:233], v[194:197], v[20:23]
	v_mfma_f32_16x16x32_bf16 v[16:19], v[238:241], v[194:197], v[16:19]
	v_mfma_f32_16x16x32_bf16 v[12:15], v[230:233], v[202:205], v[12:15]
	v_mfma_f32_16x16x32_bf16 v[8:11], v[238:241], v[202:205], v[8:11]
	v_mfma_f32_16x16x32_bf16 v[4:7], v[230:233], v[210:213], v[4:7]
	v_mfma_f32_16x16x32_bf16 v[0:3], v[238:241], v[210:213], v[0:3]
	s_setprio 0
	s_barrier
	ds_read_b128 v[128:131], v140
	ds_read_b128 v[132:135], v140 offset:1024
	ds_read_b128 v[136:139], v140 offset:2048
	ds_read_b128 v[140:143], v140 offset:3072
	s_add_u32 s20, s26, 0x90000
	s_addc_u32 s21, s27, 0
	s_mov_b32 m0, s36
	v_lshl_add_u64 v[214:215], s[20:21], 0, v[188:189]
	ds_read_b128 v[144:147], v228 offset:32768
	ds_read_b128 v[148:151], v228 offset:33792
	ds_read_b128 v[152:155], v228 offset:34816
	ds_read_b128 v[194:197], v228 offset:35840
	ds_read_b128 v[198:201], v228 offset:36864
	ds_read_b128 v[202:205], v228 offset:37888
	ds_read_b128 v[206:209], v228 offset:38912
	ds_read_b128 v[210:213], v228 offset:39936
	global_load_lds_dwordx4 v[214:215], off
	v_lshl_add_u64 v[214:215], s[20:21], 0, v[186:187]
	s_mov_b32 m0, s37
	s_nop 0
	global_load_lds_dwordx4 v[214:215], off
	s_waitcnt lgkmcnt(8)
	s_setprio 1
	s_barrier
	s_waitcnt lgkmcnt(0)
	v_mfma_f32_16x16x32_bf16 v[124:127], v[128:131], v[144:147], v[124:127]
	v_mfma_f32_16x16x32_bf16 v[120:123], v[136:139], v[144:147], v[120:123]
	v_mfma_f32_16x16x32_bf16 v[116:119], v[128:131], v[152:155], v[116:119]
	v_mfma_f32_16x16x32_bf16 v[112:115], v[136:139], v[152:155], v[112:115]
	v_mfma_f32_16x16x32_bf16 v[108:111], v[128:131], v[198:201], v[108:111]
	v_mfma_f32_16x16x32_bf16 v[104:107], v[136:139], v[198:201], v[104:107]
	v_mfma_f32_16x16x32_bf16 v[100:103], v[128:131], v[206:209], v[100:103]
	v_mfma_f32_16x16x32_bf16 v[96:99], v[136:139], v[206:209], v[96:99]
	v_mfma_f32_16x16x32_bf16 v[124:127], v[132:135], v[148:151], v[124:127]
	v_mfma_f32_16x16x32_bf16 v[120:123], v[140:143], v[148:151], v[120:123]
	v_mfma_f32_16x16x32_bf16 v[116:119], v[132:135], v[194:197], v[116:119]
	v_mfma_f32_16x16x32_bf16 v[112:115], v[140:143], v[194:197], v[112:115]
	v_mfma_f32_16x16x32_bf16 v[108:111], v[132:135], v[202:205], v[108:111]
	v_mfma_f32_16x16x32_bf16 v[104:107], v[140:143], v[202:205], v[104:107]
	v_mfma_f32_16x16x32_bf16 v[100:103], v[132:135], v[210:213], v[100:103]
	v_mfma_f32_16x16x32_bf16 v[96:99], v[140:143], v[210:213], v[96:99]
	s_setprio 0
	s_barrier
	s_add_i32 s26, 0, 0x1c000
	s_add_i32 s20, s43, s31
	v_add_u32_e32 v158, s26, v226
	v_lshl_add_u64 v[218:219], v[218:219], 0, s[94:95]
	s_mov_b32 m0, s20
	ds_read_b128 v[214:217], v158
	ds_read_b128 v[230:233], v158 offset:1024
	ds_read_b128 v[234:237], v158 offset:2048
	ds_read_b128 v[238:241], v158 offset:3072
	global_load_lds_dwordx4 v[218:219], off
	v_lshl_add_u64 v[218:219], v[220:221], 0, s[94:95]
	s_add_i32 m0, s20, 0x2000
	s_nop 0
	global_load_lds_dwordx4 v[218:219], off
	s_waitcnt lgkmcnt(0)
	s_setprio 1
	s_barrier
	v_mfma_f32_16x16x32_bf16 v[60:63], v[214:217], v[144:147], v[60:63]
	v_mfma_f32_16x16x32_bf16 v[56:59], v[234:237], v[144:147], v[56:59]
	v_mfma_f32_16x16x32_bf16 v[52:55], v[214:217], v[152:155], v[52:55]
	v_mfma_f32_16x16x32_bf16 v[48:51], v[234:237], v[152:155], v[48:51]
	v_mfma_f32_16x16x32_bf16 v[44:47], v[214:217], v[198:201], v[44:47]
	v_mfma_f32_16x16x32_bf16 v[40:43], v[234:237], v[198:201], v[40:43]
	v_mfma_f32_16x16x32_bf16 v[36:39], v[214:217], v[206:209], v[36:39]
	v_mfma_f32_16x16x32_bf16 v[32:35], v[234:237], v[206:209], v[32:35]
	v_mfma_f32_16x16x32_bf16 v[60:63], v[230:233], v[148:151], v[60:63]
	s_mov_b32 m0, s38
	v_mfma_f32_16x16x32_bf16 v[56:59], v[238:241], v[148:151], v[56:59]
	v_lshl_add_u64 v[218:219], v[242:243], 0, s[94:95]
	v_mfma_f32_16x16x32_bf16 v[52:55], v[230:233], v[194:197], v[52:55]
	v_mfma_f32_16x16x32_bf16 v[48:51], v[238:241], v[194:197], v[48:51]
	v_mfma_f32_16x16x32_bf16 v[44:47], v[230:233], v[202:205], v[44:47]
	v_mfma_f32_16x16x32_bf16 v[40:43], v[238:241], v[202:205], v[40:43]
	v_mfma_f32_16x16x32_bf16 v[36:39], v[230:233], v[210:213], v[36:39]
	v_mfma_f32_16x16x32_bf16 v[32:35], v[238:241], v[210:213], v[32:35]
	s_setprio 0
	s_barrier
	ds_read_b128 v[144:147], v228 offset:49152
	ds_read_b128 v[148:151], v228 offset:50176
	ds_read_b128 v[152:155], v228 offset:51200
	ds_read_b128 v[194:197], v228 offset:52224
	ds_read_b128 v[198:201], v228 offset:53248
	ds_read_b128 v[202:205], v228 offset:54272
	ds_read_b128 v[206:209], v228 offset:55296
	ds_read_b128 v[210:213], v228 offset:56320
	global_load_lds_dwordx4 v[218:219], off
	v_lshl_add_u64 v[218:219], v[244:245], 0, s[94:95]
	s_mov_b32 m0, s39
	s_nop 0
	global_load_lds_dwordx4 v[218:219], off
	s_waitcnt lgkmcnt(0)
	s_setprio 1
	s_barrier
; #define PG8_BAR __builtin_amdgcn_s_barrier()
; template <class Epi>
; DI void gemm_phase(LAS unsigned char* lds, const Gemm g, const StaticOrder& S, const Epi& E) {
;     ...
;             PG8_LDA(At, 1, 1); PG8_STAGE(PG8_SA(1, 0), a3);
;             PG8_BAR; PG8_WAIT_L(0); PG8_MMA(1, 0, At, B0); PG8_BAR; PG8_SCHED;
;             PG8_STAGE(PG8_SB(1, 1), b3 + hstep);
;             PG8_WAIT_V(6); PG8_BAR; PG8_MMA(1, 1, At, B1); PG8_BAR;
;     template <bool LN, int BJ, int LO, int HI> DI void batch(const f32x4 (&acc)[2][2][4][2], unsigned row0, unsigned col0, const f32x4 (&gv)[2], const f32x4 (&bv)[2]) const {
;         f32x4 r[HI - LO]; float mean[(HI - LO) / 2], rstd[(HI - LO) / 2];
; #pragma unroll
;         for (int i = LO; i < HI; ++i) { const int ai = i >> 3, m = (i >> 1) & 3, n = i & 1; const unsigned row = row0 + ai * HALF + m * 16;
;             if (n == 0) { mean[(i - LO) >> 1] = 0.f; rstd[(i - LO) >> 1] = 1.f;
;                 if (LN) { const float2 st = *(const float2*)(stats + row * 2u); mean[(i - LO) >> 1] = st.x; rstd[(i - LO) >> 1] = st.y; } }
;             r[i - LO] = *(const f32x4*)(src + (row * (unsigned)DM + col0 + BJ * HALF + n * 16)); }
; #pragma unroll
;         for (int i = LO; i < HI; ++i) { const int ai = i >> 3, m = (i >> 1) & 3, n = i & 1; const unsigned row = row0 + ai * HALF + m * 16;
;             *(f32x4*)(Y + (row * (unsigned)DM + col0 + BJ * HALF + n * 16)) = acc[ai][BJ][m][n] + ((r[i - LO] - mean[(i - LO) >> 1]) * rstd[(i - LO) >> 1]) * gv[n] + bv[n]; }
;         __builtin_amdgcn_sched_barrier(0);
;     }
;     template <bool LN, int BJ> DI void load_gb(unsigned col0, f32x4 (&gv)[2], f32x4 (&bv)[2]) const {
; #pragma unroll
;         for (int n = 0; n < 2; ++n) {
;             if (LN) { gv[n] = *(const f32x4*)(gam + col0 + BJ * HALF + n * 16) * ALPHA; bv[n] = *(const f32x4*)(bet + col0 + BJ * HALF + n * 16) * ALPHA; }
;             else { gv[n] = (f32x4){ALPHA, ALPHA, ALPHA, ALPHA}; bv[n] = (f32x4){0.f, 0.f, 0.f, 0.f}; }
;         }
;     }
;     template <bool LN> DI void run(const f32x4 (&acc)[2][2][4][2], const Unit& u, int wr, int wc, int fr, int fq) const {
;         const unsigned row0 = u.pm * BM + wr * 64 + fr, col0 = u.pn * BM + wc * 32 + 4 * fq;
;         f32x4 gv[2], bv[2];
;         load_gb<LN, 0>(col0, gv, bv);
;         batch<LN, 0, 0, 4>(acc, row0, col0, gv, bv);
;         batch<LN, 0, 4, 8>(acc, row0, col0, gv, bv);
	v_mfma_f32_16x16x32_bf16 v[92:95], v[128:131], v[144:147], v[92:95]
	v_mfma_f32_16x16x32_bf16 v[88:91], v[136:139], v[144:147], v[88:91]
	v_mfma_f32_16x16x32_bf16 v[84:87], v[128:131], v[152:155], v[84:87]
	v_mfma_f32_16x16x32_bf16 v[80:83], v[136:139], v[152:155], v[80:83]
	v_mfma_f32_16x16x32_bf16 v[76:79], v[128:131], v[198:201], v[76:79]
	v_mfma_f32_16x16x32_bf16 v[72:75], v[136:139], v[198:201], v[72:75]
	v_mfma_f32_16x16x32_bf16 v[68:71], v[128:131], v[206:209], v[68:71]
	v_mfma_f32_16x16x32_bf16 v[64:67], v[136:139], v[206:209], v[64:67]
	v_mfma_f32_16x16x32_bf16 v[92:95], v[132:135], v[148:151], v[92:95]
	v_mfma_f32_16x16x32_bf16 v[88:91], v[140:143], v[148:151], v[88:91]
	v_mfma_f32_16x16x32_bf16 v[84:87], v[132:135], v[194:197], v[84:87]
	v_mfma_f32_16x16x32_bf16 v[80:83], v[140:143], v[194:197], v[80:83]
	v_mfma_f32_16x16x32_bf16 v[76:79], v[132:135], v[202:205], v[76:79]
	v_mfma_f32_16x16x32_bf16 v[72:75], v[140:143], v[202:205], v[72:75]
	v_mfma_f32_16x16x32_bf16 v[68:71], v[132:135], v[210:213], v[68:71]
	v_mfma_f32_16x16x32_bf16 v[64:67], v[140:143], v[210:213], v[64:67]
	s_setprio 0
	s_barrier
	s_add_u32 s20, s24, 0x90080
	s_addc_u32 s21, s25, 0
	s_add_i32 s24, s26, s31
	v_lshl_add_u64 v[128:129], s[20:21], 0, v[188:189]
	s_mov_b32 m0, s24
	s_nop 0
	global_load_lds_dwordx4 v[128:129], off
	v_lshl_add_u64 v[128:129], s[20:21], 0, v[186:187]
	s_add_i32 m0, s24, 0x2000
	s_nop 0
	global_load_lds_dwordx4 v[128:129], off
	s_waitcnt vmcnt(6)
	s_setprio 1
	s_barrier
	v_mfma_f32_16x16x32_bf16 v[28:31], v[214:217], v[144:147], v[28:31]
	v_mfma_f32_16x16x32_bf16 v[24:27], v[234:237], v[144:147], v[24:27]
	v_mfma_f32_16x16x32_bf16 v[20:23], v[214:217], v[152:155], v[20:23]
	v_mfma_f32_16x16x32_bf16 v[16:19], v[234:237], v[152:155], v[16:19]
	v_mfma_f32_16x16x32_bf16 v[12:15], v[214:217], v[198:201], v[12:15]
	v_mfma_f32_16x16x32_bf16 v[8:11], v[234:237], v[198:201], v[8:11]
	v_mfma_f32_16x16x32_bf16 v[4:7], v[214:217], v[206:209], v[4:7]
	v_mfma_f32_16x16x32_bf16 v[0:3], v[234:237], v[206:209], v[0:3]
	v_mfma_f32_16x16x32_bf16 v[28:31], v[230:233], v[148:151], v[28:31]
	s_add_i32 s33, s33, 2
	v_mfma_f32_16x16x32_bf16 v[24:27], v[238:241], v[148:151], v[24:27]
	s_add_u32 s4, s4, 0x100
	v_mfma_f32_16x16x32_bf16 v[20:23], v[230:233], v[194:197], v[20:23]
	s_addc_u32 s5, s5, 0
	v_mfma_f32_16x16x32_bf16 v[16:19], v[238:241], v[194:197], v[16:19]
	s_cmp_gt_u32 s33, 33
	v_mfma_f32_16x16x32_bf16 v[12:15], v[230:233], v[202:205], v[12:15]
	s_mov_b64 s[20:21], s[22:23]
	v_mfma_f32_16x16x32_bf16 v[8:11], v[238:241], v[202:205], v[8:11]
	v_mfma_f32_16x16x32_bf16 v[4:7], v[230:233], v[210:213], v[4:7]
	v_mfma_f32_16x16x32_bf16 v[0:3], v[238:241], v[210:213], v[0:3]
	s_setprio 0
	s_barrier
	s_cbranch_scc0 .LBB0_77
	v_lshl_add_u32 v206, s3, 8, v225
	v_lshl_or_b32 v158, s2, 8, v227
	v_lshlrev_b32_e32 v232, 11, v206
	s_andn2_b64 vcc, exec, s[14:15]
	v_or_b32_e32 v231, 16, v158
	v_add_u32_e32 v194, v232, v158
	v_or_b32_e32 v230, 0x80, v158
	v_or_b32_e32 v229, 0x90, v158
	s_cbranch_vccnz .LBB0_80
	v_lshlrev_b64 v[132:133], 2, v[158:159]
	v_lshl_add_u64 v[140:141], s[16:17], 0, v[132:133]
	global_load_dwordx4 v[128:131], v[140:141], off
	v_lshl_add_u64 v[142:143], s[18:19], 0, v[132:133]
	v_readlane_b32 s2, v253, 8
	v_mov_b32_e32 v195, v159
	v_lshlrev_b32_e32 v136, 1, v206
	v_mov_b32_e32 v137, v159
	v_readlane_b32 s3, v253, 9
	v_lshlrev_b64 v[212:213], 2, v[194:195]
	v_add_u32_e32 v146, v232, v231
	v_lshl_add_u64 v[144:145], v[136:137], 2, s[2:3]
	v_lshl_add_u64 v[136:137], s[88:89], 0, v[212:213]
	v_mov_b32_e32 v147, v159
	v_lshl_add_u64 v[146:147], v[146:147], 2, s[88:89]
	v_or_b32_e32 v195, 16, v206
	v_mov_b32_e32 v201, v159
	v_mov_b32_e32 v209, v159
	v_lshl_add_u64 v[212:213], s[90:91], 0, v[212:213]
	s_waitcnt vmcnt(0)
	v_pk_mul_f32 v[152:153], v[130:131], s[78:79] op_sel_hi:[1,0]
	v_pk_mul_f32 v[154:155], v[128:129], s[78:79] op_sel_hi:[1,0]
	global_load_dwordx4 v[132:135], v[142:143], off
	global_load_dwordx4 v[128:131], v[140:141], off offset:64
	global_load_dwordx2 v[204:205], v[144:145], off
	global_load_dwordx4 v[196:199], v[146:147], off
	v_lshlrev_b32_e32 v146, 1, v195
	global_load_dwordx4 v[136:139], v[136:137], off
	v_lshlrev_b32_e32 v195, 11, v195
	v_mov_b32_e32 v147, v159
	v_add_u32_e32 v200, v195, v158
	v_lshl_add_u64 v[146:147], v[146:147], 2, s[2:3]
	v_lshl_add_u64 v[200:201], v[200:201], 2, s[88:89]
	global_load_dwordx2 v[214:215], v[146:147], off
	v_add_u32_e32 v208, v195, v231
	global_load_dwordx4 v[200:203], v[200:201], off
	v_lshl_add_u64 v[208:209], v[208:209], 2, s[88:89]
	global_load_dwordx4 v[208:211], v[208:209], off
	s_waitcnt vmcnt(0)
	v_pk_mul_f32 v[148:149], v[130:131], s[78:79] op_sel_hi:[1,0]
	v_pk_mul_f32 v[150:151], v[128:129], s[78:79] op_sel_hi:[1,0]
	global_load_dwordx4 v[128:131], v[142:143], off offset:64
	v_sub_f32_e32 v137, v137, v204
	v_sub_f32_e32 v136, v136, v204
	v_sub_f32_e32 v139, v139, v204
	v_sub_f32_e32 v138, v138, v204
	v_pk_mul_f32 v[138:139], v[204:205], v[138:139] op_sel:[1,0]
	v_pk_mul_f32 v[136:137], v[204:205], v[136:137] op_sel:[1,0]
	v_pk_fma_f32 v[138:139], v[152:153], v[138:139], v[126:127]
	v_pk_fma_f32 v[136:137], v[154:155], v[136:137], v[124:125]
	v_pk_fma_f32 v[138:139], v[134:135], s[78:79], v[138:139] op_sel_hi:[1,0,1]
	v_pk_fma_f32 v[136:137], v[132:133], s[78:79], v[136:137] op_sel_hi:[1,0,1]
	global_store_dwordx4 v[212:213], v[136:139], off
	s_nop 1
	v_sub_f32_e32 v137, v197, v204
	v_sub_f32_e32 v136, v196, v204
	v_sub_f32_e32 v139, v199, v204
	v_sub_f32_e32 v138, v198, v204
	v_pk_mul_f32 v[138:139], v[204:205], v[138:139] op_sel:[1,0]
	v_pk_mul_f32 v[136:137], v[204:205], v[136:137] op_sel:[1,0]
	v_pk_fma_f32 v[138:139], v[148:149], v[138:139], v[122:123]
	v_pk_fma_f32 v[136:137], v[150:151], v[136:137], v[120:121]
	v_or_b32_e32 v196, 16, v194
	v_mov_b32_e32 v197, v159
	v_lshl_add_u64 v[196:197], v[196:197], 2, s[90:91]
	s_waitcnt vmcnt(0)
;     template <bool LN, int BJ, int LO, int HI> DI void batch(const f32x4 (&acc)[2][2][4][2], unsigned row0, unsigned col0, const f32x4 (&gv)[2], const f32x4 (&bv)[2]) const {
;         f32x4 r[HI - LO]; float mean[(HI - LO) / 2], rstd[(HI - LO) / 2];
; #pragma unroll
;         for (int i = LO; i < HI; ++i) { const int ai = i >> 3, m = (i >> 1) & 3, n = i & 1; const unsigned row = row0 + ai * HALF + m * 16;
;             if (n == 0) { mean[(i - LO) >> 1] = 0.f; rstd[(i - LO) >> 1] = 1.f;
;                 if (LN) { const float2 st = *(const float2*)(stats + row * 2u); mean[(i - LO) >> 1] = st.x; rstd[(i - LO) >> 1] = st.y; } }
;             r[i - LO] = *(const f32x4*)(src + (row * (unsigned)DM + col0 + BJ * HALF + n * 16)); }
; #pragma unroll
;         for (int i = LO; i < HI; ++i) { const int ai = i >> 3, m = (i >> 1) & 3, n = i & 1; const unsigned row = row0 + ai * HALF + m * 16;
;             *(f32x4*)(Y + (row * (unsigned)DM + col0 + BJ * HALF + n * 16)) = acc[ai][BJ][m][n] + ((r[i - LO] - mean[(i - LO) >> 1]) * rstd[(i - LO) >> 1]) * gv[n] + bv[n]; }
	v_pk_fma_f32 v[138:139], v[130:131], s[78:79], v[138:139] op_sel_hi:[1,0,1]
	v_pk_fma_f32 v[136:137], v[128:129], s[78:79], v[136:137] op_sel_hi:[1,0,1]
	global_store_dwordx4 v[196:197], v[136:139], off
	v_add_u32_e32 v196, 0x8000, v194
	v_mov_b32_e32 v197, v159
	v_sub_f32_e32 v137, v201, v214
	v_sub_f32_e32 v136, v200, v214
	v_sub_f32_e32 v139, v203, v214
	v_sub_f32_e32 v138, v202, v214
	v_pk_mul_f32 v[138:139], v[214:215], v[138:139] op_sel:[1,0]
	v_pk_mul_f32 v[136:137], v[214:215], v[136:137] op_sel:[1,0]
	v_pk_fma_f32 v[138:139], v[152:153], v[138:139], v[118:119]
	v_pk_fma_f32 v[136:137], v[154:155], v[136:137], v[116:117]
	v_pk_fma_f32 v[138:139], v[134:135], s[78:79], v[138:139] op_sel_hi:[1,0,1]
	v_pk_fma_f32 v[136:137], v[132:133], s[78:79], v[136:137] op_sel_hi:[1,0,1]
	v_lshl_add_u64 v[196:197], v[196:197], 2, s[90:91]
	global_store_dwordx4 v[196:197], v[136:139], off
	v_add_u32_e32 v196, 0x8010, v194
	v_mov_b32_e32 v197, v159
	v_sub_f32_e32 v137, v209, v214
	v_sub_f32_e32 v136, v208, v214
	v_sub_f32_e32 v139, v211, v214
	v_sub_f32_e32 v138, v210, v214
	v_pk_mul_f32 v[138:139], v[214:215], v[138:139] op_sel:[1,0]
	v_pk_mul_f32 v[136:137], v[214:215], v[136:137] op_sel:[1,0]
	v_pk_fma_f32 v[138:139], v[148:149], v[138:139], v[114:115]
	v_pk_fma_f32 v[136:137], v[150:151], v[136:137], v[112:113]
	v_pk_fma_f32 v[138:139], v[130:131], s[78:79], v[138:139] op_sel_hi:[1,0,1]
	v_pk_fma_f32 v[136:137], v[128:129], s[78:79], v[136:137] op_sel_hi:[1,0,1]
	v_lshl_add_u64 v[196:197], v[196:197], 2, s[90:91]
	global_store_dwordx4 v[196:197], v[136:139], off
	s_nop 1
	v_or_b32_e32 v138, 32, v206
	v_lshlrev_b32_e32 v136, 1, v138
	v_mov_b32_e32 v137, v159
	v_lshlrev_b32_e32 v236, 11, v138
	v_lshl_add_u64 v[200:201], v[136:137], 2, s[2:3]
	v_add_u32_e32 v136, v236, v158
	v_lshl_add_u64 v[136:137], v[136:137], 2, s[88:89]
	global_load_dwordx2 v[204:205], v[200:201], off
	v_add_u32_e32 v196, v236, v231
	global_load_dwordx4 v[136:139], v[136:137], off
	v_mov_b32_e32 v197, v159
	v_lshl_add_u64 v[196:197], v[196:197], 2, s[88:89]
	global_load_dwordx4 v[196:199], v[196:197], off
	v_or_b32_e32 v207, 48, v206
	v_lshlrev_b32_e32 v235, 11, v207
	v_lshlrev_b32_e32 v202, 1, v207
	v_mov_b32_e32 v203, v159
	v_add_u32_e32 v208, v235, v158
	v_mov_b32_e32 v209, v159
	v_lshl_add_u64 v[202:203], v[202:203], 2, s[2:3]
	v_lshl_add_u64 v[208:209], v[208:209], 2, s[88:89]
	global_load_dwordx2 v[216:217], v[202:203], off
	v_add_u32_e32 v212, v235, v231
	global_load_dwordx4 v[208:211], v[208:209], off
	v_mov_b32_e32 v213, v159
	v_lshl_add_u64 v[212:213], v[212:213], 2, s[88:89]
	global_load_dwordx4 v[212:215], v[212:213], off
	v_add_u32_e32 v218, 0x10000, v194
	v_mov_b32_e32 v219, v159
	v_lshl_add_u64 v[218:219], v[218:219], 2, s[90:91]
	s_waitcnt vmcnt(0)
	v_sub_f32_e32 v137, v137, v204
	v_sub_f32_e32 v136, v136, v204
	v_sub_f32_e32 v139, v139, v204
	v_sub_f32_e32 v138, v138, v204
	v_pk_mul_f32 v[138:139], v[204:205], v[138:139] op_sel:[1,0]
	v_pk_mul_f32 v[136:137], v[204:205], v[136:137] op_sel:[1,0]
	v_pk_fma_f32 v[138:139], v[152:153], v[138:139], v[110:111]
	v_pk_fma_f32 v[136:137], v[154:155], v[136:137], v[108:109]
	v_pk_fma_f32 v[138:139], v[134:135], s[78:79], v[138:139] op_sel_hi:[1,0,1]
	v_pk_fma_f32 v[136:137], v[132:133], s[78:79], v[136:137] op_sel_hi:[1,0,1]
	global_store_dwordx4 v[218:219], v[136:139], off
	s_nop 1
	v_sub_f32_e32 v137, v197, v204
	v_sub_f32_e32 v136, v196, v204
	v_sub_f32_e32 v139, v199, v204
	v_sub_f32_e32 v138, v198, v204
	v_pk_mul_f32 v[138:139], v[204:205], v[138:139] op_sel:[1,0]
	v_pk_mul_f32 v[136:137], v[204:205], v[136:137] op_sel:[1,0]
	v_pk_fma_f32 v[138:139], v[148:149], v[138:139], v[106:107]
	v_pk_fma_f32 v[136:137], v[150:151], v[136:137], v[104:105]
	v_add_u32_e32 v196, 0x10010, v194
	v_mov_b32_e32 v197, v159
	v_pk_fma_f32 v[138:139], v[130:131], s[78:79], v[138:139] op_sel_hi:[1,0,1]
	v_pk_fma_f32 v[136:137], v[128:129], s[78:79], v[136:137] op_sel_hi:[1,0,1]
	v_lshl_add_u64 v[196:197], v[196:197], 2, s[90:91]
	global_store_dwordx4 v[196:197], v[136:139], off
	v_add_u32_e32 v196, 0x18000, v194
	v_mov_b32_e32 v197, v159
	v_sub_f32_e32 v137, v209, v216
	v_sub_f32_e32 v136, v208, v216
	v_sub_f32_e32 v139, v211, v216
	v_sub_f32_e32 v138, v210, v216
	v_pk_mul_f32 v[138:139], v[216:217], v[138:139] op_sel:[1,0]
	v_pk_mul_f32 v[136:137], v[216:217], v[136:137] op_sel:[1,0]
	v_pk_fma_f32 v[138:139], v[152:153], v[138:139], v[102:103]
	v_pk_fma_f32 v[136:137], v[154:155], v[136:137], v[100:101]
	v_pk_fma_f32 v[138:139], v[134:135], s[78:79], v[138:139] op_sel_hi:[1,0,1]
	v_pk_fma_f32 v[136:137], v[132:133], s[78:79], v[136:137] op_sel_hi:[1,0,1]
	v_lshl_add_u64 v[196:197], v[196:197], 2, s[90:91]
	global_store_dwordx4 v[196:197], v[136:139], off
	v_add_u32_e32 v196, 0x18010, v194
	v_mov_b32_e32 v197, v159
	v_sub_f32_e32 v137, v213, v216
	v_sub_f32_e32 v136, v212, v216
	v_sub_f32_e32 v139, v215, v216
	v_sub_f32_e32 v138, v214, v216
	v_pk_mul_f32 v[138:139], v[216:217], v[138:139] op_sel:[1,0]
	v_pk_mul_f32 v[136:137], v[216:217], v[136:137] op_sel:[1,0]
	v_pk_fma_f32 v[138:139], v[148:149], v[138:139], v[98:99]
	v_pk_fma_f32 v[136:137], v[150:151], v[136:137], v[96:97]
	v_pk_fma_f32 v[138:139], v[130:131], s[78:79], v[138:139] op_sel_hi:[1,0,1]
	v_pk_fma_f32 v[136:137], v[128:129], s[78:79], v[136:137] op_sel_hi:[1,0,1]
	v_lshl_add_u64 v[196:197], v[196:197], 2, s[90:91]
	global_store_dwordx4 v[196:197], v[136:139], off
	s_nop 1
	v_add_u32_e32 v138, 0x80, v206
	v_lshlrev_b32_e32 v136, 1, v138
	v_mov_b32_e32 v137, v159
	v_lshlrev_b32_e32 v233, 11, v138
	v_lshl_add_u64 v[196:197], v[136:137], 2, s[2:3]
	v_add_u32_e32 v136, v233, v158
	v_lshl_add_u64 v[136:137], v[136:137], 2, s[88:89]
	global_load_dwordx2 v[204:205], v[196:197], off
	v_add_u32_e32 v198, v233, v231
	global_load_dwordx4 v[136:139], v[136:137], off
	v_mov_b32_e32 v199, v159
	v_add_u32_e32 v207, 0x90, v206
	v_lshl_add_u64 v[198:199], v[198:199], 2, s[88:89]
	v_lshlrev_b32_e32 v234, 11, v207
	global_load_dwordx4 v[208:211], v[198:199], off
	v_add_u32_e32 v212, v234, v158
	v_mov_b32_e32 v213, v159
	v_lshl_add_u64 v[212:213], v[212:213], 2, s[88:89]
	global_load_dwordx4 v[212:215], v[212:213], off
	v_lshlrev_b32_e32 v198, 1, v207
	v_mov_b32_e32 v199, v159
	v_lshl_add_u64 v[198:199], v[198:199], 2, s[2:3]
	global_load_dwordx2 v[220:221], v[198:199], off
	v_add_u32_e32 v216, v234, v231
	v_mov_b32_e32 v217, v159
	v_lshl_add_u64 v[216:217], v[216:217], 2, s[88:89]
	global_load_dwordx4 v[216:219], v[216:217], off
	v_add_u32_e32 v238, 0x40000, v194
	v_mov_b32_e32 v239, v159
	v_lshl_add_u64 v[238:239], v[238:239], 2, s[90:91]
	s_waitcnt vmcnt(0)
;     template <bool LN, int BJ, int LO, int HI> DI void batch(const f32x4 (&acc)[2][2][4][2], unsigned row0, unsigned col0, const f32x4 (&gv)[2], const f32x4 (&bv)[2]) const {
;         f32x4 r[HI - LO]; float mean[(HI - LO) / 2], rstd[(HI - LO) / 2];
; #pragma unroll
;         for (int i = LO; i < HI; ++i) { const int ai = i >> 3, m = (i >> 1) & 3, n = i & 1; const unsigned row = row0 + ai * HALF + m * 16;
;             if (n == 0) { mean[(i - LO) >> 1] = 0.f; rstd[(i - LO) >> 1] = 1.f;
;                 if (LN) { const float2 st = *(const float2*)(stats + row * 2u); mean[(i - LO) >> 1] = st.x; rstd[(i - LO) >> 1] = st.y; } }
;             r[i - LO] = *(const f32x4*)(src + (row * (unsigned)DM + col0 + BJ * HALF + n * 16)); }
; #pragma unroll
;         for (int i = LO; i < HI; ++i) { const int ai = i >> 3, m = (i >> 1) & 3, n = i & 1; const unsigned row = row0 + ai * HALF + m * 16;
;             *(f32x4*)(Y + (row * (unsigned)DM + col0 + BJ * HALF + n * 16)) = acc[ai][BJ][m][n] + ((r[i - LO] - mean[(i - LO) >> 1]) * rstd[(i - LO) >> 1]) * gv[n] + bv[n]; }
;         __builtin_amdgcn_sched_barrier(0);
;     }
;     template <bool LN, int BJ> DI void load_gb(unsigned col0, f32x4 (&gv)[2], f32x4 (&bv)[2]) const {
; #pragma unroll
;         for (int n = 0; n < 2; ++n) {
;             if (LN) { gv[n] = *(const f32x4*)(gam + col0 + BJ * HALF + n * 16) * ALPHA; bv[n] = *(const f32x4*)(bet + col0 + BJ * HALF + n * 16) * ALPHA; }
;             else { gv[n] = (f32x4){ALPHA, ALPHA, ALPHA, ALPHA}; bv[n] = (f32x4){0.f, 0.f, 0.f, 0.f}; }
;         }
;     }
	v_sub_f32_e32 v137, v137, v204
	v_sub_f32_e32 v136, v136, v204
	v_sub_f32_e32 v139, v139, v204
	v_sub_f32_e32 v138, v138, v204
	v_pk_mul_f32 v[138:139], v[204:205], v[138:139] op_sel:[1,0]
	v_pk_mul_f32 v[136:137], v[204:205], v[136:137] op_sel:[1,0]
	v_pk_fma_f32 v[138:139], v[152:153], v[138:139], v[94:95]
	v_pk_fma_f32 v[136:137], v[154:155], v[136:137], v[92:93]
	v_pk_fma_f32 v[138:139], v[134:135], s[78:79], v[138:139] op_sel_hi:[1,0,1]
	v_pk_fma_f32 v[136:137], v[132:133], s[78:79], v[136:137] op_sel_hi:[1,0,1]
	global_store_dwordx4 v[238:239], v[136:139], off
	s_nop 1
	v_sub_f32_e32 v137, v209, v204
	v_sub_f32_e32 v136, v208, v204
	v_sub_f32_e32 v139, v211, v204
	v_sub_f32_e32 v138, v210, v204
	v_pk_mul_f32 v[138:139], v[204:205], v[138:139] op_sel:[1,0]
	v_pk_mul_f32 v[136:137], v[204:205], v[136:137] op_sel:[1,0]
	v_pk_fma_f32 v[138:139], v[148:149], v[138:139], v[90:91]
	v_pk_fma_f32 v[136:137], v[150:151], v[136:137], v[88:89]
	v_add_u32_e32 v204, 0x40010, v194
	v_mov_b32_e32 v205, v159
	v_pk_fma_f32 v[138:139], v[130:131], s[78:79], v[138:139] op_sel_hi:[1,0,1]
	v_pk_fma_f32 v[136:137], v[128:129], s[78:79], v[136:137] op_sel_hi:[1,0,1]
	v_lshl_add_u64 v[204:205], v[204:205], 2, s[90:91]
	global_store_dwordx4 v[204:205], v[136:139], off
	v_add_u32_e32 v204, 0x48000, v194
	v_mov_b32_e32 v205, v159
	v_sub_f32_e32 v137, v213, v220
	v_sub_f32_e32 v136, v212, v220
	v_sub_f32_e32 v139, v215, v220
	v_sub_f32_e32 v138, v214, v220
	v_pk_mul_f32 v[138:139], v[220:221], v[138:139] op_sel:[1,0]
	v_pk_mul_f32 v[136:137], v[220:221], v[136:137] op_sel:[1,0]
	v_pk_fma_f32 v[138:139], v[152:153], v[138:139], v[86:87]
	v_pk_fma_f32 v[136:137], v[154:155], v[136:137], v[84:85]
	v_pk_fma_f32 v[138:139], v[134:135], s[78:79], v[138:139] op_sel_hi:[1,0,1]
	v_pk_fma_f32 v[136:137], v[132:133], s[78:79], v[136:137] op_sel_hi:[1,0,1]
	v_lshl_add_u64 v[204:205], v[204:205], 2, s[90:91]
	global_store_dwordx4 v[204:205], v[136:139], off
	v_add_u32_e32 v204, 0x48010, v194
	v_mov_b32_e32 v205, v159
	v_sub_f32_e32 v137, v217, v220
	v_sub_f32_e32 v136, v216, v220
	v_sub_f32_e32 v139, v219, v220
	v_sub_f32_e32 v138, v218, v220
	v_pk_mul_f32 v[138:139], v[220:221], v[138:139] op_sel:[1,0]
	v_pk_mul_f32 v[136:137], v[220:221], v[136:137] op_sel:[1,0]
	v_pk_fma_f32 v[138:139], v[148:149], v[138:139], v[82:83]
	v_pk_fma_f32 v[136:137], v[150:151], v[136:137], v[80:81]
	v_pk_fma_f32 v[138:139], v[130:131], s[78:79], v[138:139] op_sel_hi:[1,0,1]
	v_pk_fma_f32 v[136:137], v[128:129], s[78:79], v[136:137] op_sel_hi:[1,0,1]
	v_lshl_add_u64 v[204:205], v[204:205], 2, s[90:91]
	global_store_dwordx4 v[204:205], v[136:139], off
	s_nop 1
	v_add_u32_e32 v138, 0xa0, v206
	v_lshlrev_b32_e32 v136, 1, v138
	v_mov_b32_e32 v137, v159
	v_lshlrev_b32_e32 v237, 11, v138
	v_lshl_add_u64 v[204:205], v[136:137], 2, s[2:3]
	v_add_u32_e32 v136, v237, v158
	v_lshl_add_u64 v[136:137], v[136:137], 2, s[88:89]
	global_load_dwordx2 v[220:221], v[204:205], off
	v_add_u32_e32 v208, v237, v231
	global_load_dwordx4 v[136:139], v[136:137], off
	v_mov_b32_e32 v209, v159
	v_lshl_add_u64 v[208:209], v[208:209], 2, s[88:89]
	global_load_dwordx4 v[212:215], v[208:209], off
	v_add_u32_e32 v208, 0xb0, v206
	v_lshlrev_b32_e32 v206, 1, v208
	v_mov_b32_e32 v207, v159
	v_lshlrev_b32_e32 v238, 11, v208
	v_lshl_add_u64 v[210:211], v[206:207], 2, s[2:3]
	v_add_u32_e32 v206, v238, v158
	v_lshl_add_u64 v[206:207], v[206:207], 2, s[88:89]
	global_load_dwordx2 v[240:241], v[210:211], off
	v_add_u32_e32 v216, v238, v231
	global_load_dwordx4 v[206:209], v[206:207], off
	v_mov_b32_e32 v217, v159
	v_lshl_add_u64 v[216:217], v[216:217], 2, s[88:89]
	global_load_dwordx4 v[216:219], v[216:217], off
	v_add_u32_e32 v242, 0x50000, v194
	v_mov_b32_e32 v243, v159
	v_lshl_add_u64 v[242:243], v[242:243], 2, s[90:91]
	s_waitcnt vmcnt(0)
	v_sub_f32_e32 v137, v137, v220
	v_sub_f32_e32 v136, v136, v220
	v_sub_f32_e32 v139, v139, v220
	v_sub_f32_e32 v138, v138, v220
	v_pk_mul_f32 v[138:139], v[220:221], v[138:139] op_sel:[1,0]
	v_pk_mul_f32 v[136:137], v[220:221], v[136:137] op_sel:[1,0]
	v_pk_fma_f32 v[138:139], v[152:153], v[138:139], v[78:79]
	v_pk_fma_f32 v[136:137], v[154:155], v[136:137], v[76:77]
	v_pk_fma_f32 v[138:139], v[134:135], s[78:79], v[138:139] op_sel_hi:[1,0,1]
	v_pk_fma_f32 v[136:137], v[132:133], s[78:79], v[136:137] op_sel_hi:[1,0,1]
	global_store_dwordx4 v[242:243], v[136:139], off
	s_nop 1
	v_sub_f32_e32 v137, v213, v220
	v_sub_f32_e32 v136, v212, v220
	v_sub_f32_e32 v139, v215, v220
	v_sub_f32_e32 v138, v214, v220
	v_pk_mul_f32 v[138:139], v[220:221], v[138:139] op_sel:[1,0]
	v_pk_mul_f32 v[136:137], v[220:221], v[136:137] op_sel:[1,0]
	v_pk_fma_f32 v[138:139], v[148:149], v[138:139], v[74:75]
	v_pk_fma_f32 v[136:137], v[150:151], v[136:137], v[72:73]
	v_add_u32_e32 v212, 0x50010, v194
	v_mov_b32_e32 v213, v159
	v_pk_fma_f32 v[138:139], v[130:131], s[78:79], v[138:139] op_sel_hi:[1,0,1]
	v_pk_fma_f32 v[136:137], v[128:129], s[78:79], v[136:137] op_sel_hi:[1,0,1]
	v_lshl_add_u64 v[212:213], v[212:213], 2, s[90:91]
	global_store_dwordx4 v[212:213], v[136:139], off
	s_nop 1
	v_sub_f32_e32 v137, v207, v240
	v_sub_f32_e32 v136, v206, v240
	v_sub_f32_e32 v139, v209, v240
	v_sub_f32_e32 v138, v208, v240
	v_pk_mul_f32 v[136:137], v[240:241], v[136:137] op_sel:[1,0]
	v_pk_mul_f32 v[138:139], v[240:241], v[138:139] op_sel:[1,0]
	v_pk_fma_f32 v[136:137], v[154:155], v[136:137], v[68:69]
	v_pk_fma_f32 v[138:139], v[152:153], v[138:139], v[70:71]
	v_pk_fma_f32 v[132:133], v[132:133], s[78:79], v[136:137] op_sel_hi:[1,0,1]
	v_add_u32_e32 v136, 0x58000, v194
	v_mov_b32_e32 v137, v159
	v_pk_fma_f32 v[134:135], v[134:135], s[78:79], v[138:139] op_sel_hi:[1,0,1]
	v_lshl_add_u64 v[136:137], v[136:137], 2, s[90:91]
	global_store_dwordx4 v[136:137], v[132:135], off
	s_nop 1
	v_sub_f32_e32 v133, v217, v240
	v_sub_f32_e32 v132, v216, v240
	v_sub_f32_e32 v135, v219, v240
	v_sub_f32_e32 v134, v218, v240
	v_pk_mul_f32 v[132:133], v[240:241], v[132:133] op_sel:[1,0]
	v_pk_mul_f32 v[134:135], v[240:241], v[134:135] op_sel:[1,0]
	v_pk_fma_f32 v[132:133], v[150:151], v[132:133], v[64:65]
	v_pk_fma_f32 v[134:135], v[148:149], v[134:135], v[66:67]
	v_pk_fma_f32 v[128:129], v[128:129], s[78:79], v[132:133] op_sel_hi:[1,0,1]
	v_add_u32_e32 v132, 0x58010, v194
	v_mov_b32_e32 v133, v159
	v_pk_fma_f32 v[130:131], v[130:131], s[78:79], v[134:135] op_sel_hi:[1,0,1]
	v_lshl_add_u64 v[132:133], v[132:133], 2, s[90:91]
	global_store_dwordx4 v[132:133], v[128:131], off
	global_load_dwordx4 v[128:131], v[140:141], off offset:512
	v_add_u32_e32 v136, v232, v230
	v_mov_b32_e32 v137, v159
	v_lshl_add_u64 v[136:137], v[136:137], 2, s[88:89]
	s_waitcnt vmcnt(0)
;     template <bool LN, int BJ, int LO, int HI> DI void batch(const f32x4 (&acc)[2][2][4][2], unsigned row0, unsigned col0, const f32x4 (&gv)[2], const f32x4 (&bv)[2]) const {
;         f32x4 r[HI - LO]; float mean[(HI - LO) / 2], rstd[(HI - LO) / 2];
; #pragma unroll
;         for (int i = LO; i < HI; ++i) { const int ai = i >> 3, m = (i >> 1) & 3, n = i & 1; const unsigned row = row0 + ai * HALF + m * 16;
;             if (n == 0) { mean[(i - LO) >> 1] = 0.f; rstd[(i - LO) >> 1] = 1.f;
;                 if (LN) { const float2 st = *(const float2*)(stats + row * 2u); mean[(i - LO) >> 1] = st.x; rstd[(i - LO) >> 1] = st.y; } }
;             r[i - LO] = *(const f32x4*)(src + (row * (unsigned)DM + col0 + BJ * HALF + n * 16)); }
; #pragma unroll
;         for (int i = LO; i < HI; ++i) { const int ai = i >> 3, m = (i >> 1) & 3, n = i & 1; const unsigned row = row0 + ai * HALF + m * 16;
;             *(f32x4*)(Y + (row * (unsigned)DM + col0 + BJ * HALF + n * 16)) = acc[ai][BJ][m][n] + ((r[i - LO] - mean[(i - LO) >> 1]) * rstd[(i - LO) >> 1]) * gv[n] + bv[n]; }
;         __builtin_amdgcn_sched_barrier(0);
;     }
;     template <bool LN, int BJ> DI void load_gb(unsigned col0, f32x4 (&gv)[2], f32x4 (&bv)[2]) const {
; #pragma unroll
;         for (int n = 0; n < 2; ++n) {
;             if (LN) { gv[n] = *(const f32x4*)(gam + col0 + BJ * HALF + n * 16) * ALPHA; bv[n] = *(const f32x4*)(bet + col0 + BJ * HALF + n * 16) * ALPHA; }
	v_pk_mul_f32 v[212:213], v[130:131], s[78:79] op_sel_hi:[1,0]
	v_pk_mul_f32 v[214:215], v[128:129], s[78:79] op_sel_hi:[1,0]
	global_load_dwordx4 v[132:135], v[142:143], off offset:512
	global_load_dwordx4 v[128:131], v[140:141], off offset:576
	s_waitcnt vmcnt(0)
	v_pk_mul_f32 v[206:207], v[130:131], s[78:79] op_sel_hi:[1,0]
	v_pk_mul_f32 v[208:209], v[128:129], s[78:79] op_sel_hi:[1,0]
	global_load_dwordx4 v[128:131], v[142:143], off offset:576
	global_load_dwordx2 v[220:221], v[144:145], off
	global_load_dwordx4 v[240:243], v[136:137], off
	v_add_u32_e32 v136, v232, v229
	v_mov_b32_e32 v137, v159
	v_lshl_add_u64 v[136:137], v[136:137], 2, s[88:89]
	global_load_dwordx4 v[244:247], v[136:137], off
	global_load_dwordx2 v[218:219], v[146:147], off
	v_add_u32_e32 v136, v195, v230
	v_mov_b32_e32 v137, v159
	v_lshl_add_u64 v[136:137], v[136:137], 2, s[88:89]
	global_load_dwordx4 v[248:251], v[136:137], off
	v_add_u32_e32 v136, v195, v229
	v_mov_b32_e32 v137, v159
	v_lshl_add_u64 v[136:137], v[136:137], 2, s[88:89]
	global_load_dwordx4 v[152:155], v[136:137], off
	global_load_dwordx2 v[216:217], v[200:201], off
	v_add_u32_e32 v136, v236, v230
	v_mov_b32_e32 v137, v159
	v_lshl_add_u64 v[136:137], v[136:137], 2, s[88:89]
	global_load_dwordx4 v[148:151], v[136:137], off
	v_add_u32_e32 v136, v236, v229
	v_mov_b32_e32 v137, v159
	v_lshl_add_u64 v[136:137], v[136:137], 2, s[88:89]
	global_load_dwordx4 v[144:147], v[136:137], off
	global_load_dwordx2 v[200:201], v[202:203], off
	v_add_u32_e32 v136, v235, v230
	v_mov_b32_e32 v137, v159
	v_lshl_add_u64 v[136:137], v[136:137], 2, s[88:89]
	global_load_dwordx4 v[140:143], v[136:137], off
	v_add_u32_e32 v136, v235, v229
	v_mov_b32_e32 v137, v159
	v_lshl_add_u64 v[136:137], v[136:137], 2, s[88:89]
	global_load_dwordx4 v[136:139], v[136:137], off
	v_add_u32_e32 v202, 0x80, v194
	v_mov_b32_e32 v203, v159
	v_lshl_add_u64 v[202:203], v[202:203], 2, s[90:91]
	s_waitcnt vmcnt(0)
	v_sub_f32_e32 v241, v241, v220
	v_sub_f32_e32 v240, v240, v220
	v_sub_f32_e32 v243, v243, v220
	v_sub_f32_e32 v242, v242, v220
	v_pk_mul_f32 v[242:243], v[220:221], v[242:243] op_sel:[1,0]
	v_pk_mul_f32 v[240:241], v[220:221], v[240:241] op_sel:[1,0]
	v_pk_fma_f32 v[242:243], v[212:213], v[242:243], v[62:63]
	v_pk_fma_f32 v[240:241], v[214:215], v[240:241], v[60:61]
	v_pk_fma_f32 v[242:243], v[134:135], s[78:79], v[242:243] op_sel_hi:[1,0,1]
	v_pk_fma_f32 v[240:241], v[132:133], s[78:79], v[240:241] op_sel_hi:[1,0,1]
	global_store_dwordx4 v[202:203], v[240:243], off
	v_sub_f32_e32 v203, v245, v220
	v_sub_f32_e32 v202, v244, v220
	v_sub_f32_e32 v241, v247, v220
	v_sub_f32_e32 v240, v246, v220
	v_pk_mul_f32 v[202:203], v[220:221], v[202:203] op_sel:[1,0]
	v_pk_mul_f32 v[240:241], v[220:221], v[240:241] op_sel:[1,0]
	v_pk_fma_f32 v[202:203], v[208:209], v[202:203], v[56:57]
	v_pk_fma_f32 v[220:221], v[206:207], v[240:241], v[58:59]
	v_pk_fma_f32 v[240:241], v[128:129], s[78:79], v[202:203] op_sel_hi:[1,0,1]
	v_add_u32_e32 v202, 0x90, v194
	v_mov_b32_e32 v203, v159
	v_pk_fma_f32 v[242:243], v[130:131], s[78:79], v[220:221] op_sel_hi:[1,0,1]
	v_lshl_add_u64 v[202:203], v[202:203], 2, s[90:91]
	global_store_dwordx4 v[202:203], v[240:243], off
	v_sub_f32_e32 v203, v249, v218
	v_sub_f32_e32 v202, v248, v218
	v_sub_f32_e32 v221, v251, v218
	v_sub_f32_e32 v220, v250, v218
	v_pk_mul_f32 v[202:203], v[218:219], v[202:203] op_sel:[1,0]
	v_pk_mul_f32 v[220:221], v[218:219], v[220:221] op_sel:[1,0]
	v_pk_fma_f32 v[202:203], v[214:215], v[202:203], v[52:53]
	v_pk_fma_f32 v[220:221], v[212:213], v[220:221], v[54:55]
	v_pk_fma_f32 v[240:241], v[132:133], s[78:79], v[202:203] op_sel_hi:[1,0,1]
	v_add_u32_e32 v202, 0x8080, v194
	v_mov_b32_e32 v203, v159
	v_sub_f32_e32 v153, v153, v218
	v_sub_f32_e32 v152, v152, v218
	v_sub_f32_e32 v155, v155, v218
	v_sub_f32_e32 v154, v154, v218
	v_pk_fma_f32 v[242:243], v[134:135], s[78:79], v[220:221] op_sel_hi:[1,0,1]
	v_lshl_add_u64 v[202:203], v[202:203], 2, s[90:91]
	v_pk_mul_f32 v[154:155], v[218:219], v[154:155] op_sel:[1,0]
	v_pk_mul_f32 v[152:153], v[218:219], v[152:153] op_sel:[1,0]
	global_store_dwordx4 v[202:203], v[240:243], off
	v_pk_fma_f32 v[152:153], v[208:209], v[152:153], v[48:49]
	v_pk_fma_f32 v[154:155], v[206:207], v[154:155], v[50:51]
	v_add_u32_e32 v202, 0x8090, v194
	v_mov_b32_e32 v203, v159
	v_sub_f32_e32 v149, v149, v216
	v_sub_f32_e32 v148, v148, v216
	v_sub_f32_e32 v151, v151, v216
	v_sub_f32_e32 v150, v150, v216
	v_pk_fma_f32 v[154:155], v[130:131], s[78:79], v[154:155] op_sel_hi:[1,0,1]
	v_pk_fma_f32 v[152:153], v[128:129], s[78:79], v[152:153] op_sel_hi:[1,0,1]
	v_lshl_add_u64 v[202:203], v[202:203], 2, s[90:91]
	v_pk_mul_f32 v[150:151], v[216:217], v[150:151] op_sel:[1,0]
	v_pk_mul_f32 v[148:149], v[216:217], v[148:149] op_sel:[1,0]
	global_store_dwordx4 v[202:203], v[152:155], off
	v_pk_fma_f32 v[148:149], v[214:215], v[148:149], v[44:45]
	v_pk_fma_f32 v[150:151], v[212:213], v[150:151], v[46:47]
	v_add_u32_e32 v152, 0x10080, v194
	v_mov_b32_e32 v153, v159
	v_sub_f32_e32 v145, v145, v216
	v_sub_f32_e32 v144, v144, v216
	v_sub_f32_e32 v147, v147, v216
	v_sub_f32_e32 v146, v146, v216
	v_pk_fma_f32 v[150:151], v[134:135], s[78:79], v[150:151] op_sel_hi:[1,0,1]
	v_pk_fma_f32 v[148:149], v[132:133], s[78:79], v[148:149] op_sel_hi:[1,0,1]
	v_lshl_add_u64 v[152:153], v[152:153], 2, s[90:91]
	v_pk_mul_f32 v[146:147], v[216:217], v[146:147] op_sel:[1,0]
	v_pk_mul_f32 v[144:145], v[216:217], v[144:145] op_sel:[1,0]
	global_store_dwordx4 v[152:153], v[148:151], off
	v_pk_fma_f32 v[144:145], v[208:209], v[144:145], v[40:41]
	v_pk_fma_f32 v[146:147], v[206:207], v[146:147], v[42:43]
;     template <bool LN, int BJ, int LO, int HI> DI void batch(const f32x4 (&acc)[2][2][4][2], unsigned row0, unsigned col0, const f32x4 (&gv)[2], const f32x4 (&bv)[2]) const {
;         f32x4 r[HI - LO]; float mean[(HI - LO) / 2], rstd[(HI - LO) / 2];
; #pragma unroll
;         for (int i = LO; i < HI; ++i) { const int ai = i >> 3, m = (i >> 1) & 3, n = i & 1; const unsigned row = row0 + ai * HALF + m * 16;
;             if (n == 0) { mean[(i - LO) >> 1] = 0.f; rstd[(i - LO) >> 1] = 1.f;
;                 if (LN) { const float2 st = *(const float2*)(stats + row * 2u); mean[(i - LO) >> 1] = st.x; rstd[(i - LO) >> 1] = st.y; } }
;             r[i - LO] = *(const f32x4*)(src + (row * (unsigned)DM + col0 + BJ * HALF + n * 16)); }
; #pragma unroll
;         for (int i = LO; i < HI; ++i) { const int ai = i >> 3, m = (i >> 1) & 3, n = i & 1; const unsigned row = row0 + ai * HALF + m * 16;
;             *(f32x4*)(Y + (row * (unsigned)DM + col0 + BJ * HALF + n * 16)) = acc[ai][BJ][m][n] + ((r[i - LO] - mean[(i - LO) >> 1]) * rstd[(i - LO) >> 1]) * gv[n] + bv[n]; }
	v_add_u32_e32 v148, 0x10090, v194
	v_mov_b32_e32 v149, v159
	v_sub_f32_e32 v141, v141, v200
	v_sub_f32_e32 v140, v140, v200
	v_sub_f32_e32 v143, v143, v200
	v_sub_f32_e32 v142, v142, v200
	v_pk_fma_f32 v[146:147], v[130:131], s[78:79], v[146:147] op_sel_hi:[1,0,1]
	v_pk_fma_f32 v[144:145], v[128:129], s[78:79], v[144:145] op_sel_hi:[1,0,1]
	v_lshl_add_u64 v[148:149], v[148:149], 2, s[90:91]
	v_pk_mul_f32 v[142:143], v[200:201], v[142:143] op_sel:[1,0]
	v_pk_mul_f32 v[140:141], v[200:201], v[140:141] op_sel:[1,0]
	global_store_dwordx4 v[148:149], v[144:147], off
	v_pk_fma_f32 v[140:141], v[214:215], v[140:141], v[36:37]
	v_pk_fma_f32 v[142:143], v[212:213], v[142:143], v[38:39]
	v_add_u32_e32 v144, 0x18080, v194
	v_mov_b32_e32 v145, v159
	v_sub_f32_e32 v137, v137, v200
	v_sub_f32_e32 v136, v136, v200
	v_sub_f32_e32 v139, v139, v200
	v_sub_f32_e32 v138, v138, v200
	v_pk_fma_f32 v[142:143], v[134:135], s[78:79], v[142:143] op_sel_hi:[1,0,1]
	v_pk_fma_f32 v[140:141], v[132:133], s[78:79], v[140:141] op_sel_hi:[1,0,1]
	v_lshl_add_u64 v[144:145], v[144:145], 2, s[90:91]
	v_pk_mul_f32 v[138:139], v[200:201], v[138:139] op_sel:[1,0]
	v_pk_mul_f32 v[136:137], v[200:201], v[136:137] op_sel:[1,0]
	global_store_dwordx4 v[144:145], v[140:143], off
	v_pk_fma_f32 v[136:137], v[208:209], v[136:137], v[32:33]
	v_pk_fma_f32 v[138:139], v[206:207], v[138:139], v[34:35]
	v_add_u32_e32 v140, 0x18090, v194
	v_mov_b32_e32 v141, v159
	v_pk_fma_f32 v[138:139], v[130:131], s[78:79], v[138:139] op_sel_hi:[1,0,1]
	v_pk_fma_f32 v[136:137], v[128:129], s[78:79], v[136:137] op_sel_hi:[1,0,1]
	v_lshl_add_u64 v[140:141], v[140:141], 2, s[90:91]
	global_store_dwordx4 v[140:141], v[136:139], off
	s_nop 1
	v_add_u32_e32 v136, v233, v230
	v_mov_b32_e32 v137, v159
	v_lshl_add_u64 v[136:137], v[136:137], 2, s[88:89]
	global_load_dwordx2 v[220:221], v[196:197], off
	global_load_dwordx4 v[216:219], v[136:137], off
	v_add_u32_e32 v136, v233, v229
	v_mov_b32_e32 v137, v159
	v_lshl_add_u64 v[136:137], v[136:137], 2, s[88:89]
	global_load_dwordx4 v[240:243], v[136:137], off
	global_load_dwordx2 v[200:201], v[198:199], off
	v_add_u32_e32 v136, v234, v230
	v_mov_b32_e32 v137, v159
	v_lshl_add_u64 v[136:137], v[136:137], 2, s[88:89]
	global_load_dwordx4 v[244:247], v[136:137], off
	v_add_u32_e32 v136, v234, v229
	v_mov_b32_e32 v137, v159
	v_lshl_add_u64 v[136:137], v[136:137], 2, s[88:89]
	global_load_dwordx4 v[152:155], v[136:137], off
	global_load_dwordx2 v[198:199], v[204:205], off
	v_add_u32_e32 v136, v237, v230
	v_mov_b32_e32 v137, v159
	v_lshl_add_u64 v[136:137], v[136:137], 2, s[88:89]
	global_load_dwordx4 v[148:151], v[136:137], off
	v_add_u32_e32 v136, v237, v229
	v_mov_b32_e32 v137, v159
	v_lshl_add_u64 v[136:137], v[136:137], 2, s[88:89]
	global_load_dwordx4 v[144:147], v[136:137], off
	global_load_dwordx2 v[196:197], v[210:211], off
	v_add_u32_e32 v136, v238, v230
	v_mov_b32_e32 v137, v159
	v_lshl_add_u64 v[136:137], v[136:137], 2, s[88:89]
	global_load_dwordx4 v[140:143], v[136:137], off
	v_add_u32_e32 v136, v238, v229
	v_mov_b32_e32 v137, v159
	v_lshl_add_u64 v[136:137], v[136:137], 2, s[88:89]
	global_load_dwordx4 v[136:139], v[136:137], off
	v_add_u32_e32 v210, 0x40080, v194
	v_mov_b32_e32 v211, v159
	v_lshl_add_u64 v[210:211], v[210:211], 2, s[90:91]
	s_waitcnt vmcnt(0)
;     template <bool LN, int BJ, int LO, int HI> DI void batch(const f32x4 (&acc)[2][2][4][2], unsigned row0, unsigned col0, const f32x4 (&gv)[2], const f32x4 (&bv)[2]) const {
;         f32x4 r[HI - LO]; float mean[(HI - LO) / 2], rstd[(HI - LO) / 2];
; #pragma unroll
;         for (int i = LO; i < HI; ++i) { const int ai = i >> 3, m = (i >> 1) & 3, n = i & 1; const unsigned row = row0 + ai * HALF + m * 16;
;             if (n == 0) { mean[(i - LO) >> 1] = 0.f; rstd[(i - LO) >> 1] = 1.f;
;                 if (LN) { const float2 st = *(const float2*)(stats + row * 2u); mean[(i - LO) >> 1] = st.x; rstd[(i - LO) >> 1] = st.y; } }
;             r[i - LO] = *(const f32x4*)(src + (row * (unsigned)DM + col0 + BJ * HALF + n * 16)); }
; #pragma unroll
;         for (int i = LO; i < HI; ++i) { const int ai = i >> 3, m = (i >> 1) & 3, n = i & 1; const unsigned row = row0 + ai * HALF + m * 16;
;             *(f32x4*)(Y + (row * (unsigned)DM + col0 + BJ * HALF + n * 16)) = acc[ai][BJ][m][n] + ((r[i - LO] - mean[(i - LO) >> 1]) * rstd[(i - LO) >> 1]) * gv[n] + bv[n]; }
	v_sub_f32_e32 v203, v217, v220
	v_sub_f32_e32 v202, v216, v220
	v_sub_f32_e32 v205, v219, v220
	v_sub_f32_e32 v204, v218, v220
	v_pk_mul_f32 v[204:205], v[220:221], v[204:205] op_sel:[1,0]
	v_pk_mul_f32 v[202:203], v[220:221], v[202:203] op_sel:[1,0]
	v_pk_fma_f32 v[204:205], v[212:213], v[204:205], v[30:31]
	v_pk_fma_f32 v[202:203], v[214:215], v[202:203], v[28:29]
	v_pk_fma_f32 v[204:205], v[134:135], s[78:79], v[204:205] op_sel_hi:[1,0,1]
	v_pk_fma_f32 v[202:203], v[132:133], s[78:79], v[202:203] op_sel_hi:[1,0,1]
	global_store_dwordx4 v[210:211], v[202:205], off
	v_add_u32_e32 v210, 0x40090, v194
	v_mov_b32_e32 v211, v159
	v_sub_f32_e32 v203, v241, v220
	v_sub_f32_e32 v202, v240, v220
	v_sub_f32_e32 v205, v243, v220
	v_sub_f32_e32 v204, v242, v220
	v_pk_mul_f32 v[204:205], v[220:221], v[204:205] op_sel:[1,0]
	v_pk_mul_f32 v[202:203], v[220:221], v[202:203] op_sel:[1,0]
	v_pk_fma_f32 v[204:205], v[206:207], v[204:205], v[26:27]
	v_pk_fma_f32 v[202:203], v[208:209], v[202:203], v[24:25]
	v_pk_fma_f32 v[204:205], v[130:131], s[78:79], v[204:205] op_sel_hi:[1,0,1]
	v_pk_fma_f32 v[202:203], v[128:129], s[78:79], v[202:203] op_sel_hi:[1,0,1]
	v_lshl_add_u64 v[210:211], v[210:211], 2, s[90:91]
	global_store_dwordx4 v[210:211], v[202:205], off
	v_sub_f32_e32 v149, v149, v198
	v_sub_f32_e32 v148, v148, v198
	v_sub_f32_e32 v203, v245, v200
	v_sub_f32_e32 v202, v244, v200
	v_sub_f32_e32 v141, v141, v196
	v_sub_f32_e32 v140, v140, v196
	v_sub_f32_e32 v205, v247, v200
	v_sub_f32_e32 v204, v246, v200
	v_pk_mul_f32 v[202:203], v[200:201], v[202:203] op_sel:[1,0]
	v_sub_f32_e32 v151, v151, v198
	v_sub_f32_e32 v150, v150, v198
	v_pk_mul_f32 v[148:149], v[198:199], v[148:149] op_sel:[1,0]
	v_sub_f32_e32 v143, v143, v196
	v_sub_f32_e32 v142, v142, v196
	v_pk_mul_f32 v[140:141], v[196:197], v[140:141] op_sel:[1,0]
	v_pk_mul_f32 v[204:205], v[200:201], v[204:205] op_sel:[1,0]
	v_pk_fma_f32 v[202:203], v[214:215], v[202:203], v[20:21]
	v_sub_f32_e32 v153, v153, v200
	v_sub_f32_e32 v152, v152, v200
	v_sub_f32_e32 v155, v155, v200
	v_sub_f32_e32 v154, v154, v200
	v_pk_mul_f32 v[150:151], v[198:199], v[150:151] op_sel:[1,0]
	v_pk_fma_f32 v[148:149], v[214:215], v[148:149], v[12:13]
	v_pk_mul_f32 v[142:143], v[196:197], v[142:143] op_sel:[1,0]
	v_pk_fma_f32 v[140:141], v[214:215], v[140:141], v[4:5]
	v_pk_fma_f32 v[204:205], v[212:213], v[204:205], v[22:23]
	v_pk_fma_f32 v[202:203], v[132:133], s[78:79], v[202:203] op_sel_hi:[1,0,1]
	v_pk_mul_f32 v[154:155], v[200:201], v[154:155] op_sel:[1,0]
	v_pk_mul_f32 v[152:153], v[200:201], v[152:153] op_sel:[1,0]
	v_pk_fma_f32 v[150:151], v[212:213], v[150:151], v[14:15]
	v_pk_fma_f32 v[148:149], v[132:133], s[78:79], v[148:149] op_sel_hi:[1,0,1]
	v_pk_fma_f32 v[142:143], v[212:213], v[142:143], v[6:7]
	v_pk_fma_f32 v[132:133], v[132:133], s[78:79], v[140:141] op_sel_hi:[1,0,1]
	v_add_u32_e32 v140, 0x58080, v194
	v_mov_b32_e32 v141, v159
	v_pk_fma_f32 v[204:205], v[134:135], s[78:79], v[204:205] op_sel_hi:[1,0,1]
	v_pk_fma_f32 v[152:153], v[208:209], v[152:153], v[16:17]
	v_pk_fma_f32 v[154:155], v[206:207], v[154:155], v[18:19]
	v_add_u32_e32 v200, 0x48090, v194
	v_mov_b32_e32 v201, v159
	v_pk_fma_f32 v[150:151], v[134:135], s[78:79], v[150:151] op_sel_hi:[1,0,1]
	v_pk_fma_f32 v[134:135], v[134:135], s[78:79], v[142:143] op_sel_hi:[1,0,1]
	v_lshl_add_u64 v[140:141], v[140:141], 2, s[90:91]
	v_pk_fma_f32 v[154:155], v[130:131], s[78:79], v[154:155] op_sel_hi:[1,0,1]
	v_pk_fma_f32 v[152:153], v[128:129], s[78:79], v[152:153] op_sel_hi:[1,0,1]
	v_lshl_add_u64 v[200:201], v[200:201], 2, s[90:91]
	v_sub_f32_e32 v145, v145, v198
	v_sub_f32_e32 v144, v144, v198
	global_store_dwordx4 v[140:141], v[132:135], off
	global_store_dwordx4 v[200:201], v[152:155], off
	v_sub_f32_e32 v147, v147, v198
	v_sub_f32_e32 v133, v137, v196
	v_sub_f32_e32 v132, v136, v196
	v_add_u32_e32 v152, 0x50080, v194
	v_mov_b32_e32 v153, v159
	v_sub_f32_e32 v146, v146, v198
	v_pk_mul_f32 v[144:145], v[198:199], v[144:145] op_sel:[1,0]
	v_sub_f32_e32 v135, v139, v196
	v_sub_f32_e32 v134, v138, v196
	v_pk_mul_f32 v[132:133], v[196:197], v[132:133] op_sel:[1,0]
	v_lshl_add_u64 v[152:153], v[152:153], 2, s[90:91]
	v_pk_mul_f32 v[146:147], v[198:199], v[146:147] op_sel:[1,0]
	v_pk_fma_f32 v[144:145], v[208:209], v[144:145], v[8:9]
	v_pk_mul_f32 v[134:135], v[196:197], v[134:135] op_sel:[1,0]
	v_pk_fma_f32 v[132:133], v[208:209], v[132:133], v[0:1]
	v_add_u32_e32 v210, 0x48080, v194
	v_mov_b32_e32 v211, v159
	global_store_dwordx4 v[152:153], v[148:151], off
	v_pk_fma_f32 v[146:147], v[206:207], v[146:147], v[10:11]
	v_pk_fma_f32 v[144:145], v[128:129], s[78:79], v[144:145] op_sel_hi:[1,0,1]
	v_add_u32_e32 v148, 0x50090, v194
	v_mov_b32_e32 v149, v159
	v_pk_fma_f32 v[134:135], v[206:207], v[134:135], v[2:3]
	v_pk_fma_f32 v[128:129], v[128:129], s[78:79], v[132:133] op_sel_hi:[1,0,1]
	v_add_u32_e32 v132, 0x58090, v194
	v_mov_b32_e32 v133, v159
	v_lshl_add_u64 v[210:211], v[210:211], 2, s[90:91]
	v_pk_fma_f32 v[146:147], v[130:131], s[78:79], v[146:147] op_sel_hi:[1,0,1]
	v_lshl_add_u64 v[148:149], v[148:149], 2, s[90:91]
	v_pk_fma_f32 v[130:131], v[130:131], s[78:79], v[134:135] op_sel_hi:[1,0,1]
	v_lshl_add_u64 v[132:133], v[132:133], 2, s[90:91]
	global_store_dwordx4 v[210:211], v[202:205], off
	global_store_dwordx4 v[148:149], v[144:147], off
	global_store_dwordx4 v[132:133], v[128:131], off
	s_mov_b64 s[20:21], 0
	s_branch .LBB0_81

; #define PG8_STAGE(bufoff, gbase) do { _Pragma("unroll") for (int _i = 0; _i < 2; ++_i) \
;         __builtin_amdgcn_global_load_lds((const unsigned*)((const char*)(gbase) + voff[_i]), (LAS unsigned*)(lds + (bufoff) + ldsw + _i * 8192), 16, 0, 0); } while (0)
; #define PG8_LDA(dst, b, h) do { _Pragma("unroll") for (int m = 0; m < 4; ++m) _Pragma("unroll") for (int k = 0; k < 2; ++k) dst[m][k] = *(const LAS bf16x8*)(lds + PG8_SA(b, h) + aoff + m * 2048 + k * 1024); } while (0)
; #define PG8_LDB(dst, b, h) do { _Pragma("unroll") for (int n = 0; n < 2; ++n) _Pragma("unroll") for (int k = 0; k < 2; ++k) dst[n][k] = *(const LAS bf16x8*)(lds + PG8_SB(b, h) + boff + n * 2048 + k * 1024); } while (0)
; #define PG8_MMA(ai, bj, At, Bt) do { __builtin_amdgcn_s_setprio(1); _Pragma("unroll") for (int m = 0; m < 4; ++m) _Pragma("unroll") for (int n = 0; n < 2; ++n) _Pragma("unroll") for (int k = 0; k < 2; ++k) \
;         acc[ai][bj][m][n] = __builtin_amdgcn_mfma_f32_16x16x32_bf16(Bt[n][k], At[m][k], acc[ai][bj][m][n], 0, 0, 0); __builtin_amdgcn_s_setprio(0); } while (0)
; #define PG8_WAIT_V(n) asm volatile("s_waitcnt vmcnt(" #n ")" ::: "memory")
; #define PG8_WAIT_L(n) asm volatile("s_waitcnt lgkmcnt(" #n ")" ::: "memory")
; #define PG8_BAR __builtin_amdgcn_s_barrier()
; #define PG8_SCHED __builtin_amdgcn_sched_barrier(0)
; template <class Epi>
; DI void gemm_phase(LAS unsigned char* lds, const Gemm g, const StaticOrder& S, const Epi& E) {
;     ...
;         for (int t = 0; t < nt; t += 2) {
;             const bool last = (t == nt - 2);
;             const char* a1 = cA + (size_t)(t + 1) * kstep;
;             const char* a2 = last ? nA : cA + (size_t)(t + 2) * kstep; const char* b2 = last ? nB : cB + (size_t)(t + 2) * kstep;
;             const char* a3 = a2 + kstep; const char* b3 = b2 + kstep;
;             PG8_LDB(B0, 0, 0); PG8_SCHED; PG8_LDA(At, 0, 0); PG8_STAGE(PG8_SA(1, 1), a1 + hstep);
;             PG8_WAIT_L(8); PG8_BAR; PG8_WAIT_L(0); PG8_MMA(0, 0, At, B0); PG8_BAR; PG8_SCHED;
;             PG8_LDB(B1, 0, 1); PG8_STAGE(PG8_SB(0, 0), b2);
;             PG8_BAR; PG8_WAIT_L(0); PG8_MMA(0, 1, At, B1); PG8_BAR;
;             PG8_LDA(At, 0, 1); PG8_STAGE(PG8_SA(0, 0), a2);
;             PG8_BAR; PG8_WAIT_L(0); PG8_MMA(1, 0, At, B0); PG8_BAR; PG8_SCHED;
;             PG8_STAGE(PG8_SB(0, 1), b2 + hstep);
;             PG8_WAIT_V(6); PG8_BAR; PG8_MMA(1, 1, At, B1); PG8_BAR;
.LBB0_134:
	s_add_u32 s18, s16, 0x100
	s_addc_u32 s19, s17, 0
	s_add_i32 s39, 0, 0x10000
	v_add_u32_e32 v148, s39, v199
	ds_read_b128 v[96:99], v148
	ds_read_b128 v[100:103], v148 offset:1024
	ds_read_b128 v[136:139], v148 offset:2048
	ds_read_b128 v[148:151], v148 offset:3072
	s_cmpk_eq_i32 s33, 0x54
	s_cselect_b32 s23, s9, s19
	s_cselect_b32 s22, s8, s18
	s_cselect_b32 s21, s11, s5
	s_cselect_b32 s20, s10, s4
	v_lshl_add_u64 v[218:219], s[16:17], 0, v[144:145]
	s_add_i32 m0, s28, 0xc000
	ds_read_b128 v[152:155], v201
	ds_read_b128 v[186:189], v201 offset:1024
	ds_read_b128 v[190:193], v201 offset:2048
	ds_read_b128 v[194:197], v201 offset:3072
	ds_read_b128 v[202:205], v201 offset:4096
	ds_read_b128 v[206:209], v201 offset:5120
	ds_read_b128 v[210:213], v201 offset:6144
	ds_read_b128 v[214:217], v201 offset:7168
	global_load_lds_dwordx4 v[218:219], off
	v_lshl_add_u64 v[218:219], s[16:17], 0, v[146:147]
	s_add_i32 m0, s28, 0xe000
	s_nop 0
	global_load_lds_dwordx4 v[218:219], off
	s_waitcnt lgkmcnt(8)
	s_setprio 1
	s_barrier
	s_waitcnt lgkmcnt(0)
	v_mfma_f32_16x16x32_bf16 v[132:135], v[96:99], v[152:155], v[132:135]
	v_mfma_f32_16x16x32_bf16 v[128:131], v[136:139], v[152:155], v[128:131]
	v_mfma_f32_16x16x32_bf16 v[124:127], v[96:99], v[190:193], v[124:127]
	v_mfma_f32_16x16x32_bf16 v[120:123], v[136:139], v[190:193], v[120:123]
	v_mfma_f32_16x16x32_bf16 v[116:119], v[96:99], v[202:205], v[116:119]
	v_mfma_f32_16x16x32_bf16 v[112:115], v[136:139], v[202:205], v[112:115]
	v_mfma_f32_16x16x32_bf16 v[108:111], v[96:99], v[210:213], v[108:111]
	v_mfma_f32_16x16x32_bf16 v[104:107], v[136:139], v[210:213], v[104:107]
	v_mfma_f32_16x16x32_bf16 v[132:135], v[100:103], v[186:189], v[132:135]
	v_mfma_f32_16x16x32_bf16 v[128:131], v[148:151], v[186:189], v[128:131]
	v_mfma_f32_16x16x32_bf16 v[124:127], v[100:103], v[194:197], v[124:127]
	v_mfma_f32_16x16x32_bf16 v[120:123], v[148:151], v[194:197], v[120:123]
	v_mfma_f32_16x16x32_bf16 v[116:119], v[100:103], v[206:209], v[116:119]
	v_mfma_f32_16x16x32_bf16 v[112:115], v[148:151], v[206:209], v[112:115]
	v_mfma_f32_16x16x32_bf16 v[108:111], v[100:103], v[214:217], v[108:111]
	v_mfma_f32_16x16x32_bf16 v[104:107], v[148:151], v[214:217], v[104:107]
	s_setprio 0
	s_barrier
	s_add_i32 s40, 0, 0x14000
	s_add_i32 s16, s39, s27
	v_add_u32_e32 v158, s40, v199
	v_lshl_add_u64 v[218:219], s[20:21], 0, v[142:143]
	s_mov_b32 m0, s16
	ds_read_b128 v[226:229], v158
	ds_read_b128 v[230:233], v158 offset:1024
	ds_read_b128 v[234:237], v158 offset:2048
	ds_read_b128 v[238:241], v158 offset:3072
	global_load_lds_dwordx4 v[218:219], off
	v_lshl_add_u64 v[220:221], s[20:21], 0, v[140:141]
	s_add_i32 m0, s16, 0x2000
	s_nop 0
	global_load_lds_dwordx4 v[220:221], off
	s_waitcnt lgkmcnt(0)
	s_setprio 1
	s_barrier
	v_mfma_f32_16x16x32_bf16 v[60:63], v[226:229], v[152:155], v[60:63]
	v_mfma_f32_16x16x32_bf16 v[56:59], v[234:237], v[152:155], v[56:59]
	v_mfma_f32_16x16x32_bf16 v[52:55], v[226:229], v[190:193], v[52:55]
	v_mfma_f32_16x16x32_bf16 v[48:51], v[234:237], v[190:193], v[48:51]
	v_mfma_f32_16x16x32_bf16 v[44:47], v[226:229], v[202:205], v[44:47]
	v_mfma_f32_16x16x32_bf16 v[40:43], v[234:237], v[202:205], v[40:43]
	v_mfma_f32_16x16x32_bf16 v[36:39], v[226:229], v[210:213], v[36:39]
	v_mfma_f32_16x16x32_bf16 v[32:35], v[234:237], v[210:213], v[32:35]
	v_mfma_f32_16x16x32_bf16 v[60:63], v[230:233], v[186:189], v[60:63]
	s_mov_b32 m0, s28
	v_mfma_f32_16x16x32_bf16 v[56:59], v[238:241], v[186:189], v[56:59]
	v_lshl_add_u64 v[242:243], s[22:23], 0, v[142:143]
	v_mfma_f32_16x16x32_bf16 v[52:55], v[230:233], v[194:197], v[52:55]
	v_mfma_f32_16x16x32_bf16 v[48:51], v[238:241], v[194:197], v[48:51]
	v_mfma_f32_16x16x32_bf16 v[44:47], v[230:233], v[206:209], v[44:47]
	v_mfma_f32_16x16x32_bf16 v[40:43], v[238:241], v[206:209], v[40:43]
	v_mfma_f32_16x16x32_bf16 v[36:39], v[230:233], v[214:217], v[36:39]
	v_mfma_f32_16x16x32_bf16 v[32:35], v[238:241], v[214:217], v[32:35]
	s_setprio 0
	s_barrier
	ds_read_b128 v[152:155], v201 offset:16384
	ds_read_b128 v[186:189], v201 offset:17408
	ds_read_b128 v[190:193], v201 offset:18432
	ds_read_b128 v[194:197], v201 offset:19456
	ds_read_b128 v[202:205], v201 offset:20480
	ds_read_b128 v[206:209], v201 offset:21504
	ds_read_b128 v[210:213], v201 offset:22528
	ds_read_b128 v[214:217], v201 offset:23552
	global_load_lds_dwordx4 v[242:243], off
	v_lshl_add_u64 v[244:245], s[22:23], 0, v[140:141]
	s_mov_b32 m0, s29
	s_nop 0
	global_load_lds_dwordx4 v[244:245], off
	s_waitcnt lgkmcnt(0)
	s_setprio 1
	s_barrier
	v_mfma_f32_16x16x32_bf16 v[92:95], v[96:99], v[152:155], v[92:95]
	v_mfma_f32_16x16x32_bf16 v[88:91], v[136:139], v[152:155], v[88:91]
	v_mfma_f32_16x16x32_bf16 v[84:87], v[96:99], v[190:193], v[84:87]
	v_mfma_f32_16x16x32_bf16 v[80:83], v[136:139], v[190:193], v[80:83]
	v_mfma_f32_16x16x32_bf16 v[76:79], v[96:99], v[202:205], v[76:79]
	v_mfma_f32_16x16x32_bf16 v[72:75], v[136:139], v[202:205], v[72:75]
	v_mfma_f32_16x16x32_bf16 v[68:71], v[96:99], v[210:213], v[68:71]
	v_mfma_f32_16x16x32_bf16 v[64:67], v[136:139], v[210:213], v[64:67]
	v_mfma_f32_16x16x32_bf16 v[92:95], v[100:103], v[186:189], v[92:95]
	v_mfma_f32_16x16x32_bf16 v[88:91], v[148:151], v[186:189], v[88:91]
	v_mfma_f32_16x16x32_bf16 v[84:87], v[100:103], v[194:197], v[84:87]
	v_mfma_f32_16x16x32_bf16 v[80:83], v[148:151], v[194:197], v[80:83]
	v_mfma_f32_16x16x32_bf16 v[76:79], v[100:103], v[206:209], v[76:79]
	v_mfma_f32_16x16x32_bf16 v[72:75], v[148:151], v[206:209], v[72:75]
	v_mfma_f32_16x16x32_bf16 v[68:71], v[100:103], v[214:217], v[68:71]
	v_mfma_f32_16x16x32_bf16 v[64:67], v[148:151], v[214:217], v[64:67]
	s_setprio 0
	s_barrier
; #define PG8_STAGE(bufoff, gbase) do { _Pragma("unroll") for (int _i = 0; _i < 2; ++_i) \
;         __builtin_amdgcn_global_load_lds((const unsigned*)((const char*)(gbase) + voff[_i]), (LAS unsigned*)(lds + (bufoff) + ldsw + _i * 8192), 16, 0, 0); } while (0)
; #define PG8_LDA(dst, b, h) do { _Pragma("unroll") for (int m = 0; m < 4; ++m) _Pragma("unroll") for (int k = 0; k < 2; ++k) dst[m][k] = *(const LAS bf16x8*)(lds + PG8_SA(b, h) + aoff + m * 2048 + k * 1024); } while (0)
; #define PG8_LDB(dst, b, h) do { _Pragma("unroll") for (int n = 0; n < 2; ++n) _Pragma("unroll") for (int k = 0; k < 2; ++k) dst[n][k] = *(const LAS bf16x8*)(lds + PG8_SB(b, h) + boff + n * 2048 + k * 1024); } while (0)
; #define PG8_MMA(ai, bj, At, Bt) do { __builtin_amdgcn_s_setprio(1); _Pragma("unroll") for (int m = 0; m < 4; ++m) _Pragma("unroll") for (int n = 0; n < 2; ++n) _Pragma("unroll") for (int k = 0; k < 2; ++k) \
;         acc[ai][bj][m][n] = __builtin_amdgcn_mfma_f32_16x16x32_bf16(Bt[n][k], At[m][k], acc[ai][bj][m][n], 0, 0, 0); __builtin_amdgcn_s_setprio(0); } while (0)
; #define PG8_WAIT_V(n) asm volatile("s_waitcnt vmcnt(" #n ")" ::: "memory")
; #define PG8_WAIT_L(n) asm volatile("s_waitcnt lgkmcnt(" #n ")" ::: "memory")
; #define PG8_BAR __builtin_amdgcn_s_barrier()
; #define PG8_SCHED __builtin_amdgcn_sched_barrier(0)
; template <class Epi>
; DI void gemm_phase(LAS unsigned char* lds, const Gemm g, const StaticOrder& S, const Epi& E) {
;     ...
;             PG8_STAGE(PG8_SB(0, 1), b2 + hstep);
;             PG8_WAIT_V(6); PG8_BAR; PG8_MMA(1, 1, At, B1); PG8_BAR;
;             PG8_LDB(B0, 1, 0); PG8_SCHED; PG8_LDA(At, 1, 0); PG8_STAGE(PG8_SA(0, 1), a2 + hstep);
;             PG8_WAIT_L(8); PG8_BAR; PG8_WAIT_L(0); PG8_MMA(0, 0, At, B0); PG8_BAR; PG8_SCHED;
;             PG8_LDB(B1, 1, 1); PG8_STAGE(PG8_SB(1, 0), b3);
;             PG8_BAR; PG8_WAIT_L(0); PG8_MMA(0, 1, At, B1); PG8_BAR;
;             PG8_LDA(At, 1, 1); PG8_STAGE(PG8_SA(1, 0), a3);
	s_add_u32 s16, s20, 0x160000
	s_addc_u32 s17, s21, 0
	s_add_i32 s39, s40, s27
	v_lshl_add_u64 v[96:97], s[16:17], 0, v[142:143]
	s_mov_b32 m0, s39
	s_nop 0
	global_load_lds_dwordx4 v[96:97], off
	v_lshl_add_u64 v[96:97], s[16:17], 0, v[140:141]
	s_add_i32 m0, s39, 0x2000
	s_nop 0
	global_load_lds_dwordx4 v[96:97], off
	s_waitcnt vmcnt(6)
	s_setprio 1
	s_barrier
	v_mfma_f32_16x16x32_bf16 v[28:31], v[226:229], v[152:155], v[28:31]
	v_mfma_f32_16x16x32_bf16 v[24:27], v[234:237], v[152:155], v[24:27]
	v_mfma_f32_16x16x32_bf16 v[20:23], v[226:229], v[190:193], v[20:23]
	v_mfma_f32_16x16x32_bf16 v[16:19], v[234:237], v[190:193], v[16:19]
	v_mfma_f32_16x16x32_bf16 v[12:15], v[226:229], v[202:205], v[12:15]
	v_mfma_f32_16x16x32_bf16 v[8:11], v[234:237], v[202:205], v[8:11]
	v_mfma_f32_16x16x32_bf16 v[4:7], v[226:229], v[210:213], v[4:7]
	v_mfma_f32_16x16x32_bf16 v[0:3], v[234:237], v[210:213], v[0:3]
	v_mfma_f32_16x16x32_bf16 v[28:31], v[230:233], v[186:189], v[28:31]
	s_add_i32 s39, 0, 0x18000
	v_mfma_f32_16x16x32_bf16 v[24:27], v[238:241], v[186:189], v[24:27]
	v_add_u32_e32 v148, s39, v199
	v_mfma_f32_16x16x32_bf16 v[20:23], v[230:233], v[194:197], v[20:23]
	v_mfma_f32_16x16x32_bf16 v[16:19], v[238:241], v[194:197], v[16:19]
	v_mfma_f32_16x16x32_bf16 v[12:15], v[230:233], v[206:209], v[12:15]
	v_mfma_f32_16x16x32_bf16 v[8:11], v[238:241], v[206:209], v[8:11]
	v_mfma_f32_16x16x32_bf16 v[4:7], v[230:233], v[214:217], v[4:7]
	v_mfma_f32_16x16x32_bf16 v[0:3], v[238:241], v[214:217], v[0:3]
	s_setprio 0
	s_barrier
	ds_read_b128 v[96:99], v148
	ds_read_b128 v[100:103], v148 offset:1024
	ds_read_b128 v[136:139], v148 offset:2048
	ds_read_b128 v[148:151], v148 offset:3072
	s_add_u32 s16, s22, 0x160000
	s_addc_u32 s17, s23, 0
	s_mov_b32 m0, s30
	v_lshl_add_u64 v[226:227], s[16:17], 0, v[142:143]
	ds_read_b128 v[152:155], v201 offset:32768
	ds_read_b128 v[186:189], v201 offset:33792
	ds_read_b128 v[190:193], v201 offset:34816
	ds_read_b128 v[194:197], v201 offset:35840
	ds_read_b128 v[202:205], v201 offset:36864
	ds_read_b128 v[206:209], v201 offset:37888
	ds_read_b128 v[210:213], v201 offset:38912
	ds_read_b128 v[214:217], v201 offset:39936
	global_load_lds_dwordx4 v[226:227], off
	v_lshl_add_u64 v[226:227], s[16:17], 0, v[140:141]
	s_mov_b32 m0, s31
	s_nop 0
	global_load_lds_dwordx4 v[226:227], off
	s_waitcnt lgkmcnt(8)
	s_setprio 1
	s_barrier
	s_waitcnt lgkmcnt(0)
	v_mfma_f32_16x16x32_bf16 v[132:135], v[96:99], v[152:155], v[132:135]
	v_mfma_f32_16x16x32_bf16 v[128:131], v[136:139], v[152:155], v[128:131]
	v_mfma_f32_16x16x32_bf16 v[124:127], v[96:99], v[190:193], v[124:127]
	v_mfma_f32_16x16x32_bf16 v[120:123], v[136:139], v[190:193], v[120:123]
	v_mfma_f32_16x16x32_bf16 v[116:119], v[96:99], v[202:205], v[116:119]
	v_mfma_f32_16x16x32_bf16 v[112:115], v[136:139], v[202:205], v[112:115]
	v_mfma_f32_16x16x32_bf16 v[108:111], v[96:99], v[210:213], v[108:111]
	v_mfma_f32_16x16x32_bf16 v[104:107], v[136:139], v[210:213], v[104:107]
	v_mfma_f32_16x16x32_bf16 v[132:135], v[100:103], v[186:189], v[132:135]
	v_mfma_f32_16x16x32_bf16 v[128:131], v[148:151], v[186:189], v[128:131]
	v_mfma_f32_16x16x32_bf16 v[124:127], v[100:103], v[194:197], v[124:127]
	v_mfma_f32_16x16x32_bf16 v[120:123], v[148:151], v[194:197], v[120:123]
	v_mfma_f32_16x16x32_bf16 v[116:119], v[100:103], v[206:209], v[116:119]
	v_mfma_f32_16x16x32_bf16 v[112:115], v[148:151], v[206:209], v[112:115]
	v_mfma_f32_16x16x32_bf16 v[108:111], v[100:103], v[214:217], v[108:111]
	v_mfma_f32_16x16x32_bf16 v[104:107], v[148:151], v[214:217], v[104:107]
	s_setprio 0
	s_barrier
	s_add_i32 s22, 0, 0x1c000
	s_add_i32 s16, s39, s27
	v_add_u32_e32 v158, s22, v199
	v_lshl_add_u64 v[218:219], v[218:219], 0, s[94:95]
	s_mov_b32 m0, s16
	ds_read_b128 v[226:229], v158
	ds_read_b128 v[230:233], v158 offset:1024
	ds_read_b128 v[234:237], v158 offset:2048
	ds_read_b128 v[238:241], v158 offset:3072
	global_load_lds_dwordx4 v[218:219], off
	v_lshl_add_u64 v[218:219], v[220:221], 0, s[94:95]
	s_add_i32 m0, s16, 0x2000
	s_nop 0
	global_load_lds_dwordx4 v[218:219], off
	s_waitcnt lgkmcnt(0)
	s_setprio 1
	s_barrier
	v_mfma_f32_16x16x32_bf16 v[60:63], v[226:229], v[152:155], v[60:63]
	v_mfma_f32_16x16x32_bf16 v[56:59], v[234:237], v[152:155], v[56:59]
	v_mfma_f32_16x16x32_bf16 v[52:55], v[226:229], v[190:193], v[52:55]
	v_mfma_f32_16x16x32_bf16 v[48:51], v[234:237], v[190:193], v[48:51]
	v_mfma_f32_16x16x32_bf16 v[44:47], v[226:229], v[202:205], v[44:47]
	v_mfma_f32_16x16x32_bf16 v[40:43], v[234:237], v[202:205], v[40:43]
	v_mfma_f32_16x16x32_bf16 v[36:39], v[226:229], v[210:213], v[36:39]
	v_mfma_f32_16x16x32_bf16 v[32:35], v[234:237], v[210:213], v[32:35]
	v_mfma_f32_16x16x32_bf16 v[60:63], v[230:233], v[186:189], v[60:63]
	s_mov_b32 m0, s34
	v_mfma_f32_16x16x32_bf16 v[56:59], v[238:241], v[186:189], v[56:59]
	v_lshl_add_u64 v[218:219], v[242:243], 0, s[94:95]
	v_mfma_f32_16x16x32_bf16 v[52:55], v[230:233], v[194:197], v[52:55]
	v_mfma_f32_16x16x32_bf16 v[48:51], v[238:241], v[194:197], v[48:51]
	v_mfma_f32_16x16x32_bf16 v[44:47], v[230:233], v[206:209], v[44:47]
	v_mfma_f32_16x16x32_bf16 v[40:43], v[238:241], v[206:209], v[40:43]
	v_mfma_f32_16x16x32_bf16 v[36:39], v[230:233], v[214:217], v[36:39]
	v_mfma_f32_16x16x32_bf16 v[32:35], v[238:241], v[214:217], v[32:35]
	s_setprio 0
	s_barrier
	ds_read_b128 v[152:155], v201 offset:49152
	ds_read_b128 v[186:189], v201 offset:50176
	ds_read_b128 v[190:193], v201 offset:51200
	ds_read_b128 v[194:197], v201 offset:52224
	ds_read_b128 v[202:205], v201 offset:53248
	ds_read_b128 v[206:209], v201 offset:54272
	ds_read_b128 v[210:213], v201 offset:55296
	ds_read_b128 v[214:217], v201 offset:56320
	global_load_lds_dwordx4 v[218:219], off
	v_lshl_add_u64 v[218:219], v[244:245], 0, s[94:95]
	s_mov_b32 m0, s35
	s_nop 0
	global_load_lds_dwordx4 v[218:219], off
	s_waitcnt lgkmcnt(0)
	s_setprio 1
	s_barrier
; #define PG8_BAR __builtin_amdgcn_s_barrier()
; template <class Epi>
; DI void gemm_phase(LAS unsigned char* lds, const Gemm g, const StaticOrder& S, const Epi& E) {
;     ...
;             PG8_LDA(At, 1, 1); PG8_STAGE(PG8_SA(1, 0), a3);
;             PG8_BAR; PG8_WAIT_L(0); PG8_MMA(1, 0, At, B0); PG8_BAR; PG8_SCHED;
;             PG8_STAGE(PG8_SB(1, 1), b3 + hstep);
;             PG8_WAIT_V(6); PG8_BAR; PG8_MMA(1, 1, At, B1); PG8_BAR;
;     template <bool LN, int BJ, int LO, int HI> DI void batch(const f32x4 (&acc)[2][2][4][2], unsigned row0, unsigned col0, const f32x4 (&gv)[2], const f32x4 (&bv)[2]) const {
;         f32x4 r[HI - LO]; float mean[(HI - LO) / 2], rstd[(HI - LO) / 2];
; #pragma unroll
;         for (int i = LO; i < HI; ++i) { const int ai = i >> 3, m = (i >> 1) & 3, n = i & 1; const unsigned row = row0 + ai * HALF + m * 16;
;             if (n == 0) { mean[(i - LO) >> 1] = 0.f; rstd[(i - LO) >> 1] = 1.f;
;                 if (LN) { const float2 st = *(const float2*)(stats + row * 2u); mean[(i - LO) >> 1] = st.x; rstd[(i - LO) >> 1] = st.y; } }
;             r[i - LO] = *(const f32x4*)(src + (row * (unsigned)DM + col0 + BJ * HALF + n * 16)); }
; #pragma unroll
;         for (int i = LO; i < HI; ++i) { const int ai = i >> 3, m = (i >> 1) & 3, n = i & 1; const unsigned row = row0 + ai * HALF + m * 16;
;             *(f32x4*)(Y + (row * (unsigned)DM + col0 + BJ * HALF + n * 16)) = acc[ai][BJ][m][n] + ((r[i - LO] - mean[(i - LO) >> 1]) * rstd[(i - LO) >> 1]) * gv[n] + bv[n]; }
;         __builtin_amdgcn_sched_barrier(0);
;     }
;     template <bool LN, int BJ> DI void load_gb(unsigned col0, f32x4 (&gv)[2], f32x4 (&bv)[2]) const {
; #pragma unroll
;         for (int n = 0; n < 2; ++n) {
;             if (LN) { gv[n] = *(const f32x4*)(gam + col0 + BJ * HALF + n * 16) * ALPHA; bv[n] = *(const f32x4*)(bet + col0 + BJ * HALF + n * 16) * ALPHA; }
;             else { gv[n] = (f32x4){ALPHA, ALPHA, ALPHA, ALPHA}; bv[n] = (f32x4){0.f, 0.f, 0.f, 0.f}; }
;         }
;     }
;     template <bool LN> DI void run(const f32x4 (&acc)[2][2][4][2], const Unit& u, int wr, int wc, int fr, int fq) const {
;         const unsigned row0 = u.pm * BM + wr * 64 + fr, col0 = u.pn * BM + wc * 32 + 4 * fq;
;         f32x4 gv[2], bv[2];
;         load_gb<LN, 0>(col0, gv, bv);
;         batch<LN, 0, 0, 4>(acc, row0, col0, gv, bv);
;         batch<LN, 0, 4, 8>(acc, row0, col0, gv, bv);
	v_mfma_f32_16x16x32_bf16 v[92:95], v[96:99], v[152:155], v[92:95]
	v_mfma_f32_16x16x32_bf16 v[88:91], v[136:139], v[152:155], v[88:91]
	v_mfma_f32_16x16x32_bf16 v[84:87], v[96:99], v[190:193], v[84:87]
	v_mfma_f32_16x16x32_bf16 v[80:83], v[136:139], v[190:193], v[80:83]
	v_mfma_f32_16x16x32_bf16 v[76:79], v[96:99], v[202:205], v[76:79]
	v_mfma_f32_16x16x32_bf16 v[72:75], v[136:139], v[202:205], v[72:75]
	v_mfma_f32_16x16x32_bf16 v[68:71], v[96:99], v[210:213], v[68:71]
	v_mfma_f32_16x16x32_bf16 v[64:67], v[136:139], v[210:213], v[64:67]
	v_mfma_f32_16x16x32_bf16 v[92:95], v[100:103], v[186:189], v[92:95]
	v_mfma_f32_16x16x32_bf16 v[88:91], v[148:151], v[186:189], v[88:91]
	v_mfma_f32_16x16x32_bf16 v[84:87], v[100:103], v[194:197], v[84:87]
	v_mfma_f32_16x16x32_bf16 v[80:83], v[148:151], v[194:197], v[80:83]
	v_mfma_f32_16x16x32_bf16 v[76:79], v[100:103], v[206:209], v[76:79]
	v_mfma_f32_16x16x32_bf16 v[72:75], v[148:151], v[206:209], v[72:75]
	v_mfma_f32_16x16x32_bf16 v[68:71], v[100:103], v[214:217], v[68:71]
	v_mfma_f32_16x16x32_bf16 v[64:67], v[148:151], v[214:217], v[64:67]
	s_setprio 0
	s_barrier
	s_add_u32 s16, s20, 0x160080
	s_addc_u32 s17, s21, 0
	s_add_i32 s20, s22, s27
	v_lshl_add_u64 v[96:97], s[16:17], 0, v[142:143]
	s_mov_b32 m0, s20
	s_nop 0
	global_load_lds_dwordx4 v[96:97], off
	v_lshl_add_u64 v[96:97], s[16:17], 0, v[140:141]
	s_add_i32 m0, s20, 0x2000
	s_nop 0
	global_load_lds_dwordx4 v[96:97], off
	s_waitcnt vmcnt(6)
	s_setprio 1
	s_barrier
	v_mfma_f32_16x16x32_bf16 v[28:31], v[226:229], v[152:155], v[28:31]
	v_mfma_f32_16x16x32_bf16 v[24:27], v[234:237], v[152:155], v[24:27]
	v_mfma_f32_16x16x32_bf16 v[20:23], v[226:229], v[190:193], v[20:23]
	v_mfma_f32_16x16x32_bf16 v[16:19], v[234:237], v[190:193], v[16:19]
	v_mfma_f32_16x16x32_bf16 v[12:15], v[226:229], v[202:205], v[12:15]
	v_mfma_f32_16x16x32_bf16 v[8:11], v[234:237], v[202:205], v[8:11]
	v_mfma_f32_16x16x32_bf16 v[4:7], v[226:229], v[210:213], v[4:7]
	v_mfma_f32_16x16x32_bf16 v[0:3], v[234:237], v[210:213], v[0:3]
	v_mfma_f32_16x16x32_bf16 v[28:31], v[230:233], v[186:189], v[28:31]
	s_add_i32 s33, s33, 2
	v_mfma_f32_16x16x32_bf16 v[24:27], v[238:241], v[186:189], v[24:27]
	s_add_u32 s4, s4, 0x100
	v_mfma_f32_16x16x32_bf16 v[20:23], v[230:233], v[194:197], v[20:23]
	s_addc_u32 s5, s5, 0
	v_mfma_f32_16x16x32_bf16 v[16:19], v[238:241], v[194:197], v[16:19]
	s_cmpk_gt_u32 s33, 0x55
	v_mfma_f32_16x16x32_bf16 v[12:15], v[230:233], v[206:209], v[12:15]
	s_mov_b64 s[16:17], s[18:19]
	v_mfma_f32_16x16x32_bf16 v[8:11], v[238:241], v[206:209], v[8:11]
	v_mfma_f32_16x16x32_bf16 v[4:7], v[230:233], v[214:217], v[4:7]
	v_mfma_f32_16x16x32_bf16 v[0:3], v[238:241], v[214:217], v[0:3]
	s_setprio 0
	s_barrier
	s_cbranch_scc0 .LBB0_134
	v_lshl_or_b32 v158, s2, 8, v200
	v_lshlrev_b64 v[100:101], 2, v[158:159]
	v_lshl_add_u64 v[150:151], s[12:13], 0, v[100:101]
	global_load_dwordx4 v[96:99], v[150:151], off
	v_lshl_add_u64 v[152:153], s[14:15], 0, v[100:101]
	v_lshl_add_u32 v203, s3, 8, v198
	v_lshlrev_b32_e32 v202, 11, v203
	v_add_u32_e32 v148, v202, v158
	v_mov_b32_e32 v149, v159
	v_lshlrev_b32_e32 v136, 1, v203
	v_mov_b32_e32 v137, v159
	v_lshlrev_b64 v[220:221], 2, v[148:149]
	v_lshl_add_u64 v[154:155], v[136:137], 2, s[96:97]
	v_lshl_add_u64 v[136:137], s[90:91], 0, v[220:221]
	v_or_b32_e32 v204, 16, v158
	v_or_b32_e32 v138, 16, v203
	v_lshlrev_b32_e32 v149, 11, v138
	s_waitcnt vmcnt(0)
	v_pk_mul_f32 v[192:193], v[98:99], s[78:79] op_sel_hi:[1,0]
	v_pk_mul_f32 v[194:195], v[96:97], s[78:79] op_sel_hi:[1,0]
	global_load_dwordx4 v[100:103], v[152:153], off
	global_load_dwordx4 v[96:99], v[150:151], off offset:64
	global_load_dwordx2 v[218:219], v[154:155], off
	global_load_dwordx4 v[206:209], v[136:137], off
	v_add_u32_e32 v136, v202, v204
	v_mov_b32_e32 v137, v159
	v_lshl_add_u64 v[136:137], v[136:137], 2, s[90:91]
	global_load_dwordx4 v[210:213], v[136:137], off
	v_lshlrev_b32_e32 v136, 1, v138
	v_mov_b32_e32 v137, v159
	v_lshl_add_u64 v[186:187], v[136:137], 2, s[96:97]
	v_add_u32_e32 v136, v149, v158
	v_lshl_add_u64 v[136:137], v[136:137], 2, s[90:91]
	global_load_dwordx2 v[196:197], v[186:187], off
	global_load_dwordx4 v[214:217], v[136:137], off
	v_add_u32_e32 v136, v149, v204
	v_mov_b32_e32 v137, v159
	v_lshl_add_u64 v[136:137], v[136:137], 2, s[90:91]
	global_load_dwordx4 v[136:139], v[136:137], off
	s_waitcnt vmcnt(0)
	v_pk_mul_f32 v[188:189], v[98:99], s[78:79] op_sel_hi:[1,0]
	v_pk_mul_f32 v[190:191], v[96:97], s[78:79] op_sel_hi:[1,0]
	global_load_dwordx4 v[96:99], v[152:153], off offset:64
	v_sub_f32_e32 v207, v207, v218
	v_sub_f32_e32 v206, v206, v218
	v_sub_f32_e32 v209, v209, v218
	v_sub_f32_e32 v208, v208, v218
	v_pk_mul_f32 v[208:209], v[218:219], v[208:209] op_sel:[1,0]
	v_pk_mul_f32 v[206:207], v[218:219], v[206:207] op_sel:[1,0]
	v_pk_fma_f32 v[134:135], v[192:193], v[208:209], v[134:135]
	v_pk_fma_f32 v[132:133], v[194:195], v[206:207], v[132:133]
	v_pk_fma_f32 v[134:135], v[102:103], s[78:79], v[134:135] op_sel_hi:[1,0,1]
	v_pk_fma_f32 v[132:133], v[100:101], s[78:79], v[132:133] op_sel_hi:[1,0,1]
	v_lshl_add_u64 v[206:207], s[88:89], 0, v[220:221]
	global_store_dwordx4 v[206:207], v[132:135], off
	s_nop 1
	v_sub_f32_e32 v133, v211, v218
	v_sub_f32_e32 v132, v210, v218
	v_sub_f32_e32 v135, v213, v218
	v_sub_f32_e32 v134, v212, v218
	v_pk_mul_f32 v[134:135], v[218:219], v[134:135] op_sel:[1,0]
	v_pk_mul_f32 v[132:133], v[218:219], v[132:133] op_sel:[1,0]
	v_pk_fma_f32 v[130:131], v[188:189], v[134:135], v[130:131]
	v_pk_fma_f32 v[128:129], v[190:191], v[132:133], v[128:129]
	v_or_b32_e32 v132, 16, v148
	v_mov_b32_e32 v133, v159
	v_lshl_add_u64 v[132:133], v[132:133], 2, s[88:89]
	s_waitcnt vmcnt(0)
;     template <bool LN, int BJ, int LO, int HI> DI void batch(const f32x4 (&acc)[2][2][4][2], unsigned row0, unsigned col0, const f32x4 (&gv)[2], const f32x4 (&bv)[2]) const {
;         f32x4 r[HI - LO]; float mean[(HI - LO) / 2], rstd[(HI - LO) / 2];
; #pragma unroll
;         for (int i = LO; i < HI; ++i) { const int ai = i >> 3, m = (i >> 1) & 3, n = i & 1; const unsigned row = row0 + ai * HALF + m * 16;
;             if (n == 0) { mean[(i - LO) >> 1] = 0.f; rstd[(i - LO) >> 1] = 1.f;
;                 if (LN) { const float2 st = *(const float2*)(stats + row * 2u); mean[(i - LO) >> 1] = st.x; rstd[(i - LO) >> 1] = st.y; } }
;             r[i - LO] = *(const f32x4*)(src + (row * (unsigned)DM + col0 + BJ * HALF + n * 16)); }
; #pragma unroll
;         for (int i = LO; i < HI; ++i) { const int ai = i >> 3, m = (i >> 1) & 3, n = i & 1; const unsigned row = row0 + ai * HALF + m * 16;
;             *(f32x4*)(Y + (row * (unsigned)DM + col0 + BJ * HALF + n * 16)) = acc[ai][BJ][m][n] + ((r[i - LO] - mean[(i - LO) >> 1]) * rstd[(i - LO) >> 1]) * gv[n] + bv[n]; }
	v_pk_fma_f32 v[130:131], v[98:99], s[78:79], v[130:131] op_sel_hi:[1,0,1]
	v_pk_fma_f32 v[128:129], v[96:97], s[78:79], v[128:129] op_sel_hi:[1,0,1]
	global_store_dwordx4 v[132:133], v[128:131], off
	s_nop 1
	v_sub_f32_e32 v129, v215, v196
	v_sub_f32_e32 v128, v214, v196
	v_sub_f32_e32 v131, v217, v196
	v_sub_f32_e32 v130, v216, v196
	v_pk_mul_f32 v[130:131], v[196:197], v[130:131] op_sel:[1,0]
	v_pk_mul_f32 v[128:129], v[196:197], v[128:129] op_sel:[1,0]
	v_pk_fma_f32 v[126:127], v[192:193], v[130:131], v[126:127]
	v_pk_fma_f32 v[124:125], v[194:195], v[128:129], v[124:125]
	v_add_u32_e32 v128, 0x8000, v148
	v_mov_b32_e32 v129, v159
	v_pk_fma_f32 v[126:127], v[102:103], s[78:79], v[126:127] op_sel_hi:[1,0,1]
	v_pk_fma_f32 v[124:125], v[100:101], s[78:79], v[124:125] op_sel_hi:[1,0,1]
	v_lshl_add_u64 v[128:129], v[128:129], 2, s[88:89]
	global_store_dwordx4 v[128:129], v[124:127], off
	s_nop 1
	v_sub_f32_e32 v125, v137, v196
	v_sub_f32_e32 v124, v136, v196
	v_sub_f32_e32 v127, v139, v196
	v_sub_f32_e32 v126, v138, v196
	v_pk_mul_f32 v[126:127], v[196:197], v[126:127] op_sel:[1,0]
	v_pk_mul_f32 v[124:125], v[196:197], v[124:125] op_sel:[1,0]
	v_pk_fma_f32 v[122:123], v[188:189], v[126:127], v[122:123]
	v_pk_fma_f32 v[120:121], v[190:191], v[124:125], v[120:121]
	v_add_u32_e32 v124, 0x8010, v148
	v_mov_b32_e32 v125, v159
	v_pk_fma_f32 v[122:123], v[98:99], s[78:79], v[122:123] op_sel_hi:[1,0,1]
	v_pk_fma_f32 v[120:121], v[96:97], s[78:79], v[120:121] op_sel_hi:[1,0,1]
	v_lshl_add_u64 v[124:125], v[124:125], 2, s[88:89]
	global_store_dwordx4 v[124:125], v[120:123], off
	s_nop 1
	v_or_b32_e32 v122, 32, v203
	v_lshlrev_b32_e32 v124, 11, v122
	v_lshlrev_b32_e32 v120, 1, v122
	v_mov_b32_e32 v121, v159
	v_add_u32_e32 v122, v124, v158
	v_mov_b32_e32 v123, v159
	v_lshl_add_u64 v[120:121], v[120:121], 2, s[96:97]
	v_lshl_add_u64 v[122:123], v[122:123], 2, s[90:91]
	global_load_dwordx2 v[138:139], v[120:121], off
	global_load_dwordx4 v[126:129], v[122:123], off
	v_add_u32_e32 v122, v124, v204
	v_mov_b32_e32 v123, v159
	v_lshl_add_u64 v[122:123], v[122:123], 2, s[90:91]
	global_load_dwordx4 v[130:133], v[122:123], off
	v_or_b32_e32 v125, 48, v203
	v_lshlrev_b32_e32 v122, 1, v125
	v_lshlrev_b32_e32 v125, 11, v125
	v_mov_b32_e32 v123, v159
	v_add_u32_e32 v134, v125, v158
	v_mov_b32_e32 v135, v159
	v_lshl_add_u64 v[122:123], v[122:123], 2, s[96:97]
	v_lshl_add_u64 v[134:135], v[134:135], 2, s[90:91]
	global_load_dwordx2 v[196:197], v[122:123], off
	v_add_u32_e32 v206, v125, v204
	global_load_dwordx4 v[134:137], v[134:135], off
	v_mov_b32_e32 v207, v159
	v_lshl_add_u64 v[206:207], v[206:207], 2, s[90:91]
	global_load_dwordx4 v[206:209], v[206:207], off
	s_waitcnt vmcnt(0)
	v_sub_f32_e32 v127, v127, v138
	v_sub_f32_e32 v126, v126, v138
	v_sub_f32_e32 v129, v129, v138
	v_sub_f32_e32 v128, v128, v138
	v_pk_mul_f32 v[128:129], v[138:139], v[128:129] op_sel:[1,0]
	v_pk_mul_f32 v[126:127], v[138:139], v[126:127] op_sel:[1,0]
	v_pk_fma_f32 v[118:119], v[192:193], v[128:129], v[118:119]
	v_pk_fma_f32 v[116:117], v[194:195], v[126:127], v[116:117]
	v_add_u32_e32 v126, 0x10000, v148
	v_mov_b32_e32 v127, v159
	v_pk_fma_f32 v[118:119], v[102:103], s[78:79], v[118:119] op_sel_hi:[1,0,1]
	v_pk_fma_f32 v[116:117], v[100:101], s[78:79], v[116:117] op_sel_hi:[1,0,1]
	v_lshl_add_u64 v[126:127], v[126:127], 2, s[88:89]
	global_store_dwordx4 v[126:127], v[116:119], off
	s_nop 1
	v_sub_f32_e32 v117, v131, v138
	v_sub_f32_e32 v116, v130, v138
	v_sub_f32_e32 v119, v133, v138
	v_sub_f32_e32 v118, v132, v138
	v_pk_mul_f32 v[118:119], v[138:139], v[118:119] op_sel:[1,0]
	v_pk_mul_f32 v[116:117], v[138:139], v[116:117] op_sel:[1,0]
	v_pk_fma_f32 v[114:115], v[188:189], v[118:119], v[114:115]
	v_pk_fma_f32 v[112:113], v[190:191], v[116:117], v[112:113]
	v_add_u32_e32 v116, 0x10010, v148
	v_mov_b32_e32 v117, v159
	v_pk_fma_f32 v[114:115], v[98:99], s[78:79], v[114:115] op_sel_hi:[1,0,1]
	v_pk_fma_f32 v[112:113], v[96:97], s[78:79], v[112:113] op_sel_hi:[1,0,1]
	v_lshl_add_u64 v[116:117], v[116:117], 2, s[88:89]
	global_store_dwordx4 v[116:117], v[112:115], off
	s_nop 1
	v_sub_f32_e32 v113, v135, v196
	v_sub_f32_e32 v112, v134, v196
	v_sub_f32_e32 v115, v137, v196
	v_sub_f32_e32 v114, v136, v196
	v_pk_mul_f32 v[114:115], v[196:197], v[114:115] op_sel:[1,0]
	v_pk_mul_f32 v[112:113], v[196:197], v[112:113] op_sel:[1,0]
	v_pk_fma_f32 v[110:111], v[192:193], v[114:115], v[110:111]
	v_pk_fma_f32 v[108:109], v[194:195], v[112:113], v[108:109]
	v_add_u32_e32 v112, 0x18000, v148
	v_mov_b32_e32 v113, v159
	v_pk_fma_f32 v[110:111], v[102:103], s[78:79], v[110:111] op_sel_hi:[1,0,1]
	v_pk_fma_f32 v[108:109], v[100:101], s[78:79], v[108:109] op_sel_hi:[1,0,1]
	v_lshl_add_u64 v[112:113], v[112:113], 2, s[88:89]
	global_store_dwordx4 v[112:113], v[108:111], off
	s_nop 1
	v_sub_f32_e32 v109, v207, v196
	v_sub_f32_e32 v108, v206, v196
	v_sub_f32_e32 v111, v209, v196
	v_sub_f32_e32 v110, v208, v196
	v_pk_mul_f32 v[110:111], v[196:197], v[110:111] op_sel:[1,0]
	v_pk_mul_f32 v[108:109], v[196:197], v[108:109] op_sel:[1,0]
	v_pk_fma_f32 v[106:107], v[188:189], v[110:111], v[106:107]
	v_pk_fma_f32 v[104:105], v[190:191], v[108:109], v[104:105]
	v_add_u32_e32 v108, 0x18010, v148
	v_mov_b32_e32 v109, v159
	v_pk_fma_f32 v[106:107], v[98:99], s[78:79], v[106:107] op_sel_hi:[1,0,1]
	v_pk_fma_f32 v[104:105], v[96:97], s[78:79], v[104:105] op_sel_hi:[1,0,1]
	v_lshl_add_u64 v[108:109], v[108:109], 2, s[88:89]
	global_store_dwordx4 v[108:109], v[104:107], off
	s_nop 1
	v_add_u32_e32 v106, 0x80, v203
	v_lshlrev_b32_e32 v114, 11, v106
	v_lshlrev_b32_e32 v104, 1, v106
	v_mov_b32_e32 v105, v159
	v_add_u32_e32 v106, v114, v158
	v_mov_b32_e32 v107, v159
	v_lshl_add_u64 v[104:105], v[104:105], 2, s[96:97]
	v_lshl_add_u64 v[106:107], v[106:107], 2, s[90:91]
	global_load_dwordx2 v[112:113], v[104:105], off
	global_load_dwordx4 v[108:111], v[106:107], off
	v_add_u32_e32 v106, v114, v204
	v_mov_b32_e32 v107, v159
	v_lshl_add_u64 v[106:107], v[106:107], 2, s[90:91]
	global_load_dwordx4 v[116:119], v[106:107], off
	v_add_u32_e32 v115, 0x90, v203
	v_lshlrev_b32_e32 v106, 1, v115
	v_lshlrev_b32_e32 v115, 11, v115
	v_mov_b32_e32 v107, v159
	v_add_u32_e32 v126, v115, v158
	v_mov_b32_e32 v127, v159
	v_lshl_add_u64 v[106:107], v[106:107], 2, s[96:97]
	v_lshl_add_u64 v[126:127], v[126:127], 2, s[90:91]
	global_load_dwordx2 v[134:135], v[106:107], off
	v_add_u32_e32 v130, v115, v204
	global_load_dwordx4 v[126:129], v[126:127], off
	v_mov_b32_e32 v131, v159
	v_lshl_add_u64 v[130:131], v[130:131], 2, s[90:91]
	global_load_dwordx4 v[130:133], v[130:131], off
	s_waitcnt vmcnt(0)
;     template <bool LN, int BJ, int LO, int HI> DI void batch(const f32x4 (&acc)[2][2][4][2], unsigned row0, unsigned col0, const f32x4 (&gv)[2], const f32x4 (&bv)[2]) const {
;     ...
;         for (int i = LO; i < HI; ++i) { const int ai = i >> 3, m = (i >> 1) & 3, n = i & 1; const unsigned row = row0 + ai * HALF + m * 16;
;             if (n == 0) { mean[(i - LO) >> 1] = 0.f; rstd[(i - LO) >> 1] = 1.f;
;                 if (LN) { const float2 st = *(const float2*)(stats + row * 2u); mean[(i - LO) >> 1] = st.x; rstd[(i - LO) >> 1] = st.y; } }
;             r[i - LO] = *(const f32x4*)(src + (row * (unsigned)DM + col0 + BJ * HALF + n * 16)); }
; #pragma unroll
;         for (int i = LO; i < HI; ++i) { const int ai = i >> 3, m = (i >> 1) & 3, n = i & 1; const unsigned row = row0 + ai * HALF + m * 16;
;             *(f32x4*)(Y + (row * (unsigned)DM + col0 + BJ * HALF + n * 16)) = acc[ai][BJ][m][n] + ((r[i - LO] - mean[(i - LO) >> 1]) * rstd[(i - LO) >> 1]) * gv[n] + bv[n]; }
	v_sub_f32_e32 v109, v109, v112
	v_sub_f32_e32 v108, v108, v112
	v_sub_f32_e32 v111, v111, v112
	v_sub_f32_e32 v110, v110, v112
	v_pk_mul_f32 v[110:111], v[112:113], v[110:111] op_sel:[1,0]
	v_pk_mul_f32 v[108:109], v[112:113], v[108:109] op_sel:[1,0]
	v_pk_fma_f32 v[94:95], v[192:193], v[110:111], v[94:95]
	v_pk_fma_f32 v[92:93], v[194:195], v[108:109], v[92:93]
	v_add_u32_e32 v108, 0x40000, v148
	v_mov_b32_e32 v109, v159
	v_pk_fma_f32 v[94:95], v[102:103], s[78:79], v[94:95] op_sel_hi:[1,0,1]
	v_pk_fma_f32 v[92:93], v[100:101], s[78:79], v[92:93] op_sel_hi:[1,0,1]
	v_lshl_add_u64 v[108:109], v[108:109], 2, s[88:89]
	global_store_dwordx4 v[108:109], v[92:95], off
	s_nop 1
	v_sub_f32_e32 v93, v117, v112
	v_sub_f32_e32 v92, v116, v112
	v_sub_f32_e32 v95, v119, v112
	v_sub_f32_e32 v94, v118, v112
	v_pk_mul_f32 v[94:95], v[112:113], v[94:95] op_sel:[1,0]
	v_pk_mul_f32 v[92:93], v[112:113], v[92:93] op_sel:[1,0]
	v_pk_fma_f32 v[90:91], v[188:189], v[94:95], v[90:91]
	v_pk_fma_f32 v[88:89], v[190:191], v[92:93], v[88:89]
	v_add_u32_e32 v92, 0x40010, v148
	v_mov_b32_e32 v93, v159
	v_pk_fma_f32 v[90:91], v[98:99], s[78:79], v[90:91] op_sel_hi:[1,0,1]
	v_pk_fma_f32 v[88:89], v[96:97], s[78:79], v[88:89] op_sel_hi:[1,0,1]
	v_lshl_add_u64 v[92:93], v[92:93], 2, s[88:89]
	global_store_dwordx4 v[92:93], v[88:91], off
	s_nop 1
	v_sub_f32_e32 v89, v127, v134
	v_sub_f32_e32 v88, v126, v134
	v_sub_f32_e32 v91, v129, v134
	v_sub_f32_e32 v90, v128, v134
	v_pk_mul_f32 v[90:91], v[134:135], v[90:91] op_sel:[1,0]
	v_pk_mul_f32 v[88:89], v[134:135], v[88:89] op_sel:[1,0]
	v_pk_fma_f32 v[86:87], v[192:193], v[90:91], v[86:87]
	v_pk_fma_f32 v[84:85], v[194:195], v[88:89], v[84:85]
	v_add_u32_e32 v88, 0x48000, v148
	v_mov_b32_e32 v89, v159
	v_pk_fma_f32 v[86:87], v[102:103], s[78:79], v[86:87] op_sel_hi:[1,0,1]
	v_pk_fma_f32 v[84:85], v[100:101], s[78:79], v[84:85] op_sel_hi:[1,0,1]
	v_lshl_add_u64 v[88:89], v[88:89], 2, s[88:89]
	global_store_dwordx4 v[88:89], v[84:87], off
	s_nop 1
	v_sub_f32_e32 v85, v131, v134
	v_sub_f32_e32 v84, v130, v134
	v_sub_f32_e32 v87, v133, v134
	v_sub_f32_e32 v86, v132, v134
	v_pk_mul_f32 v[86:87], v[134:135], v[86:87] op_sel:[1,0]
	v_pk_mul_f32 v[84:85], v[134:135], v[84:85] op_sel:[1,0]
	v_pk_fma_f32 v[82:83], v[188:189], v[86:87], v[82:83]
	v_pk_fma_f32 v[80:81], v[190:191], v[84:85], v[80:81]
	v_add_u32_e32 v84, 0x48010, v148
	v_mov_b32_e32 v85, v159
	v_pk_fma_f32 v[82:83], v[98:99], s[78:79], v[82:83] op_sel_hi:[1,0,1]
	v_pk_fma_f32 v[80:81], v[96:97], s[78:79], v[80:81] op_sel_hi:[1,0,1]
	v_lshl_add_u64 v[84:85], v[84:85], 2, s[88:89]
	global_store_dwordx4 v[84:85], v[80:83], off
	s_nop 1
	v_add_u32_e32 v82, 0xa0, v203
	v_lshlrev_b32_e32 v80, 1, v82
	v_mov_b32_e32 v81, v159
	v_lshlrev_b32_e32 v116, 11, v82
	v_lshl_add_u64 v[108:109], v[80:81], 2, s[96:97]
	v_add_u32_e32 v80, v116, v158
	v_lshl_add_u64 v[80:81], v[80:81], 2, s[90:91]
	global_load_dwordx2 v[112:113], v[108:109], off
	v_add_u32_e32 v84, v116, v204
	global_load_dwordx4 v[80:83], v[80:81], off
	v_mov_b32_e32 v85, v159
	v_lshl_add_u64 v[84:85], v[84:85], 2, s[90:91]
	global_load_dwordx4 v[84:87], v[84:85], off
	v_add_u32_e32 v90, 0xb0, v203
	v_lshlrev_b32_e32 v88, 1, v90
	v_mov_b32_e32 v89, v159
	v_lshlrev_b32_e32 v117, 11, v90
	v_lshl_add_u64 v[110:111], v[88:89], 2, s[96:97]
	v_add_u32_e32 v88, v117, v158
	v_lshl_add_u64 v[88:89], v[88:89], 2, s[90:91]
	global_load_dwordx2 v[118:119], v[110:111], off
	v_add_u32_e32 v92, v117, v204
	global_load_dwordx4 v[88:91], v[88:89], off
	v_mov_b32_e32 v93, v159
	v_lshl_add_u64 v[92:93], v[92:93], 2, s[90:91]
	global_load_dwordx4 v[92:95], v[92:93], off
	s_waitcnt vmcnt(0)
	v_sub_f32_e32 v81, v81, v112
	v_sub_f32_e32 v80, v80, v112
	v_sub_f32_e32 v83, v83, v112
	v_sub_f32_e32 v82, v82, v112
	v_pk_mul_f32 v[82:83], v[112:113], v[82:83] op_sel:[1,0]
	v_pk_mul_f32 v[80:81], v[112:113], v[80:81] op_sel:[1,0]
	v_pk_fma_f32 v[78:79], v[192:193], v[82:83], v[78:79]
	v_pk_fma_f32 v[76:77], v[194:195], v[80:81], v[76:77]
	v_add_u32_e32 v80, 0x50000, v148
	v_mov_b32_e32 v81, v159
	v_pk_fma_f32 v[78:79], v[102:103], s[78:79], v[78:79] op_sel_hi:[1,0,1]
	v_pk_fma_f32 v[76:77], v[100:101], s[78:79], v[76:77] op_sel_hi:[1,0,1]
	v_lshl_add_u64 v[80:81], v[80:81], 2, s[88:89]
	global_store_dwordx4 v[80:81], v[76:79], off
	s_nop 1
	v_sub_f32_e32 v77, v85, v112
	v_sub_f32_e32 v76, v84, v112
	v_sub_f32_e32 v79, v87, v112
	v_sub_f32_e32 v78, v86, v112
	v_pk_mul_f32 v[78:79], v[112:113], v[78:79] op_sel:[1,0]
	v_pk_mul_f32 v[76:77], v[112:113], v[76:77] op_sel:[1,0]
	v_pk_fma_f32 v[74:75], v[188:189], v[78:79], v[74:75]
	v_pk_fma_f32 v[72:73], v[190:191], v[76:77], v[72:73]
	v_add_u32_e32 v76, 0x50010, v148
	v_mov_b32_e32 v77, v159
	v_pk_fma_f32 v[74:75], v[98:99], s[78:79], v[74:75] op_sel_hi:[1,0,1]
	v_pk_fma_f32 v[72:73], v[96:97], s[78:79], v[72:73] op_sel_hi:[1,0,1]
	v_lshl_add_u64 v[76:77], v[76:77], 2, s[88:89]
	global_store_dwordx4 v[76:77], v[72:75], off
	s_nop 1
	v_sub_f32_e32 v73, v89, v118
	v_sub_f32_e32 v72, v88, v118
	v_sub_f32_e32 v75, v91, v118
	v_sub_f32_e32 v74, v90, v118
	v_pk_mul_f32 v[74:75], v[118:119], v[74:75] op_sel:[1,0]
	v_pk_mul_f32 v[72:73], v[118:119], v[72:73] op_sel:[1,0]
	v_pk_fma_f32 v[70:71], v[192:193], v[74:75], v[70:71]
	v_pk_fma_f32 v[68:69], v[194:195], v[72:73], v[68:69]
	v_add_u32_e32 v72, 0x58000, v148
	v_mov_b32_e32 v73, v159
	v_pk_fma_f32 v[70:71], v[102:103], s[78:79], v[70:71] op_sel_hi:[1,0,1]
	v_pk_fma_f32 v[68:69], v[100:101], s[78:79], v[68:69] op_sel_hi:[1,0,1]
	v_lshl_add_u64 v[72:73], v[72:73], 2, s[88:89]
	global_store_dwordx4 v[72:73], v[68:71], off
	s_nop 1
	v_sub_f32_e32 v69, v93, v118
	v_sub_f32_e32 v68, v92, v118
	v_sub_f32_e32 v71, v95, v118
	v_sub_f32_e32 v70, v94, v118
	v_pk_mul_f32 v[70:71], v[118:119], v[70:71] op_sel:[1,0]
	v_pk_mul_f32 v[68:69], v[118:119], v[68:69] op_sel:[1,0]
	v_pk_fma_f32 v[66:67], v[188:189], v[70:71], v[66:67]
	v_pk_fma_f32 v[64:65], v[190:191], v[68:69], v[64:65]
	v_add_u32_e32 v68, 0x58010, v148
	v_mov_b32_e32 v69, v159
	v_pk_fma_f32 v[66:67], v[98:99], s[78:79], v[66:67] op_sel_hi:[1,0,1]
	v_pk_fma_f32 v[64:65], v[96:97], s[78:79], v[64:65] op_sel_hi:[1,0,1]
	v_lshl_add_u64 v[68:69], v[68:69], 2, s[88:89]
	global_store_dwordx4 v[68:69], v[64:67], off
	global_load_dwordx4 v[64:67], v[150:151], off offset:512
	v_or_b32_e32 v119, 0x80, v158
	v_add_u32_e32 v72, v202, v119
	v_mov_b32_e32 v73, v159
	v_lshl_add_u64 v[72:73], v[72:73], 2, s[90:91]
	v_or_b32_e32 v118, 0x90, v158
	v_add_u32_e32 v158, v202, v118
	s_waitcnt vmcnt(0)
;     template <bool LN, int BJ, int LO, int HI> DI void batch(const f32x4 (&acc)[2][2][4][2], unsigned row0, unsigned col0, const f32x4 (&gv)[2], const f32x4 (&bv)[2]) const {
;     ...
;         for (int i = LO; i < HI; ++i) { const int ai = i >> 3, m = (i >> 1) & 3, n = i & 1; const unsigned row = row0 + ai * HALF + m * 16;
;             if (n == 0) { mean[(i - LO) >> 1] = 0.f; rstd[(i - LO) >> 1] = 1.f;
;                 if (LN) { const float2 st = *(const float2*)(stats + row * 2u); mean[(i - LO) >> 1] = st.x; rstd[(i - LO) >> 1] = st.y; } }
;             r[i - LO] = *(const f32x4*)(src + (row * (unsigned)DM + col0 + BJ * HALF + n * 16)); }
; #pragma unroll
;         for (int i = LO; i < HI; ++i) { const int ai = i >> 3, m = (i >> 1) & 3, n = i & 1; const unsigned row = row0 + ai * HALF + m * 16;
;             *(f32x4*)(Y + (row * (unsigned)DM + col0 + BJ * HALF + n * 16)) = acc[ai][BJ][m][n] + ((r[i - LO] - mean[(i - LO) >> 1]) * rstd[(i - LO) >> 1]) * gv[n] + bv[n]; }
;     template <bool LN, int BJ> DI void load_gb(unsigned col0, f32x4 (&gv)[2], f32x4 (&bv)[2]) const {
; #pragma unroll
;         for (int n = 0; n < 2; ++n) {
;             if (LN) { gv[n] = *(const f32x4*)(gam + col0 + BJ * HALF + n * 16) * ALPHA; bv[n] = *(const f32x4*)(bet + col0 + BJ * HALF + n * 16) * ALPHA; }
;             else { gv[n] = (f32x4){ALPHA, ALPHA, ALPHA, ALPHA}; bv[n] = (f32x4){0.f, 0.f, 0.f, 0.f}; }
;         }
	v_pk_mul_f32 v[96:97], v[66:67], s[78:79] op_sel_hi:[1,0]
	v_pk_mul_f32 v[98:99], v[64:65], s[78:79] op_sel_hi:[1,0]
	global_load_dwordx4 v[68:71], v[152:153], off offset:512
	global_load_dwordx4 v[64:67], v[150:151], off offset:576
	global_load_dwordx2 v[138:139], v[154:155], off
	global_load_dwordx4 v[126:129], v[72:73], off
	v_lshl_add_u64 v[72:73], v[158:159], 2, s[90:91]
	v_add_u32_e32 v158, v149, v119
	s_waitcnt vmcnt(0)
	v_pk_mul_f32 v[92:93], v[66:67], s[78:79] op_sel_hi:[1,0]
	v_pk_mul_f32 v[94:95], v[64:65], s[78:79] op_sel_hi:[1,0]
	global_load_dwordx4 v[64:67], v[152:153], off offset:576
	global_load_dwordx4 v[130:133], v[72:73], off
	global_load_dwordx2 v[112:113], v[186:187], off
	v_lshl_add_u64 v[72:73], v[158:159], 2, s[90:91]
	global_load_dwordx4 v[134:137], v[72:73], off
	v_add_u32_e32 v158, v149, v118
	v_lshl_add_u64 v[72:73], v[158:159], 2, s[90:91]
	global_load_dwordx4 v[88:91], v[72:73], off
	global_load_dwordx2 v[102:103], v[120:121], off
	v_add_u32_e32 v158, v124, v119
	v_lshl_add_u64 v[72:73], v[158:159], 2, s[90:91]
	global_load_dwordx4 v[84:87], v[72:73], off
	v_add_u32_e32 v158, v124, v118
	v_lshl_add_u64 v[72:73], v[158:159], 2, s[90:91]
	global_load_dwordx4 v[80:83], v[72:73], off
	global_load_dwordx2 v[100:101], v[122:123], off
	v_add_u32_e32 v158, v125, v119
	v_lshl_add_u64 v[72:73], v[158:159], 2, s[90:91]
	global_load_dwordx4 v[76:79], v[72:73], off
	v_add_u32_e32 v158, v125, v118
	v_lshl_add_u64 v[72:73], v[158:159], 2, s[90:91]
	global_load_dwordx4 v[72:75], v[72:73], off
	v_sub_f32_e32 v121, v127, v138
	v_sub_f32_e32 v120, v126, v138
	v_sub_f32_e32 v123, v129, v138
	v_sub_f32_e32 v122, v128, v138
	v_pk_mul_f32 v[122:123], v[138:139], v[122:123] op_sel:[1,0]
	v_pk_mul_f32 v[120:121], v[138:139], v[120:121] op_sel:[1,0]
	v_or_b32_e32 v158, 0x80, v148
	v_pk_fma_f32 v[60:61], v[98:99], v[120:121], v[60:61]
	v_pk_fma_f32 v[62:63], v[96:97], v[122:123], v[62:63]
	v_pk_fma_f32 v[60:61], v[68:69], s[78:79], v[60:61] op_sel_hi:[1,0,1]
	v_pk_fma_f32 v[62:63], v[70:71], s[78:79], v[62:63] op_sel_hi:[1,0,1]
	v_lshl_add_u64 v[120:121], v[158:159], 2, s[88:89]
	global_store_dwordx4 v[120:121], v[60:63], off
	v_or_b32_e32 v158, 0x90, v148
	s_waitcnt vmcnt(0)
	v_sub_f32_e32 v61, v131, v138
	v_sub_f32_e32 v60, v130, v138
	v_sub_f32_e32 v63, v133, v138
	v_sub_f32_e32 v62, v132, v138
	v_pk_mul_f32 v[62:63], v[138:139], v[62:63] op_sel:[1,0]
	v_pk_mul_f32 v[60:61], v[138:139], v[60:61] op_sel:[1,0]
	v_pk_fma_f32 v[58:59], v[92:93], v[62:63], v[58:59]
	v_pk_fma_f32 v[56:57], v[94:95], v[60:61], v[56:57]
	v_pk_fma_f32 v[58:59], v[66:67], s[78:79], v[58:59] op_sel_hi:[1,0,1]
	v_pk_fma_f32 v[56:57], v[64:65], s[78:79], v[56:57] op_sel_hi:[1,0,1]
	v_lshl_add_u64 v[60:61], v[158:159], 2, s[88:89]
	global_store_dwordx4 v[60:61], v[56:59], off
	v_add_u32_e32 v158, 0x8080, v148
	s_nop 0
	v_sub_f32_e32 v57, v135, v112
	v_sub_f32_e32 v56, v134, v112
	v_sub_f32_e32 v59, v137, v112
	v_sub_f32_e32 v58, v136, v112
	v_pk_mul_f32 v[58:59], v[112:113], v[58:59] op_sel:[1,0]
	v_pk_mul_f32 v[56:57], v[112:113], v[56:57] op_sel:[1,0]
	v_pk_fma_f32 v[54:55], v[96:97], v[58:59], v[54:55]
	v_pk_fma_f32 v[52:53], v[98:99], v[56:57], v[52:53]
	v_pk_fma_f32 v[54:55], v[70:71], s[78:79], v[54:55] op_sel_hi:[1,0,1]
	v_pk_fma_f32 v[52:53], v[68:69], s[78:79], v[52:53] op_sel_hi:[1,0,1]
	v_lshl_add_u64 v[56:57], v[158:159], 2, s[88:89]
	global_store_dwordx4 v[56:57], v[52:55], off
	v_add_u32_e32 v158, 0x8090, v148
	s_nop 0
	v_sub_f32_e32 v53, v89, v112
	v_sub_f32_e32 v52, v88, v112
	v_sub_f32_e32 v55, v91, v112
	v_sub_f32_e32 v54, v90, v112
	v_pk_mul_f32 v[54:55], v[112:113], v[54:55] op_sel:[1,0]
	v_pk_mul_f32 v[52:53], v[112:113], v[52:53] op_sel:[1,0]
	v_pk_fma_f32 v[50:51], v[92:93], v[54:55], v[50:51]
	v_pk_fma_f32 v[48:49], v[94:95], v[52:53], v[48:49]
	v_pk_fma_f32 v[50:51], v[66:67], s[78:79], v[50:51] op_sel_hi:[1,0,1]
	v_pk_fma_f32 v[48:49], v[64:65], s[78:79], v[48:49] op_sel_hi:[1,0,1]
	v_lshl_add_u64 v[52:53], v[158:159], 2, s[88:89]
	global_store_dwordx4 v[52:53], v[48:51], off
	v_add_u32_e32 v158, 0x10080, v148
	s_nop 0
	v_sub_f32_e32 v49, v85, v102
	v_sub_f32_e32 v48, v84, v102
	v_sub_f32_e32 v51, v87, v102
	v_sub_f32_e32 v50, v86, v102
	v_pk_mul_f32 v[50:51], v[102:103], v[50:51] op_sel:[1,0]
	v_pk_mul_f32 v[48:49], v[102:103], v[48:49] op_sel:[1,0]
	v_pk_fma_f32 v[46:47], v[96:97], v[50:51], v[46:47]
	v_pk_fma_f32 v[44:45], v[98:99], v[48:49], v[44:45]
	v_pk_fma_f32 v[46:47], v[70:71], s[78:79], v[46:47] op_sel_hi:[1,0,1]
	v_pk_fma_f32 v[44:45], v[68:69], s[78:79], v[44:45] op_sel_hi:[1,0,1]
	v_lshl_add_u64 v[48:49], v[158:159], 2, s[88:89]
	global_store_dwordx4 v[48:49], v[44:47], off
	v_add_u32_e32 v158, 0x10090, v148
	s_nop 0
	v_sub_f32_e32 v45, v81, v102
	v_sub_f32_e32 v44, v80, v102
	v_sub_f32_e32 v47, v83, v102
	v_sub_f32_e32 v46, v82, v102
	v_pk_mul_f32 v[46:47], v[102:103], v[46:47] op_sel:[1,0]
	v_pk_mul_f32 v[44:45], v[102:103], v[44:45] op_sel:[1,0]
	v_pk_fma_f32 v[42:43], v[92:93], v[46:47], v[42:43]
	v_pk_fma_f32 v[40:41], v[94:95], v[44:45], v[40:41]
	v_pk_fma_f32 v[42:43], v[66:67], s[78:79], v[42:43] op_sel_hi:[1,0,1]
	v_pk_fma_f32 v[40:41], v[64:65], s[78:79], v[40:41] op_sel_hi:[1,0,1]
	v_lshl_add_u64 v[44:45], v[158:159], 2, s[88:89]
	global_store_dwordx4 v[44:45], v[40:43], off
	v_add_u32_e32 v158, 0x18080, v148
	s_nop 0
	v_sub_f32_e32 v41, v77, v100
	v_sub_f32_e32 v40, v76, v100
	v_sub_f32_e32 v43, v79, v100
	v_sub_f32_e32 v42, v78, v100
	v_pk_mul_f32 v[42:43], v[100:101], v[42:43] op_sel:[1,0]
	v_pk_mul_f32 v[40:41], v[100:101], v[40:41] op_sel:[1,0]
	v_pk_fma_f32 v[38:39], v[96:97], v[42:43], v[38:39]
;     template <bool LN, int BJ, int LO, int HI> DI void batch(const f32x4 (&acc)[2][2][4][2], unsigned row0, unsigned col0, const f32x4 (&gv)[2], const f32x4 (&bv)[2]) const {
;     ...
;         for (int i = LO; i < HI; ++i) { const int ai = i >> 3, m = (i >> 1) & 3, n = i & 1; const unsigned row = row0 + ai * HALF + m * 16;
;             if (n == 0) { mean[(i - LO) >> 1] = 0.f; rstd[(i - LO) >> 1] = 1.f;
;                 if (LN) { const float2 st = *(const float2*)(stats + row * 2u); mean[(i - LO) >> 1] = st.x; rstd[(i - LO) >> 1] = st.y; } }
;             r[i - LO] = *(const f32x4*)(src + (row * (unsigned)DM + col0 + BJ * HALF + n * 16)); }
; #pragma unroll
;         for (int i = LO; i < HI; ++i) { const int ai = i >> 3, m = (i >> 1) & 3, n = i & 1; const unsigned row = row0 + ai * HALF + m * 16;
;             *(f32x4*)(Y + (row * (unsigned)DM + col0 + BJ * HALF + n * 16)) = acc[ai][BJ][m][n] + ((r[i - LO] - mean[(i - LO) >> 1]) * rstd[(i - LO) >> 1]) * gv[n] + bv[n]; }
	v_pk_fma_f32 v[36:37], v[98:99], v[40:41], v[36:37]
	v_pk_fma_f32 v[38:39], v[70:71], s[78:79], v[38:39] op_sel_hi:[1,0,1]
	v_pk_fma_f32 v[36:37], v[68:69], s[78:79], v[36:37] op_sel_hi:[1,0,1]
	v_lshl_add_u64 v[40:41], v[158:159], 2, s[88:89]
	global_store_dwordx4 v[40:41], v[36:39], off
	v_add_u32_e32 v158, 0x18090, v148
	s_nop 0
	v_sub_f32_e32 v37, v73, v100
	v_sub_f32_e32 v36, v72, v100
	v_sub_f32_e32 v39, v75, v100
	v_sub_f32_e32 v38, v74, v100
	v_pk_mul_f32 v[38:39], v[100:101], v[38:39] op_sel:[1,0]
	v_pk_mul_f32 v[36:37], v[100:101], v[36:37] op_sel:[1,0]
	v_pk_fma_f32 v[34:35], v[92:93], v[38:39], v[34:35]
	v_pk_fma_f32 v[32:33], v[94:95], v[36:37], v[32:33]
	v_pk_fma_f32 v[34:35], v[66:67], s[78:79], v[34:35] op_sel_hi:[1,0,1]
	v_pk_fma_f32 v[32:33], v[64:65], s[78:79], v[32:33] op_sel_hi:[1,0,1]
	v_lshl_add_u64 v[36:37], v[158:159], 2, s[88:89]
	global_store_dwordx4 v[36:37], v[32:35], off
	v_add_u32_e32 v158, v114, v119
	s_nop 0
	v_lshl_add_u64 v[32:33], v[158:159], 2, s[90:91]
	global_load_dwordx2 v[62:63], v[104:105], off
	global_load_dwordx4 v[54:57], v[32:33], off
	v_add_u32_e32 v158, v114, v118
	v_lshl_add_u64 v[32:33], v[158:159], 2, s[90:91]
	global_load_dwordx4 v[58:61], v[32:33], off
	global_load_dwordx2 v[52:53], v[106:107], off
	v_add_u32_e32 v158, v115, v119
	v_lshl_add_u64 v[32:33], v[158:159], 2, s[90:91]
	global_load_dwordx4 v[72:75], v[32:33], off
	v_add_u32_e32 v158, v115, v118
	v_lshl_add_u64 v[32:33], v[158:159], 2, s[90:91]
	global_load_dwordx4 v[76:79], v[32:33], off
	global_load_dwordx2 v[50:51], v[108:109], off
	v_add_u32_e32 v158, v116, v119
	v_lshl_add_u64 v[32:33], v[158:159], 2, s[90:91]
	global_load_dwordx4 v[44:47], v[32:33], off
	v_add_u32_e32 v158, v116, v118
	v_lshl_add_u64 v[32:33], v[158:159], 2, s[90:91]
	global_load_dwordx4 v[40:43], v[32:33], off
	global_load_dwordx2 v[48:49], v[110:111], off
	v_add_u32_e32 v158, v117, v119
	v_lshl_add_u64 v[32:33], v[158:159], 2, s[90:91]
	global_load_dwordx4 v[36:39], v[32:33], off
	v_add_u32_e32 v158, v117, v118
	v_lshl_add_u64 v[32:33], v[158:159], 2, s[90:91]
	global_load_dwordx4 v[32:35], v[32:33], off
	v_add_u32_e32 v158, 0x40080, v148
	s_waitcnt vmcnt(0)
; #define PG8_WAIT_V(n) asm volatile("s_waitcnt vmcnt(" #n ")" ::: "memory")
; #define PG8_BAR __builtin_amdgcn_s_barrier()
; template <class Epi>
; DI void gemm_phase(LAS unsigned char* lds, const Gemm g, const StaticOrder& S, const Epi& E) {
;     ...
;         E(acc, cur, wr, wc, fr, fq);
;         if (!has_next) break;
; #pragma unroll
;         for (int a = 0; a < 2; ++a)
; #pragma unroll
;             for (int b = 0; b < 2; ++b)
; #pragma unroll
;                 for (int m = 0; m < 4; ++m)
; #pragma unroll
;                     for (int n = 0; n < 2; ++n) acc[a][b][m][n] = (f32x4){0.f, 0.f, 0.f, 0.f};
;         cur = nxt; cA = nA; cB = nB; ++ui;
;     }
;     PG8_WAIT_V(0);
;     if (wr == 0) PG8_BAR;
;     PG8_BAR;
;     template <bool LN, int BJ, int LO, int HI> DI void batch(const f32x4 (&acc)[2][2][4][2], unsigned row0, unsigned col0, const f32x4 (&gv)[2], const f32x4 (&bv)[2]) const {
;     ...
;         for (int i = LO; i < HI; ++i) { const int ai = i >> 3, m = (i >> 1) & 3, n = i & 1; const unsigned row = row0 + ai * HALF + m * 16;
;             if (n == 0) { mean[(i - LO) >> 1] = 0.f; rstd[(i - LO) >> 1] = 1.f;
;                 if (LN) { const float2 st = *(const float2*)(stats + row * 2u); mean[(i - LO) >> 1] = st.x; rstd[(i - LO) >> 1] = st.y; } }
;             r[i - LO] = *(const f32x4*)(src + (row * (unsigned)DM + col0 + BJ * HALF + n * 16)); }
; #pragma unroll
;         for (int i = LO; i < HI; ++i) { const int ai = i >> 3, m = (i >> 1) & 3, n = i & 1; const unsigned row = row0 + ai * HALF + m * 16;
;             *(f32x4*)(Y + (row * (unsigned)DM + col0 + BJ * HALF + n * 16)) = acc[ai][BJ][m][n] + ((r[i - LO] - mean[(i - LO) >> 1]) * rstd[(i - LO) >> 1]) * gv[n] + bv[n]; }
	v_sub_f32_e32 v55, v55, v62
	v_sub_f32_e32 v54, v54, v62
	v_sub_f32_e32 v57, v57, v62
	v_sub_f32_e32 v56, v56, v62
	v_pk_mul_f32 v[56:57], v[62:63], v[56:57] op_sel:[1,0]
	v_pk_mul_f32 v[54:55], v[62:63], v[54:55] op_sel:[1,0]
	v_pk_fma_f32 v[30:31], v[96:97], v[56:57], v[30:31]
	v_pk_fma_f32 v[28:29], v[98:99], v[54:55], v[28:29]
	v_pk_fma_f32 v[30:31], v[70:71], s[78:79], v[30:31] op_sel_hi:[1,0,1]
	v_pk_fma_f32 v[28:29], v[68:69], s[78:79], v[28:29] op_sel_hi:[1,0,1]
	v_lshl_add_u64 v[54:55], v[158:159], 2, s[88:89]
	global_store_dwordx4 v[54:55], v[28:31], off
	v_add_u32_e32 v158, 0x40090, v148
	s_nop 0
	v_sub_f32_e32 v29, v59, v62
	v_sub_f32_e32 v28, v58, v62
	v_sub_f32_e32 v31, v61, v62
	v_sub_f32_e32 v30, v60, v62
	v_pk_mul_f32 v[30:31], v[62:63], v[30:31] op_sel:[1,0]
	v_pk_mul_f32 v[28:29], v[62:63], v[28:29] op_sel:[1,0]
	v_pk_fma_f32 v[26:27], v[92:93], v[30:31], v[26:27]
	v_pk_fma_f32 v[24:25], v[94:95], v[28:29], v[24:25]
	v_pk_fma_f32 v[26:27], v[66:67], s[78:79], v[26:27] op_sel_hi:[1,0,1]
	v_pk_fma_f32 v[24:25], v[64:65], s[78:79], v[24:25] op_sel_hi:[1,0,1]
	v_lshl_add_u64 v[28:29], v[158:159], 2, s[88:89]
	global_store_dwordx4 v[28:29], v[24:27], off
	v_add_u32_e32 v158, 0x48080, v148
	s_nop 0
	v_sub_f32_e32 v25, v73, v52
	v_sub_f32_e32 v24, v72, v52
	v_sub_f32_e32 v27, v75, v52
	v_sub_f32_e32 v26, v74, v52
	v_pk_mul_f32 v[26:27], v[52:53], v[26:27] op_sel:[1,0]
	v_pk_mul_f32 v[24:25], v[52:53], v[24:25] op_sel:[1,0]
	v_pk_fma_f32 v[22:23], v[96:97], v[26:27], v[22:23]
	v_pk_fma_f32 v[20:21], v[98:99], v[24:25], v[20:21]
	v_pk_fma_f32 v[22:23], v[70:71], s[78:79], v[22:23] op_sel_hi:[1,0,1]
	v_pk_fma_f32 v[20:21], v[68:69], s[78:79], v[20:21] op_sel_hi:[1,0,1]
	v_lshl_add_u64 v[24:25], v[158:159], 2, s[88:89]
	global_store_dwordx4 v[24:25], v[20:23], off
	v_add_u32_e32 v158, 0x48090, v148
	s_nop 0
	v_sub_f32_e32 v21, v77, v52
	v_sub_f32_e32 v20, v76, v52
	v_sub_f32_e32 v23, v79, v52
	v_sub_f32_e32 v22, v78, v52
	v_pk_mul_f32 v[22:23], v[52:53], v[22:23] op_sel:[1,0]
	v_pk_mul_f32 v[20:21], v[52:53], v[20:21] op_sel:[1,0]
	v_pk_fma_f32 v[18:19], v[92:93], v[22:23], v[18:19]
	v_pk_fma_f32 v[16:17], v[94:95], v[20:21], v[16:17]
	v_pk_fma_f32 v[18:19], v[66:67], s[78:79], v[18:19] op_sel_hi:[1,0,1]
	v_pk_fma_f32 v[16:17], v[64:65], s[78:79], v[16:17] op_sel_hi:[1,0,1]
	v_lshl_add_u64 v[20:21], v[158:159], 2, s[88:89]
	global_store_dwordx4 v[20:21], v[16:19], off
	v_add_u32_e32 v158, 0x50080, v148
	s_nop 0
	v_sub_f32_e32 v17, v45, v50
	v_sub_f32_e32 v16, v44, v50
	v_sub_f32_e32 v19, v47, v50
	v_sub_f32_e32 v18, v46, v50
	v_pk_mul_f32 v[18:19], v[50:51], v[18:19] op_sel:[1,0]
	v_pk_mul_f32 v[16:17], v[50:51], v[16:17] op_sel:[1,0]
	v_pk_fma_f32 v[14:15], v[96:97], v[18:19], v[14:15]
	v_pk_fma_f32 v[12:13], v[98:99], v[16:17], v[12:13]
	v_pk_fma_f32 v[14:15], v[70:71], s[78:79], v[14:15] op_sel_hi:[1,0,1]
	v_pk_fma_f32 v[12:13], v[68:69], s[78:79], v[12:13] op_sel_hi:[1,0,1]
	v_lshl_add_u64 v[16:17], v[158:159], 2, s[88:89]
	global_store_dwordx4 v[16:17], v[12:15], off
	v_add_u32_e32 v158, 0x50090, v148
	s_nop 0
	v_sub_f32_e32 v13, v41, v50
	v_sub_f32_e32 v12, v40, v50
	v_sub_f32_e32 v15, v43, v50
	v_sub_f32_e32 v14, v42, v50
	v_pk_mul_f32 v[14:15], v[50:51], v[14:15] op_sel:[1,0]
	v_pk_mul_f32 v[12:13], v[50:51], v[12:13] op_sel:[1,0]
	v_pk_fma_f32 v[10:11], v[92:93], v[14:15], v[10:11]
	v_pk_fma_f32 v[8:9], v[94:95], v[12:13], v[8:9]
	v_pk_fma_f32 v[10:11], v[66:67], s[78:79], v[10:11] op_sel_hi:[1,0,1]
	v_pk_fma_f32 v[8:9], v[64:65], s[78:79], v[8:9] op_sel_hi:[1,0,1]
	v_lshl_add_u64 v[12:13], v[158:159], 2, s[88:89]
	global_store_dwordx4 v[12:13], v[8:11], off
	v_add_u32_e32 v158, 0x58080, v148
	s_nop 0
	v_sub_f32_e32 v9, v37, v48
	v_sub_f32_e32 v8, v36, v48
	v_sub_f32_e32 v11, v39, v48
	v_sub_f32_e32 v10, v38, v48
	v_pk_mul_f32 v[10:11], v[48:49], v[10:11] op_sel:[1,0]
	v_pk_mul_f32 v[8:9], v[48:49], v[8:9] op_sel:[1,0]
	v_pk_fma_f32 v[6:7], v[96:97], v[10:11], v[6:7]
	v_pk_fma_f32 v[4:5], v[98:99], v[8:9], v[4:5]
	v_pk_fma_f32 v[6:7], v[70:71], s[78:79], v[6:7] op_sel_hi:[1,0,1]
	v_pk_fma_f32 v[4:5], v[68:69], s[78:79], v[4:5] op_sel_hi:[1,0,1]
	v_lshl_add_u64 v[8:9], v[158:159], 2, s[88:89]
	global_store_dwordx4 v[8:9], v[4:7], off
	v_add_u32_e32 v158, 0x58090, v148
	s_nop 0
	v_sub_f32_e32 v5, v33, v48
	v_sub_f32_e32 v4, v32, v48
	v_sub_f32_e32 v7, v35, v48
	v_sub_f32_e32 v6, v34, v48
	v_pk_mul_f32 v[6:7], v[48:49], v[6:7] op_sel:[1,0]
	v_pk_mul_f32 v[4:5], v[48:49], v[4:5] op_sel:[1,0]
	v_pk_fma_f32 v[2:3], v[92:93], v[6:7], v[2:3]
	v_pk_fma_f32 v[0:1], v[94:95], v[4:5], v[0:1]
	v_pk_fma_f32 v[2:3], v[66:67], s[78:79], v[2:3] op_sel_hi:[1,0,1]
	v_pk_fma_f32 v[0:1], v[64:65], s[78:79], v[0:1] op_sel_hi:[1,0,1]
	v_lshl_add_u64 v[4:5], v[158:159], 2, s[88:89]
	global_store_dwordx4 v[4:5], v[0:3], off
	s_and_b64 vcc, exec, s[6:7]
	s_mov_b32 s2, s37
	s_mov_b32 s3, s38
	s_mov_b64 s[18:19], s[10:11]
	s_mov_b64 s[16:17], s[8:9]
	v_readlane_b32 s33, v255, 39
	s_cbranch_vccz .LBB0_123
	s_waitcnt vmcnt(0)
	s_cmpk_gt_u32 s24, 0xff
	s_cbranch_scc1 .LBB0_138
	s_barrier

; #define PG8_STAGE(bufoff, gbase) do { _Pragma("unroll") for (int _i = 0; _i < 2; ++_i) \
;         __builtin_amdgcn_global_load_lds((const unsigned*)((const char*)(gbase) + voff[_i]), (LAS unsigned*)(lds + (bufoff) + ldsw + _i * 8192), 16, 0, 0); } while (0)
; #define PG8_LDA(dst, b, h) do { _Pragma("unroll") for (int m = 0; m < 4; ++m) _Pragma("unroll") for (int k = 0; k < 2; ++k) dst[m][k] = *(const LAS bf16x8*)(lds + PG8_SA(b, h) + aoff + m * 2048 + k * 1024); } while (0)
; #define PG8_LDB(dst, b, h) do { _Pragma("unroll") for (int n = 0; n < 2; ++n) _Pragma("unroll") for (int k = 0; k < 2; ++k) dst[n][k] = *(const LAS bf16x8*)(lds + PG8_SB(b, h) + boff + n * 2048 + k * 1024); } while (0)
; #define PG8_MMA(ai, bj, At, Bt) do { __builtin_amdgcn_s_setprio(1); _Pragma("unroll") for (int m = 0; m < 4; ++m) _Pragma("unroll") for (int n = 0; n < 2; ++n) _Pragma("unroll") for (int k = 0; k < 2; ++k) \
;         acc[ai][bj][m][n] = __builtin_amdgcn_mfma_f32_16x16x32_bf16(Bt[n][k], At[m][k], acc[ai][bj][m][n], 0, 0, 0); __builtin_amdgcn_s_setprio(0); } while (0)
; #define PG8_WAIT_V(n) asm volatile("s_waitcnt vmcnt(" #n ")" ::: "memory")
; #define PG8_WAIT_L(n) asm volatile("s_waitcnt lgkmcnt(" #n ")" ::: "memory")
; #define PG8_BAR __builtin_amdgcn_s_barrier()
; #define PG8_SCHED __builtin_amdgcn_sched_barrier(0)
; template <class Epi>
; DI void gemm_phase(LAS unsigned char* lds, const Gemm g, const StaticOrder& S, const Epi& E) {
;     ...
;         for (int t = 0; t < nt; t += 2) {
;             const bool last = (t == nt - 2);
;             const char* a1 = cA + (size_t)(t + 1) * kstep;
;             const char* a2 = last ? nA : cA + (size_t)(t + 2) * kstep; const char* b2 = last ? nB : cB + (size_t)(t + 2) * kstep;
;             const char* a3 = a2 + kstep; const char* b3 = b2 + kstep;
;             PG8_LDB(B0, 0, 0); PG8_SCHED; PG8_LDA(At, 0, 0); PG8_STAGE(PG8_SA(1, 1), a1 + hstep);
;             PG8_WAIT_L(8); PG8_BAR; PG8_WAIT_L(0); PG8_MMA(0, 0, At, B0); PG8_BAR; PG8_SCHED;
;             PG8_LDB(B1, 0, 1); PG8_STAGE(PG8_SB(0, 0), b2);
;             PG8_BAR; PG8_WAIT_L(0); PG8_MMA(0, 1, At, B1); PG8_BAR;
;             PG8_LDA(At, 0, 1); PG8_STAGE(PG8_SA(0, 0), a2);
;             PG8_BAR; PG8_WAIT_L(0); PG8_MMA(1, 0, At, B0); PG8_BAR; PG8_SCHED;
;             PG8_STAGE(PG8_SB(0, 1), b2 + hstep);
;             PG8_WAIT_V(6); PG8_BAR; PG8_MMA(1, 1, At, B1); PG8_BAR;
.LBB0_202:
	s_add_u32 s18, s8, 0xfff80080
	s_addc_u32 s19, s9, -1
	s_add_i32 s37, 0, 0x10000
	v_add_u32_e32 v140, s37, v187
	s_waitcnt lgkmcnt(0)
	ds_read_b128 v[128:131], v140
	ds_read_b128 v[132:135], v140 offset:1024
	ds_read_b128 v[136:139], v140 offset:2048
	ds_read_b128 v[190:193], v140 offset:3072
	s_cmp_eq_u32 s36, 28
	s_cselect_b32 s21, s4, s19
	s_cselect_b32 s20, s5, s18
	s_cselect_b32 s19, s11, s35
	s_cselect_b32 s18, s13, s33
	v_lshl_add_u64 v[140:141], s[8:9], 0, v[150:151]
	s_add_i32 m0, s26, 0xc000
	ds_read_b128 v[194:197], v189
	ds_read_b128 v[198:201], v189 offset:1024
	ds_read_b128 v[202:205], v189 offset:2048
	ds_read_b128 v[206:209], v189 offset:3072
	ds_read_b128 v[210:213], v189 offset:4096
	ds_read_b128 v[214:217], v189 offset:5120
	ds_read_b128 v[226:229], v189 offset:6144
	ds_read_b128 v[230:233], v189 offset:7168
	global_load_lds_dwordx4 v[140:141], off
	v_lshl_add_u64 v[140:141], s[8:9], 0, v[152:153]
	s_add_i32 m0, s26, 0xe000
	s_nop 0
	global_load_lds_dwordx4 v[140:141], off
	s_waitcnt lgkmcnt(8)
	s_setprio 1
	s_barrier
	s_waitcnt lgkmcnt(0)
	v_mfma_f32_16x16x32_bf16 v[124:127], v[128:131], v[194:197], v[124:127]
	v_mfma_f32_16x16x32_bf16 v[120:123], v[136:139], v[194:197], v[120:123]
	v_mfma_f32_16x16x32_bf16 v[108:111], v[128:131], v[202:205], v[108:111]
	v_mfma_f32_16x16x32_bf16 v[104:107], v[136:139], v[202:205], v[104:107]
	v_mfma_f32_16x16x32_bf16 v[92:95], v[128:131], v[210:213], v[92:95]
	v_mfma_f32_16x16x32_bf16 v[88:91], v[136:139], v[210:213], v[88:91]
	v_mfma_f32_16x16x32_bf16 v[76:79], v[128:131], v[226:229], v[76:79]
	v_mfma_f32_16x16x32_bf16 v[72:75], v[136:139], v[226:229], v[72:75]
	v_mfma_f32_16x16x32_bf16 v[124:127], v[132:135], v[198:201], v[124:127]
	v_mfma_f32_16x16x32_bf16 v[120:123], v[190:193], v[198:201], v[120:123]
	v_mfma_f32_16x16x32_bf16 v[108:111], v[132:135], v[206:209], v[108:111]
	v_mfma_f32_16x16x32_bf16 v[104:107], v[190:193], v[206:209], v[104:107]
	v_mfma_f32_16x16x32_bf16 v[92:95], v[132:135], v[214:217], v[92:95]
	v_mfma_f32_16x16x32_bf16 v[88:91], v[190:193], v[214:217], v[88:91]
	v_mfma_f32_16x16x32_bf16 v[76:79], v[132:135], v[230:233], v[76:79]
	v_mfma_f32_16x16x32_bf16 v[72:75], v[190:193], v[230:233], v[72:75]
	s_setprio 0
	s_barrier
	s_add_i32 s40, 0, 0x14000
	v_add_u32_e32 v140, s40, v187
	s_add_i32 s37, s37, s25
	ds_read_b128 v[234:237], v140
	ds_read_b128 v[238:241], v140 offset:1024
	ds_read_b128 v[242:245], v140 offset:2048
	ds_read_b128 v[246:249], v140 offset:3072
	v_lshl_add_u64 v[140:141], s[18:19], 0, v[144:145]
	s_mov_b32 m0, s37
	v_lshl_add_u64 v[154:155], s[18:19], 0, v[142:143]
	global_load_lds_dwordx4 v[140:141], off
	s_add_i32 m0, s37, 0x2000
	s_nop 0
	global_load_lds_dwordx4 v[154:155], off
	s_waitcnt lgkmcnt(0)
	s_setprio 1
	s_barrier
	v_mfma_f32_16x16x32_bf16 v[116:119], v[234:237], v[194:197], v[116:119]
	v_mfma_f32_16x16x32_bf16 v[112:115], v[242:245], v[194:197], v[112:115]
	v_mfma_f32_16x16x32_bf16 v[100:103], v[234:237], v[202:205], v[100:103]
	v_mfma_f32_16x16x32_bf16 v[96:99], v[242:245], v[202:205], v[96:99]
	v_mfma_f32_16x16x32_bf16 v[84:87], v[234:237], v[210:213], v[84:87]
	v_mfma_f32_16x16x32_bf16 v[80:83], v[242:245], v[210:213], v[80:83]
	v_mfma_f32_16x16x32_bf16 v[68:71], v[234:237], v[226:229], v[68:71]
	v_mfma_f32_16x16x32_bf16 v[64:67], v[242:245], v[226:229], v[64:67]
	v_mfma_f32_16x16x32_bf16 v[116:119], v[238:241], v[198:201], v[116:119]
	s_mov_b32 m0, s26
	v_mfma_f32_16x16x32_bf16 v[112:115], v[246:249], v[198:201], v[112:115]
	v_lshl_add_u64 v[218:219], s[20:21], 0, v[144:145]
	v_mfma_f32_16x16x32_bf16 v[100:103], v[238:241], v[206:209], v[100:103]
	v_mfma_f32_16x16x32_bf16 v[96:99], v[246:249], v[206:209], v[96:99]
	v_mfma_f32_16x16x32_bf16 v[84:87], v[238:241], v[214:217], v[84:87]
	v_mfma_f32_16x16x32_bf16 v[80:83], v[246:249], v[214:217], v[80:83]
	v_mfma_f32_16x16x32_bf16 v[68:71], v[238:241], v[230:233], v[68:71]
	v_mfma_f32_16x16x32_bf16 v[64:67], v[246:249], v[230:233], v[64:67]
	s_setprio 0
	s_barrier
	ds_read_b128 v[194:197], v189 offset:16384
	ds_read_b128 v[198:201], v189 offset:17408
	ds_read_b128 v[202:205], v189 offset:18432
	ds_read_b128 v[206:209], v189 offset:19456
	ds_read_b128 v[210:213], v189 offset:20480
	ds_read_b128 v[214:217], v189 offset:21504
	ds_read_b128 v[226:229], v189 offset:22528
	ds_read_b128 v[230:233], v189 offset:23552
	global_load_lds_dwordx4 v[218:219], off
	v_lshl_add_u64 v[250:251], s[20:21], 0, v[142:143]
	s_mov_b32 m0, s27
	s_nop 0
	global_load_lds_dwordx4 v[250:251], off
	s_waitcnt lgkmcnt(0)
	s_setprio 1
	s_barrier
	v_mfma_f32_16x16x32_bf16 v[60:63], v[128:131], v[194:197], v[60:63]
	v_mfma_f32_16x16x32_bf16 v[56:59], v[136:139], v[194:197], v[56:59]
	v_mfma_f32_16x16x32_bf16 v[44:47], v[128:131], v[202:205], v[44:47]
	v_mfma_f32_16x16x32_bf16 v[40:43], v[136:139], v[202:205], v[40:43]
	v_mfma_f32_16x16x32_bf16 v[28:31], v[128:131], v[210:213], v[28:31]
	v_mfma_f32_16x16x32_bf16 v[24:27], v[136:139], v[210:213], v[24:27]
	v_mfma_f32_16x16x32_bf16 v[12:15], v[128:131], v[226:229], v[12:15]
	v_mfma_f32_16x16x32_bf16 v[8:11], v[136:139], v[226:229], v[8:11]
	v_mfma_f32_16x16x32_bf16 v[60:63], v[132:135], v[198:201], v[60:63]
	v_mfma_f32_16x16x32_bf16 v[56:59], v[190:193], v[198:201], v[56:59]
	v_mfma_f32_16x16x32_bf16 v[44:47], v[132:135], v[206:209], v[44:47]
	v_mfma_f32_16x16x32_bf16 v[40:43], v[190:193], v[206:209], v[40:43]
	v_mfma_f32_16x16x32_bf16 v[28:31], v[132:135], v[214:217], v[28:31]
	v_mfma_f32_16x16x32_bf16 v[24:27], v[190:193], v[214:217], v[24:27]
	v_mfma_f32_16x16x32_bf16 v[12:15], v[132:135], v[230:233], v[12:15]
	v_mfma_f32_16x16x32_bf16 v[8:11], v[190:193], v[230:233], v[8:11]
	s_setprio 0
	s_barrier
; #define PG8_STAGE(bufoff, gbase) do { _Pragma("unroll") for (int _i = 0; _i < 2; ++_i) \
;         __builtin_amdgcn_global_load_lds((const unsigned*)((const char*)(gbase) + voff[_i]), (LAS unsigned*)(lds + (bufoff) + ldsw + _i * 8192), 16, 0, 0); } while (0)
; #define PG8_LDA(dst, b, h) do { _Pragma("unroll") for (int m = 0; m < 4; ++m) _Pragma("unroll") for (int k = 0; k < 2; ++k) dst[m][k] = *(const LAS bf16x8*)(lds + PG8_SA(b, h) + aoff + m * 2048 + k * 1024); } while (0)
; #define PG8_LDB(dst, b, h) do { _Pragma("unroll") for (int n = 0; n < 2; ++n) _Pragma("unroll") for (int k = 0; k < 2; ++k) dst[n][k] = *(const LAS bf16x8*)(lds + PG8_SB(b, h) + boff + n * 2048 + k * 1024); } while (0)
; #define PG8_MMA(ai, bj, At, Bt) do { __builtin_amdgcn_s_setprio(1); _Pragma("unroll") for (int m = 0; m < 4; ++m) _Pragma("unroll") for (int n = 0; n < 2; ++n) _Pragma("unroll") for (int k = 0; k < 2; ++k) \
;         acc[ai][bj][m][n] = __builtin_amdgcn_mfma_f32_16x16x32_bf16(Bt[n][k], At[m][k], acc[ai][bj][m][n], 0, 0, 0); __builtin_amdgcn_s_setprio(0); } while (0)
; #define PG8_WAIT_V(n) asm volatile("s_waitcnt vmcnt(" #n ")" ::: "memory")
; #define PG8_WAIT_L(n) asm volatile("s_waitcnt lgkmcnt(" #n ")" ::: "memory")
; #define PG8_BAR __builtin_amdgcn_s_barrier()
; #define PG8_SCHED __builtin_amdgcn_sched_barrier(0)
; template <class Epi>
; DI void gemm_phase(LAS unsigned char* lds, const Gemm g, const StaticOrder& S, const Epi& E) {
;     ...
;             PG8_STAGE(PG8_SB(0, 1), b2 + hstep);
;             PG8_WAIT_V(6); PG8_BAR; PG8_MMA(1, 1, At, B1); PG8_BAR;
;             PG8_LDB(B0, 1, 0); PG8_SCHED; PG8_LDA(At, 1, 0); PG8_STAGE(PG8_SA(0, 1), a2 + hstep);
;             PG8_WAIT_L(8); PG8_BAR; PG8_WAIT_L(0); PG8_MMA(0, 0, At, B0); PG8_BAR; PG8_SCHED;
;             PG8_LDB(B1, 1, 1); PG8_STAGE(PG8_SB(1, 0), b3);
;             PG8_BAR; PG8_WAIT_L(0); PG8_MMA(0, 1, At, B1); PG8_BAR;
;             PG8_LDA(At, 1, 1); PG8_STAGE(PG8_SA(1, 0), a3);
;             PG8_BAR; PG8_WAIT_L(0); PG8_MMA(1, 0, At, B0); PG8_BAR; PG8_SCHED;
	s_add_u32 s38, s18, 0x80000
	s_addc_u32 s39, s19, 0
	s_add_i32 s37, s40, s25
	v_lshl_add_u64 v[128:129], s[38:39], 0, v[144:145]
	s_mov_b32 m0, s37
	s_nop 0
	global_load_lds_dwordx4 v[128:129], off
	v_lshl_add_u64 v[128:129], s[38:39], 0, v[142:143]
	s_add_i32 m0, s37, 0x2000
	s_nop 0
	global_load_lds_dwordx4 v[128:129], off
	s_waitcnt vmcnt(6)
	s_setprio 1
	s_barrier
	v_mfma_f32_16x16x32_bf16 v[52:55], v[234:237], v[194:197], v[52:55]
	v_mfma_f32_16x16x32_bf16 v[48:51], v[242:245], v[194:197], v[48:51]
	v_mfma_f32_16x16x32_bf16 v[36:39], v[234:237], v[202:205], v[36:39]
	v_mfma_f32_16x16x32_bf16 v[32:35], v[242:245], v[202:205], v[32:35]
	v_mfma_f32_16x16x32_bf16 v[20:23], v[234:237], v[210:213], v[20:23]
	v_mfma_f32_16x16x32_bf16 v[16:19], v[242:245], v[210:213], v[16:19]
	v_mfma_f32_16x16x32_bf16 v[4:7], v[234:237], v[226:229], v[4:7]
	v_mfma_f32_16x16x32_bf16 v[0:3], v[242:245], v[226:229], v[0:3]
	v_mfma_f32_16x16x32_bf16 v[52:55], v[238:241], v[198:201], v[52:55]
	s_add_i32 s37, 0, 0x18000
	v_mfma_f32_16x16x32_bf16 v[48:51], v[246:249], v[198:201], v[48:51]
	v_add_u32_e32 v158, s37, v187
	v_mfma_f32_16x16x32_bf16 v[36:39], v[238:241], v[206:209], v[36:39]
	v_mfma_f32_16x16x32_bf16 v[32:35], v[246:249], v[206:209], v[32:35]
	v_mfma_f32_16x16x32_bf16 v[20:23], v[238:241], v[214:217], v[20:23]
	v_mfma_f32_16x16x32_bf16 v[16:19], v[246:249], v[214:217], v[16:19]
	v_mfma_f32_16x16x32_bf16 v[4:7], v[238:241], v[230:233], v[4:7]
	v_mfma_f32_16x16x32_bf16 v[0:3], v[246:249], v[230:233], v[0:3]
	s_setprio 0
	s_barrier
	ds_read_b128 v[128:131], v158
	ds_read_b128 v[132:135], v158 offset:1024
	ds_read_b128 v[136:139], v158 offset:2048
	ds_read_b128 v[190:193], v158 offset:3072
	s_add_u32 s20, s20, 0x80000
	s_addc_u32 s21, s21, 0
	s_mov_b32 m0, s28
	v_lshl_add_u64 v[234:235], s[20:21], 0, v[144:145]
	ds_read_b128 v[194:197], v189 offset:32768
	ds_read_b128 v[198:201], v189 offset:33792
	ds_read_b128 v[202:205], v189 offset:34816
	ds_read_b128 v[206:209], v189 offset:35840
	ds_read_b128 v[210:213], v189 offset:36864
	ds_read_b128 v[214:217], v189 offset:37888
	ds_read_b128 v[226:229], v189 offset:38912
	ds_read_b128 v[230:233], v189 offset:39936
	global_load_lds_dwordx4 v[234:235], off
	v_lshl_add_u64 v[234:235], s[20:21], 0, v[142:143]
	s_mov_b32 m0, s29
	s_nop 0
	global_load_lds_dwordx4 v[234:235], off
	s_waitcnt lgkmcnt(8)
	s_setprio 1
	s_barrier
	s_waitcnt lgkmcnt(0)
	v_mfma_f32_16x16x32_bf16 v[124:127], v[128:131], v[194:197], v[124:127]
	v_mfma_f32_16x16x32_bf16 v[120:123], v[136:139], v[194:197], v[120:123]
	v_mfma_f32_16x16x32_bf16 v[108:111], v[128:131], v[202:205], v[108:111]
	v_mfma_f32_16x16x32_bf16 v[104:107], v[136:139], v[202:205], v[104:107]
	v_mfma_f32_16x16x32_bf16 v[92:95], v[128:131], v[210:213], v[92:95]
	v_mfma_f32_16x16x32_bf16 v[88:91], v[136:139], v[210:213], v[88:91]
	v_mfma_f32_16x16x32_bf16 v[76:79], v[128:131], v[226:229], v[76:79]
	v_mfma_f32_16x16x32_bf16 v[72:75], v[136:139], v[226:229], v[72:75]
	v_mfma_f32_16x16x32_bf16 v[124:127], v[132:135], v[198:201], v[124:127]
	v_mfma_f32_16x16x32_bf16 v[120:123], v[190:193], v[198:201], v[120:123]
	v_mfma_f32_16x16x32_bf16 v[108:111], v[132:135], v[206:209], v[108:111]
	v_mfma_f32_16x16x32_bf16 v[104:107], v[190:193], v[206:209], v[104:107]
	v_mfma_f32_16x16x32_bf16 v[92:95], v[132:135], v[214:217], v[92:95]
	v_mfma_f32_16x16x32_bf16 v[88:91], v[190:193], v[214:217], v[88:91]
	v_mfma_f32_16x16x32_bf16 v[76:79], v[132:135], v[230:233], v[76:79]
	v_mfma_f32_16x16x32_bf16 v[72:75], v[190:193], v[230:233], v[72:75]
	s_setprio 0
	s_barrier
	s_add_i32 s20, 0, 0x1c000
	s_add_i32 s21, s37, s25
	v_add_u32_e32 v158, s20, v187
	v_lshl_add_u64 v[140:141], v[140:141], 0, s[94:95]
	s_mov_b32 m0, s21
	ds_read_b128 v[234:237], v158
	ds_read_b128 v[238:241], v158 offset:1024
	ds_read_b128 v[242:245], v158 offset:2048
	ds_read_b128 v[246:249], v158 offset:3072
	global_load_lds_dwordx4 v[140:141], off
	v_lshl_add_u64 v[140:141], v[154:155], 0, s[94:95]
	s_add_i32 m0, s21, 0x2000
	s_nop 0
	global_load_lds_dwordx4 v[140:141], off
	s_waitcnt lgkmcnt(0)
	s_setprio 1
	s_barrier
; #define PG8_STAGE(bufoff, gbase) do { _Pragma("unroll") for (int _i = 0; _i < 2; ++_i) \
;         __builtin_amdgcn_global_load_lds((const unsigned*)((const char*)(gbase) + voff[_i]), (LAS unsigned*)(lds + (bufoff) + ldsw + _i * 8192), 16, 0, 0); } while (0)
; #define PG8_MMA(ai, bj, At, Bt) do { __builtin_amdgcn_s_setprio(1); _Pragma("unroll") for (int m = 0; m < 4; ++m) _Pragma("unroll") for (int n = 0; n < 2; ++n) _Pragma("unroll") for (int k = 0; k < 2; ++k) \
;         acc[ai][bj][m][n] = __builtin_amdgcn_mfma_f32_16x16x32_bf16(Bt[n][k], At[m][k], acc[ai][bj][m][n], 0, 0, 0); __builtin_amdgcn_s_setprio(0); } while (0)
; #define PG8_WAIT_V(n) asm volatile("s_waitcnt vmcnt(" #n ")" ::: "memory")
; #define PG8_WAIT_L(n) asm volatile("s_waitcnt lgkmcnt(" #n ")" ::: "memory")
; #define PG8_BAR __builtin_amdgcn_s_barrier()
; #define PG8_SCHED __builtin_amdgcn_sched_barrier(0)
; template <class Epi>
; DI void gemm_phase(LAS unsigned char* lds, const Gemm g, const StaticOrder& S, const Epi& E) {
;     ...
;             PG8_BAR; PG8_WAIT_L(0); PG8_MMA(1, 0, At, B0); PG8_BAR; PG8_SCHED;
;             PG8_STAGE(PG8_SB(1, 1), b3 + hstep);
;             PG8_WAIT_V(6); PG8_BAR; PG8_MMA(1, 1, At, B1); PG8_BAR;
;     DI void operator()(const f32x4 (&acc)[2][2][4][2], const Unit& u, int wr, int wc, int fr, int fq) const {
;         const int row0 = u.pm * BM + wr * 64 + fr, col0 = u.pn * BM + wc * 16 + 4 * fq;
;         const bool rot = u.pn < 18;
; #pragma unroll
;         for (int ai = 0; ai < 2; ++ai)
; #pragma unroll
;             for (int m = 0; m < 4; ++m) { const int row = row0 + ai * HALF + m * 16; u16* rowp = O + (size_t)row * NQKV_DIL + col0;
;                 f32x4 c4 = (f32x4){1.f, 1.f, 1.f, 1.f}, s4 = (f32x4){0.f, 0.f, 0.f, 0.f};
;                 if (rot) { const int pos = row & (SEQ - 1); c4 = *(const f32x4*)(cs + pos * 64 + wc * 16 + 4 * fq); s4 = *(const f32x4*)(sn + pos * 64 + wc * 16 + 4 * fq); }
	v_mfma_f32_16x16x32_bf16 v[116:119], v[234:237], v[194:197], v[116:119]
	v_mfma_f32_16x16x32_bf16 v[112:115], v[242:245], v[194:197], v[112:115]
	v_mfma_f32_16x16x32_bf16 v[100:103], v[234:237], v[202:205], v[100:103]
	v_mfma_f32_16x16x32_bf16 v[96:99], v[242:245], v[202:205], v[96:99]
	v_mfma_f32_16x16x32_bf16 v[84:87], v[234:237], v[210:213], v[84:87]
	v_mfma_f32_16x16x32_bf16 v[80:83], v[242:245], v[210:213], v[80:83]
	v_mfma_f32_16x16x32_bf16 v[68:71], v[234:237], v[226:229], v[68:71]
	v_mfma_f32_16x16x32_bf16 v[64:67], v[242:245], v[226:229], v[64:67]
	v_mfma_f32_16x16x32_bf16 v[116:119], v[238:241], v[198:201], v[116:119]
	s_mov_b32 m0, s30
	v_mfma_f32_16x16x32_bf16 v[112:115], v[246:249], v[198:201], v[112:115]
	v_lshl_add_u64 v[140:141], v[218:219], 0, s[94:95]
	v_mfma_f32_16x16x32_bf16 v[100:103], v[238:241], v[206:209], v[100:103]
	v_mfma_f32_16x16x32_bf16 v[96:99], v[246:249], v[206:209], v[96:99]
	v_mfma_f32_16x16x32_bf16 v[84:87], v[238:241], v[214:217], v[84:87]
	v_mfma_f32_16x16x32_bf16 v[80:83], v[246:249], v[214:217], v[80:83]
	v_mfma_f32_16x16x32_bf16 v[68:71], v[238:241], v[230:233], v[68:71]
	v_mfma_f32_16x16x32_bf16 v[64:67], v[246:249], v[230:233], v[64:67]
	s_setprio 0
	s_barrier
	ds_read_b128 v[194:197], v189 offset:49152
	ds_read_b128 v[198:201], v189 offset:50176
	ds_read_b128 v[202:205], v189 offset:51200
	ds_read_b128 v[206:209], v189 offset:52224
	ds_read_b128 v[210:213], v189 offset:53248
	ds_read_b128 v[214:217], v189 offset:54272
	ds_read_b128 v[226:229], v189 offset:55296
	ds_read_b128 v[230:233], v189 offset:56320
	global_load_lds_dwordx4 v[140:141], off
	v_lshl_add_u64 v[140:141], v[250:251], 0, s[94:95]
	s_mov_b32 m0, s31
	s_nop 0
	global_load_lds_dwordx4 v[140:141], off
	s_waitcnt lgkmcnt(0)
	s_setprio 1
	s_barrier
	v_mfma_f32_16x16x32_bf16 v[60:63], v[128:131], v[194:197], v[60:63]
	v_mfma_f32_16x16x32_bf16 v[56:59], v[136:139], v[194:197], v[56:59]
	v_mfma_f32_16x16x32_bf16 v[44:47], v[128:131], v[202:205], v[44:47]
	v_mfma_f32_16x16x32_bf16 v[40:43], v[136:139], v[202:205], v[40:43]
	v_mfma_f32_16x16x32_bf16 v[28:31], v[128:131], v[210:213], v[28:31]
	v_mfma_f32_16x16x32_bf16 v[24:27], v[136:139], v[210:213], v[24:27]
	v_mfma_f32_16x16x32_bf16 v[12:15], v[128:131], v[226:229], v[12:15]
	v_mfma_f32_16x16x32_bf16 v[8:11], v[136:139], v[226:229], v[8:11]
	v_mfma_f32_16x16x32_bf16 v[60:63], v[132:135], v[198:201], v[60:63]
	v_mfma_f32_16x16x32_bf16 v[56:59], v[190:193], v[198:201], v[56:59]
	v_mfma_f32_16x16x32_bf16 v[44:47], v[132:135], v[206:209], v[44:47]
	v_mfma_f32_16x16x32_bf16 v[40:43], v[190:193], v[206:209], v[40:43]
	v_mfma_f32_16x16x32_bf16 v[28:31], v[132:135], v[214:217], v[28:31]
	v_mfma_f32_16x16x32_bf16 v[24:27], v[190:193], v[214:217], v[24:27]
	v_mfma_f32_16x16x32_bf16 v[12:15], v[132:135], v[230:233], v[12:15]
	v_mfma_f32_16x16x32_bf16 v[8:11], v[190:193], v[230:233], v[8:11]
	s_setprio 0
	s_barrier
	s_add_u32 s18, s18, 0x80080
	s_addc_u32 s19, s19, 0
	s_add_i32 s20, s20, s25
	v_lshl_add_u64 v[128:129], s[18:19], 0, v[144:145]
	s_mov_b32 m0, s20
	s_nop 0
	global_load_lds_dwordx4 v[128:129], off
	v_lshl_add_u64 v[128:129], s[18:19], 0, v[142:143]
	s_add_i32 m0, s20, 0x2000
	s_nop 0
	global_load_lds_dwordx4 v[128:129], off
	s_waitcnt vmcnt(6)
	s_setprio 1
	s_barrier
	v_mfma_f32_16x16x32_bf16 v[52:55], v[234:237], v[194:197], v[52:55]
	v_mfma_f32_16x16x32_bf16 v[48:51], v[242:245], v[194:197], v[48:51]
	v_mfma_f32_16x16x32_bf16 v[36:39], v[234:237], v[202:205], v[36:39]
	v_mfma_f32_16x16x32_bf16 v[32:35], v[242:245], v[202:205], v[32:35]
	v_mfma_f32_16x16x32_bf16 v[20:23], v[234:237], v[210:213], v[20:23]
	v_mfma_f32_16x16x32_bf16 v[16:19], v[242:245], v[210:213], v[16:19]
	v_mfma_f32_16x16x32_bf16 v[4:7], v[234:237], v[226:229], v[4:7]
	v_mfma_f32_16x16x32_bf16 v[0:3], v[242:245], v[226:229], v[0:3]
	v_mfma_f32_16x16x32_bf16 v[52:55], v[238:241], v[198:201], v[52:55]
	s_add_i32 s36, s36, 2
	v_mfma_f32_16x16x32_bf16 v[48:51], v[246:249], v[198:201], v[48:51]
	s_add_u32 s8, s8, 0x100
	v_mfma_f32_16x16x32_bf16 v[36:39], v[238:241], v[206:209], v[36:39]
	s_addc_u32 s9, s9, 0
	v_mfma_f32_16x16x32_bf16 v[32:35], v[246:249], v[206:209], v[32:35]
	s_add_u32 s33, s33, 0x100
	v_mfma_f32_16x16x32_bf16 v[20:23], v[238:241], v[214:217], v[20:23]
	s_addc_u32 s35, s35, 0
	v_mfma_f32_16x16x32_bf16 v[16:19], v[246:249], v[214:217], v[16:19]
	s_cmp_gt_u32 s36, 29
	v_mfma_f32_16x16x32_bf16 v[4:7], v[238:241], v[230:233], v[4:7]
	v_mfma_f32_16x16x32_bf16 v[0:3], v[246:249], v[230:233], v[0:3]
	s_setprio 0
	s_barrier
	s_cbranch_scc0 .LBB0_202
	s_cmp_lt_i32 s2, 18
	v_lshl_add_u32 v190, s3, 8, v186
	v_mov_b32_e32 v128, 1.0
	v_mov_b32_e32 v132, 0
	s_cselect_b64 s[18:19], -1, 0
	s_cmp_gt_i32 s2, 17
	v_mov_b32_e32 v134, 0
	v_mov_b32_e32 v135, 0
	v_mov_b32_e32 v136, 0
	v_mov_b32_e32 v137, 0
	v_mov_b32_e32 v138, 1.0
	v_mov_b32_e32 v139, 1.0
	v_mov_b32_e32 v140, 1.0
	v_mov_b32_e32 v141, 1.0
	s_cbranch_scc1 .LBB0_205
	v_lshlrev_b32_e32 v129, 8, v190
	v_and_b32_e32 v158, 0xfcf00, v129
	v_lshl_add_u64 v[130:131], v[146:147], 0, v[158:159]
	v_lshl_add_u64 v[134:135], v[148:149], 0, v[158:159]
	global_load_dwordx4 v[138:141], v[130:131], off
	s_nop 0
	global_load_dwordx4 v[134:137], v[134:135], off

; #define PG8_STAGE(bufoff, gbase) do { _Pragma("unroll") for (int _i = 0; _i < 2; ++_i) \
;         __builtin_amdgcn_global_load_lds((const unsigned*)((const char*)(gbase) + voff[_i]), (LAS unsigned*)(lds + (bufoff) + ldsw + _i * 8192), 16, 0, 0); } while (0)
; #define PG8_LDA(dst, b, h) do { _Pragma("unroll") for (int m = 0; m < 4; ++m) _Pragma("unroll") for (int k = 0; k < 2; ++k) dst[m][k] = *(const LAS bf16x8*)(lds + PG8_SA(b, h) + aoff + m * 2048 + k * 1024); } while (0)
; #define PG8_LDB(dst, b, h) do { _Pragma("unroll") for (int n = 0; n < 2; ++n) _Pragma("unroll") for (int k = 0; k < 2; ++k) dst[n][k] = *(const LAS bf16x8*)(lds + PG8_SB(b, h) + boff + n * 2048 + k * 1024); } while (0)
; #define PG8_MMA(ai, bj, At, Bt) do { __builtin_amdgcn_s_setprio(1); _Pragma("unroll") for (int m = 0; m < 4; ++m) _Pragma("unroll") for (int n = 0; n < 2; ++n) _Pragma("unroll") for (int k = 0; k < 2; ++k) \
;         acc[ai][bj][m][n] = __builtin_amdgcn_mfma_f32_16x16x32_bf16(Bt[n][k], At[m][k], acc[ai][bj][m][n], 0, 0, 0); __builtin_amdgcn_s_setprio(0); } while (0)
; #define PG8_WAIT_V(n) asm volatile("s_waitcnt vmcnt(" #n ")" ::: "memory")
; #define PG8_WAIT_L(n) asm volatile("s_waitcnt lgkmcnt(" #n ")" ::: "memory")
; #define PG8_BAR __builtin_amdgcn_s_barrier()
; #define PG8_SCHED __builtin_amdgcn_sched_barrier(0)
; template <class Epi>
; DI void gemm_phase(LAS unsigned char* lds, const Gemm g, const StaticOrder& S, const Epi& E) {
;     ...
;         for (int t = 0; t < nt; t += 2) {
;             const bool last = (t == nt - 2);
;             const char* a1 = cA + (size_t)(t + 1) * kstep;
;             const char* a2 = last ? nA : cA + (size_t)(t + 2) * kstep; const char* b2 = last ? nB : cB + (size_t)(t + 2) * kstep;
;             const char* a3 = a2 + kstep; const char* b3 = b2 + kstep;
;             PG8_LDB(B0, 0, 0); PG8_SCHED; PG8_LDA(At, 0, 0); PG8_STAGE(PG8_SA(1, 1), a1 + hstep);
;             PG8_WAIT_L(8); PG8_BAR; PG8_WAIT_L(0); PG8_MMA(0, 0, At, B0); PG8_BAR; PG8_SCHED;
;             PG8_LDB(B1, 0, 1); PG8_STAGE(PG8_SB(0, 0), b2);
;             PG8_BAR; PG8_WAIT_L(0); PG8_MMA(0, 1, At, B1); PG8_BAR;
;             PG8_LDA(At, 0, 1); PG8_STAGE(PG8_SA(0, 0), a2);
;             PG8_BAR; PG8_WAIT_L(0); PG8_MMA(1, 0, At, B0); PG8_BAR; PG8_SCHED;
;             PG8_STAGE(PG8_SB(0, 1), b2 + hstep);
;             PG8_WAIT_V(6); PG8_BAR; PG8_MMA(1, 1, At, B1); PG8_BAR;
.LBB0_231:
	s_add_u32 s18, s16, 0xfff80080
	s_addc_u32 s19, s17, -1
	s_add_i32 s37, 0, 0x10000
	v_add_u32_e32 v150, s37, v135
	ds_read_b128 v[138:141], v150
	ds_read_b128 v[142:145], v150 offset:1024
	ds_read_b128 v[146:149], v150 offset:2048
	ds_read_b128 v[150:153], v150 offset:3072
	s_cmp_eq_u32 s36, 28
	s_cselect_b32 s21, s4, s19
	s_cselect_b32 s20, s5, s18
	s_cselect_b32 s19, s9, s35
	s_cselect_b32 s18, s11, s34
	v_lshl_add_u64 v[154:155], s[16:17], 0, v[130:131]
	s_add_i32 m0, s24, 0xc000
	ds_read_b128 v[186:189], v137
	ds_read_b128 v[190:193], v137 offset:1024
	ds_read_b128 v[194:197], v137 offset:2048
	ds_read_b128 v[198:201], v137 offset:3072
	ds_read_b128 v[202:205], v137 offset:4096
	ds_read_b128 v[206:209], v137 offset:5120
	ds_read_b128 v[210:213], v137 offset:6144
	ds_read_b128 v[214:217], v137 offset:7168
	global_load_lds_dwordx4 v[154:155], off
	v_lshl_add_u64 v[154:155], s[16:17], 0, v[132:133]
	s_add_i32 m0, s24, 0xe000
	s_nop 0
	global_load_lds_dwordx4 v[154:155], off
	s_waitcnt lgkmcnt(8)
	s_setprio 1
	s_barrier
	s_waitcnt lgkmcnt(0)
	v_mfma_f32_16x16x32_bf16 v[124:127], v[138:141], v[186:189], v[124:127]
	v_mfma_f32_16x16x32_bf16 v[120:123], v[146:149], v[186:189], v[120:123]
	v_mfma_f32_16x16x32_bf16 v[116:119], v[138:141], v[194:197], v[116:119]
	v_mfma_f32_16x16x32_bf16 v[112:115], v[146:149], v[194:197], v[112:115]
	v_mfma_f32_16x16x32_bf16 v[100:103], v[138:141], v[202:205], v[100:103]
	v_mfma_f32_16x16x32_bf16 v[96:99], v[146:149], v[202:205], v[96:99]
	v_mfma_f32_16x16x32_bf16 v[84:87], v[138:141], v[210:213], v[84:87]
	v_mfma_f32_16x16x32_bf16 v[80:83], v[146:149], v[210:213], v[80:83]
	v_mfma_f32_16x16x32_bf16 v[124:127], v[142:145], v[190:193], v[124:127]
	v_mfma_f32_16x16x32_bf16 v[120:123], v[150:153], v[190:193], v[120:123]
	v_mfma_f32_16x16x32_bf16 v[116:119], v[142:145], v[198:201], v[116:119]
	v_mfma_f32_16x16x32_bf16 v[112:115], v[150:153], v[198:201], v[112:115]
	v_mfma_f32_16x16x32_bf16 v[100:103], v[142:145], v[206:209], v[100:103]
	v_mfma_f32_16x16x32_bf16 v[96:99], v[150:153], v[206:209], v[96:99]
	v_mfma_f32_16x16x32_bf16 v[84:87], v[142:145], v[214:217], v[84:87]
	v_mfma_f32_16x16x32_bf16 v[80:83], v[150:153], v[214:217], v[80:83]
	s_setprio 0
	s_barrier
	s_add_i32 s40, 0, 0x14000
	v_add_u32_e32 v154, s40, v135
	s_add_i32 s37, s37, s23
	ds_read_b128 v[226:229], v154
	ds_read_b128 v[230:233], v154 offset:1024
	ds_read_b128 v[234:237], v154 offset:2048
	ds_read_b128 v[238:241], v154 offset:3072
	v_lshl_add_u64 v[154:155], s[18:19], 0, v[158:159]
	s_mov_b32 m0, s37
	v_lshl_add_u64 v[218:219], s[18:19], 0, v[128:129]
	global_load_lds_dwordx4 v[154:155], off
	s_add_i32 m0, s37, 0x2000
	s_nop 0
	global_load_lds_dwordx4 v[218:219], off
	s_waitcnt lgkmcnt(0)
	s_setprio 1
	s_barrier
	v_mfma_f32_16x16x32_bf16 v[108:111], v[226:229], v[186:189], v[108:111]
	v_mfma_f32_16x16x32_bf16 v[104:107], v[234:237], v[186:189], v[104:107]
	v_mfma_f32_16x16x32_bf16 v[92:95], v[226:229], v[194:197], v[92:95]
	v_mfma_f32_16x16x32_bf16 v[88:91], v[234:237], v[194:197], v[88:91]
	v_mfma_f32_16x16x32_bf16 v[76:79], v[226:229], v[202:205], v[76:79]
	v_mfma_f32_16x16x32_bf16 v[72:75], v[234:237], v[202:205], v[72:75]
	v_mfma_f32_16x16x32_bf16 v[68:71], v[226:229], v[210:213], v[68:71]
	v_mfma_f32_16x16x32_bf16 v[64:67], v[234:237], v[210:213], v[64:67]
	v_mfma_f32_16x16x32_bf16 v[108:111], v[230:233], v[190:193], v[108:111]
	s_mov_b32 m0, s24
	v_mfma_f32_16x16x32_bf16 v[104:107], v[238:241], v[190:193], v[104:107]
	v_lshl_add_u64 v[242:243], s[20:21], 0, v[158:159]
	v_mfma_f32_16x16x32_bf16 v[92:95], v[230:233], v[198:201], v[92:95]
	v_mfma_f32_16x16x32_bf16 v[88:91], v[238:241], v[198:201], v[88:91]
	v_mfma_f32_16x16x32_bf16 v[76:79], v[230:233], v[206:209], v[76:79]
	v_mfma_f32_16x16x32_bf16 v[72:75], v[238:241], v[206:209], v[72:75]
	v_mfma_f32_16x16x32_bf16 v[68:71], v[230:233], v[214:217], v[68:71]
	v_mfma_f32_16x16x32_bf16 v[64:67], v[238:241], v[214:217], v[64:67]
	s_setprio 0
	s_barrier
	ds_read_b128 v[186:189], v137 offset:16384
	ds_read_b128 v[190:193], v137 offset:17408
	ds_read_b128 v[194:197], v137 offset:18432
	ds_read_b128 v[198:201], v137 offset:19456
	ds_read_b128 v[202:205], v137 offset:20480
	ds_read_b128 v[206:209], v137 offset:21504
	ds_read_b128 v[210:213], v137 offset:22528
	ds_read_b128 v[214:217], v137 offset:23552
	global_load_lds_dwordx4 v[242:243], off
	v_lshl_add_u64 v[244:245], s[20:21], 0, v[128:129]
	s_mov_b32 m0, s25
	s_nop 0
	global_load_lds_dwordx4 v[244:245], off
	s_waitcnt lgkmcnt(0)
	s_setprio 1
	s_barrier
	v_mfma_f32_16x16x32_bf16 v[60:63], v[138:141], v[186:189], v[60:63]
	v_mfma_f32_16x16x32_bf16 v[56:59], v[146:149], v[186:189], v[56:59]
	v_mfma_f32_16x16x32_bf16 v[52:55], v[138:141], v[194:197], v[52:55]
	v_mfma_f32_16x16x32_bf16 v[48:51], v[146:149], v[194:197], v[48:51]
	v_mfma_f32_16x16x32_bf16 v[36:39], v[138:141], v[202:205], v[36:39]
	v_mfma_f32_16x16x32_bf16 v[32:35], v[146:149], v[202:205], v[32:35]
	v_mfma_f32_16x16x32_bf16 v[20:23], v[138:141], v[210:213], v[20:23]
	v_mfma_f32_16x16x32_bf16 v[16:19], v[146:149], v[210:213], v[16:19]
	v_mfma_f32_16x16x32_bf16 v[60:63], v[142:145], v[190:193], v[60:63]
	v_mfma_f32_16x16x32_bf16 v[56:59], v[150:153], v[190:193], v[56:59]
	v_mfma_f32_16x16x32_bf16 v[52:55], v[142:145], v[198:201], v[52:55]
	v_mfma_f32_16x16x32_bf16 v[48:51], v[150:153], v[198:201], v[48:51]
	v_mfma_f32_16x16x32_bf16 v[36:39], v[142:145], v[206:209], v[36:39]
	v_mfma_f32_16x16x32_bf16 v[32:35], v[150:153], v[206:209], v[32:35]
	v_mfma_f32_16x16x32_bf16 v[20:23], v[142:145], v[214:217], v[20:23]
	v_mfma_f32_16x16x32_bf16 v[16:19], v[150:153], v[214:217], v[16:19]
	s_setprio 0
	s_barrier
; #define PG8_STAGE(bufoff, gbase) do { _Pragma("unroll") for (int _i = 0; _i < 2; ++_i) \
;         __builtin_amdgcn_global_load_lds((const unsigned*)((const char*)(gbase) + voff[_i]), (LAS unsigned*)(lds + (bufoff) + ldsw + _i * 8192), 16, 0, 0); } while (0)
; #define PG8_LDA(dst, b, h) do { _Pragma("unroll") for (int m = 0; m < 4; ++m) _Pragma("unroll") for (int k = 0; k < 2; ++k) dst[m][k] = *(const LAS bf16x8*)(lds + PG8_SA(b, h) + aoff + m * 2048 + k * 1024); } while (0)
; #define PG8_LDB(dst, b, h) do { _Pragma("unroll") for (int n = 0; n < 2; ++n) _Pragma("unroll") for (int k = 0; k < 2; ++k) dst[n][k] = *(const LAS bf16x8*)(lds + PG8_SB(b, h) + boff + n * 2048 + k * 1024); } while (0)
; #define PG8_MMA(ai, bj, At, Bt) do { __builtin_amdgcn_s_setprio(1); _Pragma("unroll") for (int m = 0; m < 4; ++m) _Pragma("unroll") for (int n = 0; n < 2; ++n) _Pragma("unroll") for (int k = 0; k < 2; ++k) \
;         acc[ai][bj][m][n] = __builtin_amdgcn_mfma_f32_16x16x32_bf16(Bt[n][k], At[m][k], acc[ai][bj][m][n], 0, 0, 0); __builtin_amdgcn_s_setprio(0); } while (0)
; #define PG8_WAIT_V(n) asm volatile("s_waitcnt vmcnt(" #n ")" ::: "memory")
; #define PG8_WAIT_L(n) asm volatile("s_waitcnt lgkmcnt(" #n ")" ::: "memory")
; #define PG8_BAR __builtin_amdgcn_s_barrier()
; #define PG8_SCHED __builtin_amdgcn_sched_barrier(0)
; template <class Epi>
; DI void gemm_phase(LAS unsigned char* lds, const Gemm g, const StaticOrder& S, const Epi& E) {
;     ...
;             PG8_STAGE(PG8_SB(0, 1), b2 + hstep);
;             PG8_WAIT_V(6); PG8_BAR; PG8_MMA(1, 1, At, B1); PG8_BAR;
;             PG8_LDB(B0, 1, 0); PG8_SCHED; PG8_LDA(At, 1, 0); PG8_STAGE(PG8_SA(0, 1), a2 + hstep);
;             PG8_WAIT_L(8); PG8_BAR; PG8_WAIT_L(0); PG8_MMA(0, 0, At, B0); PG8_BAR; PG8_SCHED;
;             PG8_LDB(B1, 1, 1); PG8_STAGE(PG8_SB(1, 0), b3);
;             PG8_BAR; PG8_WAIT_L(0); PG8_MMA(0, 1, At, B1); PG8_BAR;
;             PG8_LDA(At, 1, 1); PG8_STAGE(PG8_SA(1, 0), a3);
;             PG8_BAR; PG8_WAIT_L(0); PG8_MMA(1, 0, At, B0); PG8_BAR; PG8_SCHED;
	s_add_u32 s38, s18, 0x80000
	s_addc_u32 s39, s19, 0
	s_add_i32 s37, s40, s23
	v_lshl_add_u64 v[138:139], s[38:39], 0, v[158:159]
	s_mov_b32 m0, s37
	s_nop 0
	global_load_lds_dwordx4 v[138:139], off
	v_lshl_add_u64 v[138:139], s[38:39], 0, v[128:129]
	s_add_i32 m0, s37, 0x2000
	s_nop 0
	global_load_lds_dwordx4 v[138:139], off
	s_waitcnt vmcnt(6)
	s_setprio 1
	s_barrier
	v_mfma_f32_16x16x32_bf16 v[44:47], v[226:229], v[186:189], v[44:47]
	v_mfma_f32_16x16x32_bf16 v[40:43], v[234:237], v[186:189], v[40:43]
	v_mfma_f32_16x16x32_bf16 v[28:31], v[226:229], v[194:197], v[28:31]
	v_mfma_f32_16x16x32_bf16 v[24:27], v[234:237], v[194:197], v[24:27]
	v_mfma_f32_16x16x32_bf16 v[12:15], v[226:229], v[202:205], v[12:15]
	v_mfma_f32_16x16x32_bf16 v[8:11], v[234:237], v[202:205], v[8:11]
	v_mfma_f32_16x16x32_bf16 v[4:7], v[226:229], v[210:213], v[4:7]
	v_mfma_f32_16x16x32_bf16 v[0:3], v[234:237], v[210:213], v[0:3]
	v_mfma_f32_16x16x32_bf16 v[44:47], v[230:233], v[190:193], v[44:47]
	s_add_i32 s37, 0, 0x18000
	v_mfma_f32_16x16x32_bf16 v[40:43], v[238:241], v[190:193], v[40:43]
	v_add_u32_e32 v150, s37, v135
	v_mfma_f32_16x16x32_bf16 v[28:31], v[230:233], v[198:201], v[28:31]
	v_mfma_f32_16x16x32_bf16 v[24:27], v[238:241], v[198:201], v[24:27]
	v_mfma_f32_16x16x32_bf16 v[12:15], v[230:233], v[206:209], v[12:15]
	v_mfma_f32_16x16x32_bf16 v[8:11], v[238:241], v[206:209], v[8:11]
	v_mfma_f32_16x16x32_bf16 v[4:7], v[230:233], v[214:217], v[4:7]
	v_mfma_f32_16x16x32_bf16 v[0:3], v[238:241], v[214:217], v[0:3]
	s_setprio 0
	s_barrier
	ds_read_b128 v[138:141], v150
	ds_read_b128 v[142:145], v150 offset:1024
	ds_read_b128 v[146:149], v150 offset:2048
	ds_read_b128 v[150:153], v150 offset:3072
	s_add_u32 s20, s20, 0x80000
	s_addc_u32 s21, s21, 0
	s_mov_b32 m0, s26
	v_lshl_add_u64 v[226:227], s[20:21], 0, v[158:159]
	ds_read_b128 v[186:189], v137 offset:32768
	ds_read_b128 v[190:193], v137 offset:33792
	ds_read_b128 v[194:197], v137 offset:34816
	ds_read_b128 v[198:201], v137 offset:35840
	ds_read_b128 v[202:205], v137 offset:36864
	ds_read_b128 v[206:209], v137 offset:37888
	ds_read_b128 v[210:213], v137 offset:38912
	ds_read_b128 v[214:217], v137 offset:39936
	global_load_lds_dwordx4 v[226:227], off
	v_lshl_add_u64 v[226:227], s[20:21], 0, v[128:129]
	s_mov_b32 m0, s27
	s_nop 0
	global_load_lds_dwordx4 v[226:227], off
	s_waitcnt lgkmcnt(8)
	s_setprio 1
	s_barrier
	s_waitcnt lgkmcnt(0)
	v_mfma_f32_16x16x32_bf16 v[124:127], v[138:141], v[186:189], v[124:127]
	v_mfma_f32_16x16x32_bf16 v[120:123], v[146:149], v[186:189], v[120:123]
	v_mfma_f32_16x16x32_bf16 v[116:119], v[138:141], v[194:197], v[116:119]
	v_mfma_f32_16x16x32_bf16 v[112:115], v[146:149], v[194:197], v[112:115]
	v_mfma_f32_16x16x32_bf16 v[100:103], v[138:141], v[202:205], v[100:103]
	v_mfma_f32_16x16x32_bf16 v[96:99], v[146:149], v[202:205], v[96:99]
	v_mfma_f32_16x16x32_bf16 v[84:87], v[138:141], v[210:213], v[84:87]
	v_mfma_f32_16x16x32_bf16 v[80:83], v[146:149], v[210:213], v[80:83]
	v_mfma_f32_16x16x32_bf16 v[124:127], v[142:145], v[190:193], v[124:127]
	v_mfma_f32_16x16x32_bf16 v[120:123], v[150:153], v[190:193], v[120:123]
	v_mfma_f32_16x16x32_bf16 v[116:119], v[142:145], v[198:201], v[116:119]
	v_mfma_f32_16x16x32_bf16 v[112:115], v[150:153], v[198:201], v[112:115]
	v_mfma_f32_16x16x32_bf16 v[100:103], v[142:145], v[206:209], v[100:103]
	v_mfma_f32_16x16x32_bf16 v[96:99], v[150:153], v[206:209], v[96:99]
	v_mfma_f32_16x16x32_bf16 v[84:87], v[142:145], v[214:217], v[84:87]
	v_mfma_f32_16x16x32_bf16 v[80:83], v[150:153], v[214:217], v[80:83]
	s_setprio 0
	s_barrier
	s_add_i32 s20, 0, 0x1c000
	s_add_i32 s21, s37, s23
	v_add_u32_e32 v220, s20, v135
	v_lshl_add_u64 v[154:155], v[154:155], 0, s[94:95]
	s_mov_b32 m0, s21
	ds_read_b128 v[226:229], v220
	ds_read_b128 v[230:233], v220 offset:1024
	ds_read_b128 v[234:237], v220 offset:2048
	ds_read_b128 v[238:241], v220 offset:3072
	global_load_lds_dwordx4 v[154:155], off
	v_lshl_add_u64 v[154:155], v[218:219], 0, s[94:95]
	s_add_i32 m0, s21, 0x2000
	s_nop 0
	global_load_lds_dwordx4 v[154:155], off
	s_waitcnt lgkmcnt(0)
	s_setprio 1
	s_barrier
	v_mfma_f32_16x16x32_bf16 v[108:111], v[226:229], v[186:189], v[108:111]
	v_mfma_f32_16x16x32_bf16 v[104:107], v[234:237], v[186:189], v[104:107]
	v_mfma_f32_16x16x32_bf16 v[92:95], v[226:229], v[194:197], v[92:95]
	v_mfma_f32_16x16x32_bf16 v[88:91], v[234:237], v[194:197], v[88:91]
	v_mfma_f32_16x16x32_bf16 v[76:79], v[226:229], v[202:205], v[76:79]
	v_mfma_f32_16x16x32_bf16 v[72:75], v[234:237], v[202:205], v[72:75]
	v_mfma_f32_16x16x32_bf16 v[68:71], v[226:229], v[210:213], v[68:71]
	v_mfma_f32_16x16x32_bf16 v[64:67], v[234:237], v[210:213], v[64:67]
	v_mfma_f32_16x16x32_bf16 v[108:111], v[230:233], v[190:193], v[108:111]
	s_mov_b32 m0, s28
	v_mfma_f32_16x16x32_bf16 v[104:107], v[238:241], v[190:193], v[104:107]
	v_lshl_add_u64 v[154:155], v[242:243], 0, s[94:95]
	v_mfma_f32_16x16x32_bf16 v[92:95], v[230:233], v[198:201], v[92:95]
	v_mfma_f32_16x16x32_bf16 v[88:91], v[238:241], v[198:201], v[88:91]
	v_mfma_f32_16x16x32_bf16 v[76:79], v[230:233], v[206:209], v[76:79]
	v_mfma_f32_16x16x32_bf16 v[72:75], v[238:241], v[206:209], v[72:75]
	v_mfma_f32_16x16x32_bf16 v[68:71], v[230:233], v[214:217], v[68:71]
	v_mfma_f32_16x16x32_bf16 v[64:67], v[238:241], v[214:217], v[64:67]
	s_setprio 0
	s_barrier
	ds_read_b128 v[186:189], v137 offset:49152
	ds_read_b128 v[190:193], v137 offset:50176
	ds_read_b128 v[194:197], v137 offset:51200
	ds_read_b128 v[198:201], v137 offset:52224
	ds_read_b128 v[202:205], v137 offset:53248
	ds_read_b128 v[206:209], v137 offset:54272
	ds_read_b128 v[210:213], v137 offset:55296
	ds_read_b128 v[214:217], v137 offset:56320
	global_load_lds_dwordx4 v[154:155], off
	v_lshl_add_u64 v[154:155], v[244:245], 0, s[94:95]
	s_mov_b32 m0, s29
	s_nop 0
	global_load_lds_dwordx4 v[154:155], off
	s_waitcnt lgkmcnt(0)
	s_setprio 1
	s_barrier
; #define PG8_STAGE(bufoff, gbase) do { _Pragma("unroll") for (int _i = 0; _i < 2; ++_i) \
;         __builtin_amdgcn_global_load_lds((const unsigned*)((const char*)(gbase) + voff[_i]), (LAS unsigned*)(lds + (bufoff) + ldsw + _i * 8192), 16, 0, 0); } while (0)
; #define PG8_MMA(ai, bj, At, Bt) do { __builtin_amdgcn_s_setprio(1); _Pragma("unroll") for (int m = 0; m < 4; ++m) _Pragma("unroll") for (int n = 0; n < 2; ++n) _Pragma("unroll") for (int k = 0; k < 2; ++k) \
;         acc[ai][bj][m][n] = __builtin_amdgcn_mfma_f32_16x16x32_bf16(Bt[n][k], At[m][k], acc[ai][bj][m][n], 0, 0, 0); __builtin_amdgcn_s_setprio(0); } while (0)
; #define PG8_WAIT_V(n) asm volatile("s_waitcnt vmcnt(" #n ")" ::: "memory")
; #define PG8_WAIT_L(n) asm volatile("s_waitcnt lgkmcnt(" #n ")" ::: "memory")
; #define PG8_BAR __builtin_amdgcn_s_barrier()
; #define PG8_SCHED __builtin_amdgcn_sched_barrier(0)
; template <class Epi>
; DI void gemm_phase(LAS unsigned char* lds, const Gemm g, const StaticOrder& S, const Epi& E) {
;     ...
;             PG8_BAR; PG8_WAIT_L(0); PG8_MMA(1, 0, At, B0); PG8_BAR; PG8_SCHED;
;             PG8_STAGE(PG8_SB(1, 1), b3 + hstep);
;             PG8_WAIT_V(6); PG8_BAR; PG8_MMA(1, 1, At, B1); PG8_BAR;
;         }
	v_mfma_f32_16x16x32_bf16 v[60:63], v[138:141], v[186:189], v[60:63]
	v_mfma_f32_16x16x32_bf16 v[56:59], v[146:149], v[186:189], v[56:59]
	v_mfma_f32_16x16x32_bf16 v[52:55], v[138:141], v[194:197], v[52:55]
	v_mfma_f32_16x16x32_bf16 v[48:51], v[146:149], v[194:197], v[48:51]
	v_mfma_f32_16x16x32_bf16 v[36:39], v[138:141], v[202:205], v[36:39]
	v_mfma_f32_16x16x32_bf16 v[32:35], v[146:149], v[202:205], v[32:35]
	v_mfma_f32_16x16x32_bf16 v[20:23], v[138:141], v[210:213], v[20:23]
	v_mfma_f32_16x16x32_bf16 v[16:19], v[146:149], v[210:213], v[16:19]
	v_mfma_f32_16x16x32_bf16 v[60:63], v[142:145], v[190:193], v[60:63]
	v_mfma_f32_16x16x32_bf16 v[56:59], v[150:153], v[190:193], v[56:59]
	v_mfma_f32_16x16x32_bf16 v[52:55], v[142:145], v[198:201], v[52:55]
	v_mfma_f32_16x16x32_bf16 v[48:51], v[150:153], v[198:201], v[48:51]
	v_mfma_f32_16x16x32_bf16 v[36:39], v[142:145], v[206:209], v[36:39]
	v_mfma_f32_16x16x32_bf16 v[32:35], v[150:153], v[206:209], v[32:35]
	v_mfma_f32_16x16x32_bf16 v[20:23], v[142:145], v[214:217], v[20:23]
	v_mfma_f32_16x16x32_bf16 v[16:19], v[150:153], v[214:217], v[16:19]
	s_setprio 0
	s_barrier
	s_add_u32 s18, s18, 0x80080
	s_addc_u32 s19, s19, 0
	s_add_i32 s20, s20, s23
	v_lshl_add_u64 v[138:139], s[18:19], 0, v[158:159]
	s_mov_b32 m0, s20
	s_nop 0
	global_load_lds_dwordx4 v[138:139], off
	v_lshl_add_u64 v[138:139], s[18:19], 0, v[128:129]
	s_add_i32 m0, s20, 0x2000
	s_nop 0
	global_load_lds_dwordx4 v[138:139], off
	s_waitcnt vmcnt(6)
	s_setprio 1
	s_barrier
	v_mfma_f32_16x16x32_bf16 v[44:47], v[226:229], v[186:189], v[44:47]
	v_mfma_f32_16x16x32_bf16 v[40:43], v[234:237], v[186:189], v[40:43]
	v_mfma_f32_16x16x32_bf16 v[28:31], v[226:229], v[194:197], v[28:31]
	v_mfma_f32_16x16x32_bf16 v[24:27], v[234:237], v[194:197], v[24:27]
	v_mfma_f32_16x16x32_bf16 v[12:15], v[226:229], v[202:205], v[12:15]
	v_mfma_f32_16x16x32_bf16 v[8:11], v[234:237], v[202:205], v[8:11]
	v_mfma_f32_16x16x32_bf16 v[4:7], v[226:229], v[210:213], v[4:7]
	v_mfma_f32_16x16x32_bf16 v[0:3], v[234:237], v[210:213], v[0:3]
	v_mfma_f32_16x16x32_bf16 v[44:47], v[230:233], v[190:193], v[44:47]
	s_add_i32 s36, s36, 2
	v_mfma_f32_16x16x32_bf16 v[40:43], v[238:241], v[190:193], v[40:43]
	s_add_u32 s16, s16, 0x100
	v_mfma_f32_16x16x32_bf16 v[28:31], v[230:233], v[198:201], v[28:31]
	s_addc_u32 s17, s17, 0
	v_mfma_f32_16x16x32_bf16 v[24:27], v[238:241], v[198:201], v[24:27]
	s_add_u32 s34, s34, 0x100
	v_mfma_f32_16x16x32_bf16 v[12:15], v[230:233], v[206:209], v[12:15]
	s_addc_u32 s35, s35, 0
	v_mfma_f32_16x16x32_bf16 v[8:11], v[238:241], v[206:209], v[8:11]
	s_cmp_gt_u32 s36, 29
	v_mfma_f32_16x16x32_bf16 v[4:7], v[230:233], v[214:217], v[4:7]
	v_mfma_f32_16x16x32_bf16 v[0:3], v[238:241], v[214:217], v[0:3]
	s_setprio 0
	s_barrier
	s_cbranch_scc0 .LBB0_231
;     DI void operator()(const f32x4 (&acc)[2][2][4][2], const Unit& u, int wr, int wc, int fr, int fq) const {
;         const int row0 = u.pm * BM + wr * 64 + fr, col0 = u.pn * BM + wc * 32 + 8 * fq;
; #pragma unroll
;         for (int ai = 0; ai < 2; ++ai)
; #pragma unroll
;             for (int m = 0; m < 4; ++m) { u16* rowp = O + (size_t)(row0 + ai * HALF + m * 16) * ldc + col0;
; #pragma unroll
;                 for (int bj = 0; bj < 2; ++bj) { const f32x4 v0 = acc[ai][bj][m][0], v1 = acc[ai][bj][m][1];
;                     *(u32x4*)(rowp + bj * HALF) = (u32x4){pk(v0[0], v0[1]), pk(v0[2], v0[3]), pk(v1[0], v1[1]), pk(v1[2], v1[3])}; } }
;     }
	v_lshl_add_u32 v144, s33, 8, v134
	v_lshl_or_b32 v138, s31, 8, v136
	v_ashrrev_i32_e32 v139, 31, v138
	v_mov_b64_e32 v[140:141], s[50:51]
	s_movk_i32 s9, 0x3000
	v_cvt_pk_bf16_f32 v68, v68, v69
	v_cvt_pk_bf16_f32 v69, v70, v71
	v_cvt_pk_bf16_f32 v70, v64, v65
	v_add_u32_e32 v64, 0x80, v144
	v_mad_i64_i32 v[142:143], s[4:5], v144, s9, v[140:141]
	v_lshlrev_b64 v[138:139], 1, v[138:139]
	v_cvt_pk_bf16_f32 v108, v108, v109
	v_cvt_pk_bf16_f32 v109, v110, v111
	v_cvt_pk_bf16_f32 v110, v104, v105
	v_or_b32_e32 v104, 16, v144
	v_mad_i64_i32 v[64:65], s[4:5], v64, s9, v[140:141]
	v_cvt_pk_bf16_f32 v44, v44, v45
	v_cvt_pk_bf16_f32 v45, v46, v47
	v_cvt_pk_bf16_f32 v46, v40, v41
	v_add_u32_e32 v40, 0x90, v144
	v_lshl_add_u64 v[142:143], v[142:143], 0, v[138:139]
	v_cvt_pk_bf16_f32 v111, v106, v107
	v_mad_i64_i32 v[104:105], s[4:5], v104, s9, v[140:141]
	v_cvt_pk_bf16_f32 v92, v92, v93
	v_cvt_pk_bf16_f32 v93, v94, v95
	v_cvt_pk_bf16_f32 v94, v88, v89
	v_or_b32_e32 v88, 32, v144
	v_lshl_add_u64 v[64:65], v[64:65], 0, v[138:139]
	v_cvt_pk_bf16_f32 v47, v42, v43
	v_mad_i64_i32 v[40:41], s[4:5], v40, s9, v[140:141]
	v_cvt_pk_bf16_f32 v28, v28, v29
	v_cvt_pk_bf16_f32 v29, v30, v31
	v_cvt_pk_bf16_f32 v30, v24, v25
	v_add_u32_e32 v24, 0xa0, v144
	global_store_dwordx4 v[142:143], v[108:111], off offset:256
	v_cvt_pk_bf16_f32 v95, v90, v91
	v_mad_i64_i32 v[88:89], s[4:5], v88, s9, v[140:141]
	v_lshl_add_u64 v[108:109], v[104:105], 0, v[138:139]
	v_cvt_pk_bf16_f32 v76, v76, v77
	v_cvt_pk_bf16_f32 v77, v78, v79
	v_cvt_pk_bf16_f32 v78, v72, v73
	v_or_b32_e32 v72, 48, v144
	global_store_dwordx4 v[64:65], v[44:47], off offset:256
	v_cvt_pk_bf16_f32 v31, v26, v27
	v_mad_i64_i32 v[24:25], s[4:5], v24, s9, v[140:141]
	v_lshl_add_u64 v[44:45], v[40:41], 0, v[138:139]
	v_cvt_pk_bf16_f32 v12, v12, v13
	v_cvt_pk_bf16_f32 v13, v14, v15
	v_cvt_pk_bf16_f32 v14, v8, v9
	v_add_u32_e32 v8, 0xb0, v144
	global_store_dwordx4 v[108:109], v[92:95], off offset:256
	v_cvt_pk_bf16_f32 v79, v74, v75
	v_mad_i64_i32 v[72:73], s[4:5], v72, s9, v[140:141]
	v_lshl_add_u64 v[92:93], v[88:89], 0, v[138:139]
	global_store_dwordx4 v[44:45], v[28:31], off offset:256
	v_cvt_pk_bf16_f32 v15, v10, v11
	v_mad_i64_i32 v[8:9], s[4:5], v8, s9, v[140:141]
	v_lshl_add_u64 v[28:29], v[24:25], 0, v[138:139]
	v_cvt_pk_bf16_f32 v124, v124, v125
	v_cvt_pk_bf16_f32 v125, v126, v127
	v_cvt_pk_bf16_f32 v126, v120, v121
	v_cvt_pk_bf16_f32 v127, v122, v123
	v_cvt_pk_bf16_f32 v104, v116, v117
	v_cvt_pk_bf16_f32 v105, v118, v119
	v_cvt_pk_bf16_f32 v106, v112, v113
	v_cvt_pk_bf16_f32 v107, v114, v115
	v_cvt_pk_bf16_f32 v88, v100, v101
	v_cvt_pk_bf16_f32 v89, v102, v103
	v_cvt_pk_bf16_f32 v90, v96, v97
	v_cvt_pk_bf16_f32 v91, v98, v99
	global_store_dwordx4 v[92:93], v[76:79], off offset:256
	v_cvt_pk_bf16_f32 v74, v80, v81
	v_cvt_pk_bf16_f32 v75, v82, v83
	v_lshl_add_u64 v[76:77], v[72:73], 0, v[138:139]
	v_cvt_pk_bf16_f32 v72, v84, v85
	v_cvt_pk_bf16_f32 v73, v86, v87
	v_cvt_pk_bf16_f32 v71, v66, v67
	v_cvt_pk_bf16_f32 v60, v60, v61
	v_cvt_pk_bf16_f32 v61, v62, v63
	v_cvt_pk_bf16_f32 v62, v56, v57
	v_cvt_pk_bf16_f32 v63, v58, v59
	v_cvt_pk_bf16_f32 v40, v52, v53
	v_cvt_pk_bf16_f32 v41, v54, v55
	v_cvt_pk_bf16_f32 v42, v48, v49
	v_cvt_pk_bf16_f32 v43, v50, v51
	v_cvt_pk_bf16_f32 v24, v36, v37
	v_cvt_pk_bf16_f32 v25, v38, v39
	v_cvt_pk_bf16_f32 v26, v32, v33
	v_cvt_pk_bf16_f32 v27, v34, v35
	global_store_dwordx4 v[28:29], v[12:15], off offset:256
	v_cvt_pk_bf16_f32 v10, v16, v17
	v_cvt_pk_bf16_f32 v11, v18, v19
	v_lshl_add_u64 v[12:13], v[8:9], 0, v[138:139]
	v_cvt_pk_bf16_f32 v8, v20, v21
	v_cvt_pk_bf16_f32 v9, v22, v23
	v_cvt_pk_bf16_f32 v4, v4, v5
	v_cvt_pk_bf16_f32 v5, v6, v7
	v_cvt_pk_bf16_f32 v6, v0, v1
	v_cvt_pk_bf16_f32 v7, v2, v3
	s_and_b64 vcc, exec, s[6:7]
	s_mov_b32 s31, s8
	s_mov_b32 s33, s10
	s_mov_b64 s[18:19], s[14:15]
	s_mov_b64 s[16:17], s[12:13]
	global_store_dwordx4 v[142:143], v[124:127], off
	global_store_dwordx4 v[108:109], v[104:107], off
	global_store_dwordx4 v[92:93], v[88:91], off
	global_store_dwordx4 v[76:77], v[72:75], off
	global_store_dwordx4 v[76:77], v[68:71], off offset:256
	global_store_dwordx4 v[64:65], v[60:63], off
	global_store_dwordx4 v[44:45], v[40:43], off
	global_store_dwordx4 v[28:29], v[24:27], off
	global_store_dwordx4 v[12:13], v[8:11], off
	global_store_dwordx4 v[12:13], v[4:7], off offset:256
	s_cbranch_vccz .LBB0_228
	s_waitcnt vmcnt(0)
	s_cmpk_gt_u32 s2, 0xff
	s_cbranch_scc1 .LBB0_235
	s_barrier

; #define PG8_STAGE(bufoff, gbase) do { _Pragma("unroll") for (int _i = 0; _i < 2; ++_i) \
;         __builtin_amdgcn_global_load_lds((const unsigned*)((const char*)(gbase) + voff[_i]), (LAS unsigned*)(lds + (bufoff) + ldsw + _i * 8192), 16, 0, 0); } while (0)
; #define PG8_LDA(dst, b, h) do { _Pragma("unroll") for (int m = 0; m < 4; ++m) _Pragma("unroll") for (int k = 0; k < 2; ++k) dst[m][k] = *(const LAS bf16x8*)(lds + PG8_SA(b, h) + aoff + m * 2048 + k * 1024); } while (0)
; #define PG8_LDB(dst, b, h) do { _Pragma("unroll") for (int n = 0; n < 2; ++n) _Pragma("unroll") for (int k = 0; k < 2; ++k) dst[n][k] = *(const LAS bf16x8*)(lds + PG8_SB(b, h) + boff + n * 2048 + k * 1024); } while (0)
; #define PG8_MMA(ai, bj, At, Bt) do { __builtin_amdgcn_s_setprio(1); _Pragma("unroll") for (int m = 0; m < 4; ++m) _Pragma("unroll") for (int n = 0; n < 2; ++n) _Pragma("unroll") for (int k = 0; k < 2; ++k) \
;         acc[ai][bj][m][n] = __builtin_amdgcn_mfma_f32_16x16x32_bf16(Bt[n][k], At[m][k], acc[ai][bj][m][n], 0, 0, 0); __builtin_amdgcn_s_setprio(0); } while (0)
; #define PG8_WAIT_V(n) asm volatile("s_waitcnt vmcnt(" #n ")" ::: "memory")
; #define PG8_WAIT_L(n) asm volatile("s_waitcnt lgkmcnt(" #n ")" ::: "memory")
; #define PG8_BAR __builtin_amdgcn_s_barrier()
; #define PG8_SCHED __builtin_amdgcn_sched_barrier(0)
; template <class Epi>
; DI void gemm_phase(LAS unsigned char* lds, const Gemm g, const StaticOrder& S, const Epi& E) {
;     ...
;         for (int t = 0; t < nt; t += 2) {
;             const bool last = (t == nt - 2);
;             const char* a1 = cA + (size_t)(t + 1) * kstep;
;             const char* a2 = last ? nA : cA + (size_t)(t + 2) * kstep; const char* b2 = last ? nB : cB + (size_t)(t + 2) * kstep;
;             const char* a3 = a2 + kstep; const char* b3 = b2 + kstep;
;             PG8_LDB(B0, 0, 0); PG8_SCHED; PG8_LDA(At, 0, 0); PG8_STAGE(PG8_SA(1, 1), a1 + hstep);
;             PG8_WAIT_L(8); PG8_BAR; PG8_WAIT_L(0); PG8_MMA(0, 0, At, B0); PG8_BAR; PG8_SCHED;
;             PG8_LDB(B1, 0, 1); PG8_STAGE(PG8_SB(0, 0), b2);
;             PG8_BAR; PG8_WAIT_L(0); PG8_MMA(0, 1, At, B1); PG8_BAR;
;             PG8_LDA(At, 0, 1); PG8_STAGE(PG8_SA(0, 0), a2);
;             PG8_BAR; PG8_WAIT_L(0); PG8_MMA(1, 0, At, B0); PG8_BAR; PG8_SCHED;
;             PG8_STAGE(PG8_SB(0, 1), b2 + hstep);
;             PG8_WAIT_V(6); PG8_BAR; PG8_MMA(1, 1, At, B1); PG8_BAR;
.LBB0_320:
	s_add_u32 s26, s24, 0x100
	s_addc_u32 s27, s25, 0
	s_add_i32 s47, 0, 0x10000
	v_add_u32_e32 v140, s47, v226
	ds_read_b128 v[128:131], v140
	ds_read_b128 v[132:135], v140 offset:1024
	ds_read_b128 v[136:139], v140 offset:2048
	ds_read_b128 v[140:143], v140 offset:3072
	s_cmp_eq_u32 s46, 28
	s_cselect_b32 s31, s4, s27
	s_cselect_b32 s30, s5, s26
	s_cselect_b32 s29, s9, s45
	s_cselect_b32 s28, s11, s33
	v_lshl_add_u64 v[214:215], s[24:25], 0, v[190:191]
	s_add_i32 m0, s38, 0xc000
	ds_read_b128 v[144:147], v228
	ds_read_b128 v[148:151], v228 offset:1024
	ds_read_b128 v[152:155], v228 offset:2048
	ds_read_b128 v[194:197], v228 offset:3072
	ds_read_b128 v[198:201], v228 offset:4096
	ds_read_b128 v[202:205], v228 offset:5120
	ds_read_b128 v[206:209], v228 offset:6144
	ds_read_b128 v[210:213], v228 offset:7168
	global_load_lds_dwordx4 v[214:215], off
	v_lshl_add_u64 v[214:215], s[24:25], 0, v[192:193]
	s_add_i32 m0, s38, 0xe000
	s_nop 0
	global_load_lds_dwordx4 v[214:215], off
	s_waitcnt lgkmcnt(8)
	s_setprio 1
	s_barrier
	s_waitcnt lgkmcnt(0)
	v_mfma_f32_16x16x32_bf16 v[124:127], v[128:131], v[144:147], v[124:127]
	v_mfma_f32_16x16x32_bf16 v[120:123], v[136:139], v[144:147], v[120:123]
	v_mfma_f32_16x16x32_bf16 v[116:119], v[128:131], v[152:155], v[116:119]
	v_mfma_f32_16x16x32_bf16 v[112:115], v[136:139], v[152:155], v[112:115]
	v_mfma_f32_16x16x32_bf16 v[108:111], v[128:131], v[198:201], v[108:111]
	v_mfma_f32_16x16x32_bf16 v[104:107], v[136:139], v[198:201], v[104:107]
	v_mfma_f32_16x16x32_bf16 v[100:103], v[128:131], v[206:209], v[100:103]
	v_mfma_f32_16x16x32_bf16 v[96:99], v[136:139], v[206:209], v[96:99]
	v_mfma_f32_16x16x32_bf16 v[124:127], v[132:135], v[148:151], v[124:127]
	v_mfma_f32_16x16x32_bf16 v[120:123], v[140:143], v[148:151], v[120:123]
	v_mfma_f32_16x16x32_bf16 v[116:119], v[132:135], v[194:197], v[116:119]
	v_mfma_f32_16x16x32_bf16 v[112:115], v[140:143], v[194:197], v[112:115]
	v_mfma_f32_16x16x32_bf16 v[108:111], v[132:135], v[202:205], v[108:111]
	v_mfma_f32_16x16x32_bf16 v[104:107], v[140:143], v[202:205], v[104:107]
	v_mfma_f32_16x16x32_bf16 v[100:103], v[132:135], v[210:213], v[100:103]
	v_mfma_f32_16x16x32_bf16 v[96:99], v[140:143], v[210:213], v[96:99]
	s_setprio 0
	s_barrier
	s_add_i32 s48, 0, 0x14000
	s_add_i32 s24, s47, s37
	v_add_u32_e32 v158, s48, v226
	v_lshl_add_u64 v[218:219], s[28:29], 0, v[188:189]
	s_mov_b32 m0, s24
	ds_read_b128 v[214:217], v158
	ds_read_b128 v[230:233], v158 offset:1024
	ds_read_b128 v[234:237], v158 offset:2048
	ds_read_b128 v[238:241], v158 offset:3072
	global_load_lds_dwordx4 v[218:219], off
	v_lshl_add_u64 v[220:221], s[28:29], 0, v[186:187]
	s_add_i32 m0, s24, 0x2000
	s_nop 0
	global_load_lds_dwordx4 v[220:221], off
	s_waitcnt lgkmcnt(0)
	s_setprio 1
	s_barrier
	v_mfma_f32_16x16x32_bf16 v[60:63], v[214:217], v[144:147], v[60:63]
	v_mfma_f32_16x16x32_bf16 v[56:59], v[234:237], v[144:147], v[56:59]
	v_mfma_f32_16x16x32_bf16 v[52:55], v[214:217], v[152:155], v[52:55]
	v_mfma_f32_16x16x32_bf16 v[48:51], v[234:237], v[152:155], v[48:51]
	v_mfma_f32_16x16x32_bf16 v[44:47], v[214:217], v[198:201], v[44:47]
	v_mfma_f32_16x16x32_bf16 v[40:43], v[234:237], v[198:201], v[40:43]
	v_mfma_f32_16x16x32_bf16 v[36:39], v[214:217], v[206:209], v[36:39]
	v_mfma_f32_16x16x32_bf16 v[32:35], v[234:237], v[206:209], v[32:35]
	v_mfma_f32_16x16x32_bf16 v[60:63], v[230:233], v[148:151], v[60:63]
	s_mov_b32 m0, s38
	v_mfma_f32_16x16x32_bf16 v[56:59], v[238:241], v[148:151], v[56:59]
	v_lshl_add_u64 v[242:243], s[30:31], 0, v[188:189]
	v_mfma_f32_16x16x32_bf16 v[52:55], v[230:233], v[194:197], v[52:55]
	v_mfma_f32_16x16x32_bf16 v[48:51], v[238:241], v[194:197], v[48:51]
	v_mfma_f32_16x16x32_bf16 v[44:47], v[230:233], v[202:205], v[44:47]
	v_mfma_f32_16x16x32_bf16 v[40:43], v[238:241], v[202:205], v[40:43]
	v_mfma_f32_16x16x32_bf16 v[36:39], v[230:233], v[210:213], v[36:39]
	v_mfma_f32_16x16x32_bf16 v[32:35], v[238:241], v[210:213], v[32:35]
	s_setprio 0
	s_barrier
	ds_read_b128 v[144:147], v228 offset:16384
	ds_read_b128 v[148:151], v228 offset:17408
	ds_read_b128 v[152:155], v228 offset:18432
	ds_read_b128 v[194:197], v228 offset:19456
	ds_read_b128 v[198:201], v228 offset:20480
	ds_read_b128 v[202:205], v228 offset:21504
	ds_read_b128 v[206:209], v228 offset:22528
	ds_read_b128 v[210:213], v228 offset:23552
	global_load_lds_dwordx4 v[242:243], off
	v_lshl_add_u64 v[244:245], s[30:31], 0, v[186:187]
	s_mov_b32 m0, s39
	s_nop 0
	global_load_lds_dwordx4 v[244:245], off
	s_waitcnt lgkmcnt(0)
	s_setprio 1
	s_barrier
	v_mfma_f32_16x16x32_bf16 v[92:95], v[128:131], v[144:147], v[92:95]
	v_mfma_f32_16x16x32_bf16 v[88:91], v[136:139], v[144:147], v[88:91]
	v_mfma_f32_16x16x32_bf16 v[84:87], v[128:131], v[152:155], v[84:87]
	v_mfma_f32_16x16x32_bf16 v[80:83], v[136:139], v[152:155], v[80:83]
	v_mfma_f32_16x16x32_bf16 v[76:79], v[128:131], v[198:201], v[76:79]
	v_mfma_f32_16x16x32_bf16 v[72:75], v[136:139], v[198:201], v[72:75]
	v_mfma_f32_16x16x32_bf16 v[68:71], v[128:131], v[206:209], v[68:71]
	v_mfma_f32_16x16x32_bf16 v[64:67], v[136:139], v[206:209], v[64:67]
	v_mfma_f32_16x16x32_bf16 v[92:95], v[132:135], v[148:151], v[92:95]
	v_mfma_f32_16x16x32_bf16 v[88:91], v[140:143], v[148:151], v[88:91]
	v_mfma_f32_16x16x32_bf16 v[84:87], v[132:135], v[194:197], v[84:87]
	v_mfma_f32_16x16x32_bf16 v[80:83], v[140:143], v[194:197], v[80:83]
	v_mfma_f32_16x16x32_bf16 v[76:79], v[132:135], v[202:205], v[76:79]
	v_mfma_f32_16x16x32_bf16 v[72:75], v[140:143], v[202:205], v[72:75]
	v_mfma_f32_16x16x32_bf16 v[68:71], v[132:135], v[210:213], v[68:71]
	v_mfma_f32_16x16x32_bf16 v[64:67], v[140:143], v[210:213], v[64:67]
	s_setprio 0
	s_barrier
; #define PG8_STAGE(bufoff, gbase) do { _Pragma("unroll") for (int _i = 0; _i < 2; ++_i) \
;         __builtin_amdgcn_global_load_lds((const unsigned*)((const char*)(gbase) + voff[_i]), (LAS unsigned*)(lds + (bufoff) + ldsw + _i * 8192), 16, 0, 0); } while (0)
; #define PG8_LDA(dst, b, h) do { _Pragma("unroll") for (int m = 0; m < 4; ++m) _Pragma("unroll") for (int k = 0; k < 2; ++k) dst[m][k] = *(const LAS bf16x8*)(lds + PG8_SA(b, h) + aoff + m * 2048 + k * 1024); } while (0)
; #define PG8_LDB(dst, b, h) do { _Pragma("unroll") for (int n = 0; n < 2; ++n) _Pragma("unroll") for (int k = 0; k < 2; ++k) dst[n][k] = *(const LAS bf16x8*)(lds + PG8_SB(b, h) + boff + n * 2048 + k * 1024); } while (0)
; #define PG8_MMA(ai, bj, At, Bt) do { __builtin_amdgcn_s_setprio(1); _Pragma("unroll") for (int m = 0; m < 4; ++m) _Pragma("unroll") for (int n = 0; n < 2; ++n) _Pragma("unroll") for (int k = 0; k < 2; ++k) \
;         acc[ai][bj][m][n] = __builtin_amdgcn_mfma_f32_16x16x32_bf16(Bt[n][k], At[m][k], acc[ai][bj][m][n], 0, 0, 0); __builtin_amdgcn_s_setprio(0); } while (0)
; #define PG8_WAIT_V(n) asm volatile("s_waitcnt vmcnt(" #n ")" ::: "memory")
; #define PG8_WAIT_L(n) asm volatile("s_waitcnt lgkmcnt(" #n ")" ::: "memory")
; #define PG8_BAR __builtin_amdgcn_s_barrier()
; #define PG8_SCHED __builtin_amdgcn_sched_barrier(0)
; template <class Epi>
; DI void gemm_phase(LAS unsigned char* lds, const Gemm g, const StaticOrder& S, const Epi& E) {
;     ...
;             PG8_STAGE(PG8_SB(0, 1), b2 + hstep);
;             PG8_WAIT_V(6); PG8_BAR; PG8_MMA(1, 1, At, B1); PG8_BAR;
;             PG8_LDB(B0, 1, 0); PG8_SCHED; PG8_LDA(At, 1, 0); PG8_STAGE(PG8_SA(0, 1), a2 + hstep);
;             PG8_WAIT_L(8); PG8_BAR; PG8_WAIT_L(0); PG8_MMA(0, 0, At, B0); PG8_BAR; PG8_SCHED;
;             PG8_LDB(B1, 1, 1); PG8_STAGE(PG8_SB(1, 0), b3);
;             PG8_BAR; PG8_WAIT_L(0); PG8_MMA(0, 1, At, B1); PG8_BAR;
;             PG8_LDA(At, 1, 1); PG8_STAGE(PG8_SA(1, 0), a3);
;             PG8_BAR; PG8_WAIT_L(0); PG8_MMA(1, 0, At, B0); PG8_BAR; PG8_SCHED;
	s_add_u32 s24, s28, 0x80000
	s_addc_u32 s25, s29, 0
	s_add_i32 s47, s48, s37
	v_lshl_add_u64 v[128:129], s[24:25], 0, v[188:189]
	s_mov_b32 m0, s47
	s_nop 0
	global_load_lds_dwordx4 v[128:129], off
	v_lshl_add_u64 v[128:129], s[24:25], 0, v[186:187]
	s_add_i32 m0, s47, 0x2000
	s_nop 0
	global_load_lds_dwordx4 v[128:129], off
	s_waitcnt vmcnt(6)
	s_setprio 1
	s_barrier
	v_mfma_f32_16x16x32_bf16 v[28:31], v[214:217], v[144:147], v[28:31]
	v_mfma_f32_16x16x32_bf16 v[24:27], v[234:237], v[144:147], v[24:27]
	v_mfma_f32_16x16x32_bf16 v[20:23], v[214:217], v[152:155], v[20:23]
	v_mfma_f32_16x16x32_bf16 v[16:19], v[234:237], v[152:155], v[16:19]
	v_mfma_f32_16x16x32_bf16 v[12:15], v[214:217], v[198:201], v[12:15]
	v_mfma_f32_16x16x32_bf16 v[8:11], v[234:237], v[198:201], v[8:11]
	v_mfma_f32_16x16x32_bf16 v[4:7], v[214:217], v[206:209], v[4:7]
	v_mfma_f32_16x16x32_bf16 v[0:3], v[234:237], v[206:209], v[0:3]
	v_mfma_f32_16x16x32_bf16 v[28:31], v[230:233], v[148:151], v[28:31]
	s_add_i32 s47, 0, 0x18000
	v_mfma_f32_16x16x32_bf16 v[24:27], v[238:241], v[148:151], v[24:27]
	v_add_u32_e32 v140, s47, v226
	v_mfma_f32_16x16x32_bf16 v[20:23], v[230:233], v[194:197], v[20:23]
	v_mfma_f32_16x16x32_bf16 v[16:19], v[238:241], v[194:197], v[16:19]
	v_mfma_f32_16x16x32_bf16 v[12:15], v[230:233], v[202:205], v[12:15]
	v_mfma_f32_16x16x32_bf16 v[8:11], v[238:241], v[202:205], v[8:11]
	v_mfma_f32_16x16x32_bf16 v[4:7], v[230:233], v[210:213], v[4:7]
	v_mfma_f32_16x16x32_bf16 v[0:3], v[238:241], v[210:213], v[0:3]
	s_setprio 0
	s_barrier
	ds_read_b128 v[128:131], v140
	ds_read_b128 v[132:135], v140 offset:1024
	ds_read_b128 v[136:139], v140 offset:2048
	ds_read_b128 v[140:143], v140 offset:3072
	s_add_u32 s24, s30, 0x80000
	s_addc_u32 s25, s31, 0
	s_mov_b32 m0, s40
	v_lshl_add_u64 v[214:215], s[24:25], 0, v[188:189]
	ds_read_b128 v[144:147], v228 offset:32768
	ds_read_b128 v[148:151], v228 offset:33792
	ds_read_b128 v[152:155], v228 offset:34816
	ds_read_b128 v[194:197], v228 offset:35840
	ds_read_b128 v[198:201], v228 offset:36864
	ds_read_b128 v[202:205], v228 offset:37888
	ds_read_b128 v[206:209], v228 offset:38912
	ds_read_b128 v[210:213], v228 offset:39936
	global_load_lds_dwordx4 v[214:215], off
	v_lshl_add_u64 v[214:215], s[24:25], 0, v[186:187]
	s_mov_b32 m0, s41
	s_nop 0
	global_load_lds_dwordx4 v[214:215], off
	s_waitcnt lgkmcnt(8)
	s_setprio 1
	s_barrier
	s_waitcnt lgkmcnt(0)
	v_mfma_f32_16x16x32_bf16 v[124:127], v[128:131], v[144:147], v[124:127]
	v_mfma_f32_16x16x32_bf16 v[120:123], v[136:139], v[144:147], v[120:123]
	v_mfma_f32_16x16x32_bf16 v[116:119], v[128:131], v[152:155], v[116:119]
	v_mfma_f32_16x16x32_bf16 v[112:115], v[136:139], v[152:155], v[112:115]
	v_mfma_f32_16x16x32_bf16 v[108:111], v[128:131], v[198:201], v[108:111]
	v_mfma_f32_16x16x32_bf16 v[104:107], v[136:139], v[198:201], v[104:107]
	v_mfma_f32_16x16x32_bf16 v[100:103], v[128:131], v[206:209], v[100:103]
	v_mfma_f32_16x16x32_bf16 v[96:99], v[136:139], v[206:209], v[96:99]
	v_mfma_f32_16x16x32_bf16 v[124:127], v[132:135], v[148:151], v[124:127]
	v_mfma_f32_16x16x32_bf16 v[120:123], v[140:143], v[148:151], v[120:123]
	v_mfma_f32_16x16x32_bf16 v[116:119], v[132:135], v[194:197], v[116:119]
	v_mfma_f32_16x16x32_bf16 v[112:115], v[140:143], v[194:197], v[112:115]
	v_mfma_f32_16x16x32_bf16 v[108:111], v[132:135], v[202:205], v[108:111]
	v_mfma_f32_16x16x32_bf16 v[104:107], v[140:143], v[202:205], v[104:107]
	v_mfma_f32_16x16x32_bf16 v[100:103], v[132:135], v[210:213], v[100:103]
	v_mfma_f32_16x16x32_bf16 v[96:99], v[140:143], v[210:213], v[96:99]
	s_setprio 0
	s_barrier
	s_add_i32 s30, 0, 0x1c000
	s_add_i32 s24, s47, s37
	v_add_u32_e32 v158, s30, v226
	v_lshl_add_u64 v[218:219], v[218:219], 0, s[94:95]
	s_mov_b32 m0, s24
	ds_read_b128 v[214:217], v158
	ds_read_b128 v[230:233], v158 offset:1024
	ds_read_b128 v[234:237], v158 offset:2048
	ds_read_b128 v[238:241], v158 offset:3072
	global_load_lds_dwordx4 v[218:219], off
	v_lshl_add_u64 v[218:219], v[220:221], 0, s[94:95]
	s_add_i32 m0, s24, 0x2000
	s_nop 0
	global_load_lds_dwordx4 v[218:219], off
	s_waitcnt lgkmcnt(0)
	s_setprio 1
	s_barrier
	v_mfma_f32_16x16x32_bf16 v[60:63], v[214:217], v[144:147], v[60:63]
	v_mfma_f32_16x16x32_bf16 v[56:59], v[234:237], v[144:147], v[56:59]
	v_mfma_f32_16x16x32_bf16 v[52:55], v[214:217], v[152:155], v[52:55]
	v_mfma_f32_16x16x32_bf16 v[48:51], v[234:237], v[152:155], v[48:51]
	v_mfma_f32_16x16x32_bf16 v[44:47], v[214:217], v[198:201], v[44:47]
	v_mfma_f32_16x16x32_bf16 v[40:43], v[234:237], v[198:201], v[40:43]
	v_mfma_f32_16x16x32_bf16 v[36:39], v[214:217], v[206:209], v[36:39]
	v_mfma_f32_16x16x32_bf16 v[32:35], v[234:237], v[206:209], v[32:35]
	v_mfma_f32_16x16x32_bf16 v[60:63], v[230:233], v[148:151], v[60:63]
	s_mov_b32 m0, s42
	v_mfma_f32_16x16x32_bf16 v[56:59], v[238:241], v[148:151], v[56:59]
	v_lshl_add_u64 v[218:219], v[242:243], 0, s[94:95]
	v_mfma_f32_16x16x32_bf16 v[52:55], v[230:233], v[194:197], v[52:55]
	v_mfma_f32_16x16x32_bf16 v[48:51], v[238:241], v[194:197], v[48:51]
	v_mfma_f32_16x16x32_bf16 v[44:47], v[230:233], v[202:205], v[44:47]
	v_mfma_f32_16x16x32_bf16 v[40:43], v[238:241], v[202:205], v[40:43]
	v_mfma_f32_16x16x32_bf16 v[36:39], v[230:233], v[210:213], v[36:39]
	v_mfma_f32_16x16x32_bf16 v[32:35], v[238:241], v[210:213], v[32:35]
	s_setprio 0
	s_barrier
	ds_read_b128 v[144:147], v228 offset:49152
	ds_read_b128 v[148:151], v228 offset:50176
	ds_read_b128 v[152:155], v228 offset:51200
	ds_read_b128 v[194:197], v228 offset:52224
	ds_read_b128 v[198:201], v228 offset:53248
	ds_read_b128 v[202:205], v228 offset:54272
	ds_read_b128 v[206:209], v228 offset:55296
	ds_read_b128 v[210:213], v228 offset:56320
	global_load_lds_dwordx4 v[218:219], off
	v_lshl_add_u64 v[218:219], v[244:245], 0, s[94:95]
	s_mov_b32 m0, s43
	s_nop 0
	global_load_lds_dwordx4 v[218:219], off
	s_waitcnt lgkmcnt(0)
	s_setprio 1
	s_barrier
; #define PG8_STAGE(bufoff, gbase) do { _Pragma("unroll") for (int _i = 0; _i < 2; ++_i) \
;         __builtin_amdgcn_global_load_lds((const unsigned*)((const char*)(gbase) + voff[_i]), (LAS unsigned*)(lds + (bufoff) + ldsw + _i * 8192), 16, 0, 0); } while (0)
; #define PG8_MMA(ai, bj, At, Bt) do { __builtin_amdgcn_s_setprio(1); _Pragma("unroll") for (int m = 0; m < 4; ++m) _Pragma("unroll") for (int n = 0; n < 2; ++n) _Pragma("unroll") for (int k = 0; k < 2; ++k) \
;         acc[ai][bj][m][n] = __builtin_amdgcn_mfma_f32_16x16x32_bf16(Bt[n][k], At[m][k], acc[ai][bj][m][n], 0, 0, 0); __builtin_amdgcn_s_setprio(0); } while (0)
; #define PG8_WAIT_V(n) asm volatile("s_waitcnt vmcnt(" #n ")" ::: "memory")
; #define PG8_WAIT_L(n) asm volatile("s_waitcnt lgkmcnt(" #n ")" ::: "memory")
; #define PG8_BAR __builtin_amdgcn_s_barrier()
; #define PG8_SCHED __builtin_amdgcn_sched_barrier(0)
; template <class Epi>
; DI void gemm_phase(LAS unsigned char* lds, const Gemm g, const StaticOrder& S, const Epi& E) {
;     ...
;             PG8_BAR; PG8_WAIT_L(0); PG8_MMA(1, 0, At, B0); PG8_BAR; PG8_SCHED;
;             PG8_STAGE(PG8_SB(1, 1), b3 + hstep);
;             PG8_WAIT_V(6); PG8_BAR; PG8_MMA(1, 1, At, B1); PG8_BAR;
;     template <bool LN, int BJ> DI void load_gb(unsigned col0, f32x4 (&gv)[2], f32x4 (&bv)[2]) const {
; #pragma unroll
;         for (int n = 0; n < 2; ++n) {
;             if (LN) { gv[n] = *(const f32x4*)(gam + col0 + BJ * HALF + n * 16) * ALPHA; bv[n] = *(const f32x4*)(bet + col0 + BJ * HALF + n * 16) * ALPHA; }
;             else { gv[n] = (f32x4){ALPHA, ALPHA, ALPHA, ALPHA}; bv[n] = (f32x4){0.f, 0.f, 0.f, 0.f}; }
;         }
;     }
;     template <bool LN> DI void run(const f32x4 (&acc)[2][2][4][2], const Unit& u, int wr, int wc, int fr, int fq) const {
;         const unsigned row0 = u.pm * BM + wr * 64 + fr, col0 = u.pn * BM + wc * 32 + 4 * fq;
;         f32x4 gv[2], bv[2];
;         load_gb<LN, 0>(col0, gv, bv);
;         batch<LN, 0, 0, 4>(acc, row0, col0, gv, bv);
	v_mfma_f32_16x16x32_bf16 v[92:95], v[128:131], v[144:147], v[92:95]
	v_mfma_f32_16x16x32_bf16 v[88:91], v[136:139], v[144:147], v[88:91]
	v_mfma_f32_16x16x32_bf16 v[84:87], v[128:131], v[152:155], v[84:87]
	v_mfma_f32_16x16x32_bf16 v[80:83], v[136:139], v[152:155], v[80:83]
	v_mfma_f32_16x16x32_bf16 v[76:79], v[128:131], v[198:201], v[76:79]
	v_mfma_f32_16x16x32_bf16 v[72:75], v[136:139], v[198:201], v[72:75]
	v_mfma_f32_16x16x32_bf16 v[68:71], v[128:131], v[206:209], v[68:71]
	v_mfma_f32_16x16x32_bf16 v[64:67], v[136:139], v[206:209], v[64:67]
	v_mfma_f32_16x16x32_bf16 v[92:95], v[132:135], v[148:151], v[92:95]
	v_mfma_f32_16x16x32_bf16 v[88:91], v[140:143], v[148:151], v[88:91]
	v_mfma_f32_16x16x32_bf16 v[84:87], v[132:135], v[194:197], v[84:87]
	v_mfma_f32_16x16x32_bf16 v[80:83], v[140:143], v[194:197], v[80:83]
	v_mfma_f32_16x16x32_bf16 v[76:79], v[132:135], v[202:205], v[76:79]
	v_mfma_f32_16x16x32_bf16 v[72:75], v[140:143], v[202:205], v[72:75]
	v_mfma_f32_16x16x32_bf16 v[68:71], v[132:135], v[210:213], v[68:71]
	v_mfma_f32_16x16x32_bf16 v[64:67], v[140:143], v[210:213], v[64:67]
	s_setprio 0
	s_barrier
	s_add_u32 s24, s28, 0x80080
	s_addc_u32 s25, s29, 0
	s_add_i32 s28, s30, s37
	v_lshl_add_u64 v[128:129], s[24:25], 0, v[188:189]
	s_mov_b32 m0, s28
	s_nop 0
	global_load_lds_dwordx4 v[128:129], off
	v_lshl_add_u64 v[128:129], s[24:25], 0, v[186:187]
	s_add_i32 m0, s28, 0x2000
	s_nop 0
	global_load_lds_dwordx4 v[128:129], off
	s_waitcnt vmcnt(6)
	s_setprio 1
	s_barrier
	v_mfma_f32_16x16x32_bf16 v[28:31], v[214:217], v[144:147], v[28:31]
	v_mfma_f32_16x16x32_bf16 v[24:27], v[234:237], v[144:147], v[24:27]
	v_mfma_f32_16x16x32_bf16 v[20:23], v[214:217], v[152:155], v[20:23]
	v_mfma_f32_16x16x32_bf16 v[16:19], v[234:237], v[152:155], v[16:19]
	v_mfma_f32_16x16x32_bf16 v[12:15], v[214:217], v[198:201], v[12:15]
	v_mfma_f32_16x16x32_bf16 v[8:11], v[234:237], v[198:201], v[8:11]
	v_mfma_f32_16x16x32_bf16 v[4:7], v[214:217], v[206:209], v[4:7]
	v_mfma_f32_16x16x32_bf16 v[0:3], v[234:237], v[206:209], v[0:3]
	v_mfma_f32_16x16x32_bf16 v[28:31], v[230:233], v[148:151], v[28:31]
	s_add_i32 s46, s46, 2
	v_mfma_f32_16x16x32_bf16 v[24:27], v[238:241], v[148:151], v[24:27]
	s_add_u32 s33, s33, 0x100
	v_mfma_f32_16x16x32_bf16 v[20:23], v[230:233], v[194:197], v[20:23]
	s_addc_u32 s45, s45, 0
	v_mfma_f32_16x16x32_bf16 v[16:19], v[238:241], v[194:197], v[16:19]
	s_cmp_gt_u32 s46, 29
	v_mfma_f32_16x16x32_bf16 v[12:15], v[230:233], v[202:205], v[12:15]
	s_mov_b64 s[24:25], s[26:27]
	v_mfma_f32_16x16x32_bf16 v[8:11], v[238:241], v[202:205], v[8:11]
	v_mfma_f32_16x16x32_bf16 v[4:7], v[230:233], v[210:213], v[4:7]
	v_mfma_f32_16x16x32_bf16 v[0:3], v[238:241], v[210:213], v[0:3]
	s_setprio 0
	s_barrier
	s_cbranch_scc0 .LBB0_320
	v_lshl_add_u32 v206, s3, 8, v225
	v_lshl_or_b32 v158, s2, 8, v227
	v_lshlrev_b32_e32 v232, 11, v206
	s_andn2_b64 vcc, exec, s[14:15]
	v_or_b32_e32 v231, 16, v158
	v_add_u32_e32 v194, v232, v158
	v_or_b32_e32 v230, 0x80, v158
	v_or_b32_e32 v229, 0x90, v158
	s_cbranch_vccnz .LBB0_323
	v_lshlrev_b64 v[132:133], 2, v[158:159]
	v_lshl_add_u64 v[140:141], s[16:17], 0, v[132:133]
	global_load_dwordx4 v[128:131], v[140:141], off
	v_lshl_add_u64 v[142:143], s[18:19], 0, v[132:133]
	v_readlane_b32 s2, v253, 8
	v_mov_b32_e32 v195, v159
	v_lshlrev_b32_e32 v136, 1, v206
	v_mov_b32_e32 v137, v159
	v_readlane_b32 s3, v253, 9
	v_lshlrev_b64 v[212:213], 2, v[194:195]
	v_add_u32_e32 v146, v232, v231
	v_lshl_add_u64 v[144:145], v[136:137], 2, s[2:3]
	v_lshl_add_u64 v[136:137], s[88:89], 0, v[212:213]
	v_mov_b32_e32 v147, v159
	v_lshl_add_u64 v[146:147], v[146:147], 2, s[88:89]
	v_or_b32_e32 v195, 16, v206
	v_mov_b32_e32 v201, v159
	v_mov_b32_e32 v209, v159
	v_lshl_add_u64 v[212:213], s[90:91], 0, v[212:213]
	s_waitcnt vmcnt(0)
	v_pk_mul_f32 v[152:153], v[130:131], s[78:79] op_sel_hi:[1,0]
	v_pk_mul_f32 v[154:155], v[128:129], s[78:79] op_sel_hi:[1,0]
	global_load_dwordx4 v[132:135], v[142:143], off
	global_load_dwordx4 v[128:131], v[140:141], off offset:64
	global_load_dwordx2 v[204:205], v[144:145], off
	global_load_dwordx4 v[196:199], v[146:147], off
	v_lshlrev_b32_e32 v146, 1, v195
	global_load_dwordx4 v[136:139], v[136:137], off
	v_lshlrev_b32_e32 v195, 11, v195
	v_mov_b32_e32 v147, v159
	v_add_u32_e32 v200, v195, v158
	v_lshl_add_u64 v[146:147], v[146:147], 2, s[2:3]
	v_lshl_add_u64 v[200:201], v[200:201], 2, s[88:89]
	global_load_dwordx2 v[214:215], v[146:147], off
	v_add_u32_e32 v208, v195, v231
	global_load_dwordx4 v[200:203], v[200:201], off
	v_lshl_add_u64 v[208:209], v[208:209], 2, s[88:89]
	global_load_dwordx4 v[208:211], v[208:209], off
	s_waitcnt vmcnt(0)
	v_pk_mul_f32 v[148:149], v[130:131], s[78:79] op_sel_hi:[1,0]
	v_pk_mul_f32 v[150:151], v[128:129], s[78:79] op_sel_hi:[1,0]
	global_load_dwordx4 v[128:131], v[142:143], off offset:64
	v_sub_f32_e32 v137, v137, v204
	v_sub_f32_e32 v136, v136, v204
	v_sub_f32_e32 v139, v139, v204
	v_sub_f32_e32 v138, v138, v204
	v_pk_mul_f32 v[138:139], v[204:205], v[138:139] op_sel:[1,0]
	v_pk_mul_f32 v[136:137], v[204:205], v[136:137] op_sel:[1,0]
	v_pk_fma_f32 v[138:139], v[152:153], v[138:139], v[126:127]
	v_pk_fma_f32 v[136:137], v[154:155], v[136:137], v[124:125]
	v_pk_fma_f32 v[138:139], v[134:135], s[78:79], v[138:139] op_sel_hi:[1,0,1]
	v_pk_fma_f32 v[136:137], v[132:133], s[78:79], v[136:137] op_sel_hi:[1,0,1]
	global_store_dwordx4 v[212:213], v[136:139], off
	s_nop 1
	v_sub_f32_e32 v137, v197, v204
	v_sub_f32_e32 v136, v196, v204
	v_sub_f32_e32 v139, v199, v204
	v_sub_f32_e32 v138, v198, v204
	v_pk_mul_f32 v[138:139], v[204:205], v[138:139] op_sel:[1,0]
	v_pk_mul_f32 v[136:137], v[204:205], v[136:137] op_sel:[1,0]
	v_pk_fma_f32 v[138:139], v[148:149], v[138:139], v[122:123]
	v_pk_fma_f32 v[136:137], v[150:151], v[136:137], v[120:121]
	v_or_b32_e32 v196, 16, v194
	v_mov_b32_e32 v197, v159
	v_lshl_add_u64 v[196:197], v[196:197], 2, s[90:91]
	s_waitcnt vmcnt(0)
;     template <bool LN, int BJ, int LO, int HI> DI void batch(const f32x4 (&acc)[2][2][4][2], unsigned row0, unsigned col0, const f32x4 (&gv)[2], const f32x4 (&bv)[2]) const {
;     ...
;         for (int i = LO; i < HI; ++i) { const int ai = i >> 3, m = (i >> 1) & 3, n = i & 1; const unsigned row = row0 + ai * HALF + m * 16;
;             if (n == 0) { mean[(i - LO) >> 1] = 0.f; rstd[(i - LO) >> 1] = 1.f;
;                 if (LN) { const float2 st = *(const float2*)(stats + row * 2u); mean[(i - LO) >> 1] = st.x; rstd[(i - LO) >> 1] = st.y; } }
;             r[i - LO] = *(const f32x4*)(src + (row * (unsigned)DM + col0 + BJ * HALF + n * 16)); }
; #pragma unroll
;         for (int i = LO; i < HI; ++i) { const int ai = i >> 3, m = (i >> 1) & 3, n = i & 1; const unsigned row = row0 + ai * HALF + m * 16;
;             *(f32x4*)(Y + (row * (unsigned)DM + col0 + BJ * HALF + n * 16)) = acc[ai][BJ][m][n] + ((r[i - LO] - mean[(i - LO) >> 1]) * rstd[(i - LO) >> 1]) * gv[n] + bv[n]; }
	v_pk_fma_f32 v[138:139], v[130:131], s[78:79], v[138:139] op_sel_hi:[1,0,1]
	v_pk_fma_f32 v[136:137], v[128:129], s[78:79], v[136:137] op_sel_hi:[1,0,1]
	global_store_dwordx4 v[196:197], v[136:139], off
	v_add_u32_e32 v196, 0x8000, v194
	v_mov_b32_e32 v197, v159
	v_sub_f32_e32 v137, v201, v214
	v_sub_f32_e32 v136, v200, v214
	v_sub_f32_e32 v139, v203, v214
	v_sub_f32_e32 v138, v202, v214
	v_pk_mul_f32 v[138:139], v[214:215], v[138:139] op_sel:[1,0]
	v_pk_mul_f32 v[136:137], v[214:215], v[136:137] op_sel:[1,0]
	v_pk_fma_f32 v[138:139], v[152:153], v[138:139], v[118:119]
	v_pk_fma_f32 v[136:137], v[154:155], v[136:137], v[116:117]
	v_pk_fma_f32 v[138:139], v[134:135], s[78:79], v[138:139] op_sel_hi:[1,0,1]
	v_pk_fma_f32 v[136:137], v[132:133], s[78:79], v[136:137] op_sel_hi:[1,0,1]
	v_lshl_add_u64 v[196:197], v[196:197], 2, s[90:91]
	global_store_dwordx4 v[196:197], v[136:139], off
	v_add_u32_e32 v196, 0x8010, v194
	v_mov_b32_e32 v197, v159
	v_sub_f32_e32 v137, v209, v214
	v_sub_f32_e32 v136, v208, v214
	v_sub_f32_e32 v139, v211, v214
	v_sub_f32_e32 v138, v210, v214
	v_pk_mul_f32 v[138:139], v[214:215], v[138:139] op_sel:[1,0]
	v_pk_mul_f32 v[136:137], v[214:215], v[136:137] op_sel:[1,0]
	v_pk_fma_f32 v[138:139], v[148:149], v[138:139], v[114:115]
	v_pk_fma_f32 v[136:137], v[150:151], v[136:137], v[112:113]
	v_pk_fma_f32 v[138:139], v[130:131], s[78:79], v[138:139] op_sel_hi:[1,0,1]
	v_pk_fma_f32 v[136:137], v[128:129], s[78:79], v[136:137] op_sel_hi:[1,0,1]
	v_lshl_add_u64 v[196:197], v[196:197], 2, s[90:91]
	global_store_dwordx4 v[196:197], v[136:139], off
	s_nop 1
	v_or_b32_e32 v138, 32, v206
	v_lshlrev_b32_e32 v136, 1, v138
	v_mov_b32_e32 v137, v159
	v_lshlrev_b32_e32 v236, 11, v138
	v_lshl_add_u64 v[200:201], v[136:137], 2, s[2:3]
	v_add_u32_e32 v136, v236, v158
	v_lshl_add_u64 v[136:137], v[136:137], 2, s[88:89]
	global_load_dwordx2 v[204:205], v[200:201], off
	v_add_u32_e32 v196, v236, v231
	global_load_dwordx4 v[136:139], v[136:137], off
	v_mov_b32_e32 v197, v159
	v_lshl_add_u64 v[196:197], v[196:197], 2, s[88:89]
	global_load_dwordx4 v[196:199], v[196:197], off
	v_or_b32_e32 v207, 48, v206
	v_lshlrev_b32_e32 v235, 11, v207
	v_lshlrev_b32_e32 v202, 1, v207
	v_mov_b32_e32 v203, v159
	v_add_u32_e32 v208, v235, v158
	v_mov_b32_e32 v209, v159
	v_lshl_add_u64 v[202:203], v[202:203], 2, s[2:3]
	v_lshl_add_u64 v[208:209], v[208:209], 2, s[88:89]
	global_load_dwordx2 v[216:217], v[202:203], off
	v_add_u32_e32 v212, v235, v231
	global_load_dwordx4 v[208:211], v[208:209], off
	v_mov_b32_e32 v213, v159
	v_lshl_add_u64 v[212:213], v[212:213], 2, s[88:89]
	global_load_dwordx4 v[212:215], v[212:213], off
	v_add_u32_e32 v218, 0x10000, v194
	v_mov_b32_e32 v219, v159
	v_lshl_add_u64 v[218:219], v[218:219], 2, s[90:91]
	s_waitcnt vmcnt(0)
	v_sub_f32_e32 v137, v137, v204
	v_sub_f32_e32 v136, v136, v204
	v_sub_f32_e32 v139, v139, v204
	v_sub_f32_e32 v138, v138, v204
	v_pk_mul_f32 v[138:139], v[204:205], v[138:139] op_sel:[1,0]
	v_pk_mul_f32 v[136:137], v[204:205], v[136:137] op_sel:[1,0]
	v_pk_fma_f32 v[138:139], v[152:153], v[138:139], v[110:111]
	v_pk_fma_f32 v[136:137], v[154:155], v[136:137], v[108:109]
	v_pk_fma_f32 v[138:139], v[134:135], s[78:79], v[138:139] op_sel_hi:[1,0,1]
	v_pk_fma_f32 v[136:137], v[132:133], s[78:79], v[136:137] op_sel_hi:[1,0,1]
	global_store_dwordx4 v[218:219], v[136:139], off
	s_nop 1
	v_sub_f32_e32 v137, v197, v204
	v_sub_f32_e32 v136, v196, v204
	v_sub_f32_e32 v139, v199, v204
	v_sub_f32_e32 v138, v198, v204
	v_pk_mul_f32 v[138:139], v[204:205], v[138:139] op_sel:[1,0]
	v_pk_mul_f32 v[136:137], v[204:205], v[136:137] op_sel:[1,0]
	v_pk_fma_f32 v[138:139], v[148:149], v[138:139], v[106:107]
	v_pk_fma_f32 v[136:137], v[150:151], v[136:137], v[104:105]
	v_add_u32_e32 v196, 0x10010, v194
	v_mov_b32_e32 v197, v159
	v_pk_fma_f32 v[138:139], v[130:131], s[78:79], v[138:139] op_sel_hi:[1,0,1]
	v_pk_fma_f32 v[136:137], v[128:129], s[78:79], v[136:137] op_sel_hi:[1,0,1]
	v_lshl_add_u64 v[196:197], v[196:197], 2, s[90:91]
	global_store_dwordx4 v[196:197], v[136:139], off
	v_add_u32_e32 v196, 0x18000, v194
	v_mov_b32_e32 v197, v159
	v_sub_f32_e32 v137, v209, v216
	v_sub_f32_e32 v136, v208, v216
	v_sub_f32_e32 v139, v211, v216
	v_sub_f32_e32 v138, v210, v216
	v_pk_mul_f32 v[138:139], v[216:217], v[138:139] op_sel:[1,0]
	v_pk_mul_f32 v[136:137], v[216:217], v[136:137] op_sel:[1,0]
	v_pk_fma_f32 v[138:139], v[152:153], v[138:139], v[102:103]
	v_pk_fma_f32 v[136:137], v[154:155], v[136:137], v[100:101]
	v_pk_fma_f32 v[138:139], v[134:135], s[78:79], v[138:139] op_sel_hi:[1,0,1]
	v_pk_fma_f32 v[136:137], v[132:133], s[78:79], v[136:137] op_sel_hi:[1,0,1]
	v_lshl_add_u64 v[196:197], v[196:197], 2, s[90:91]
	global_store_dwordx4 v[196:197], v[136:139], off
	v_add_u32_e32 v196, 0x18010, v194
	v_mov_b32_e32 v197, v159
	v_sub_f32_e32 v137, v213, v216
	v_sub_f32_e32 v136, v212, v216
	v_sub_f32_e32 v139, v215, v216
	v_sub_f32_e32 v138, v214, v216
	v_pk_mul_f32 v[138:139], v[216:217], v[138:139] op_sel:[1,0]
	v_pk_mul_f32 v[136:137], v[216:217], v[136:137] op_sel:[1,0]
	v_pk_fma_f32 v[138:139], v[148:149], v[138:139], v[98:99]
	v_pk_fma_f32 v[136:137], v[150:151], v[136:137], v[96:97]
	v_pk_fma_f32 v[138:139], v[130:131], s[78:79], v[138:139] op_sel_hi:[1,0,1]
	v_pk_fma_f32 v[136:137], v[128:129], s[78:79], v[136:137] op_sel_hi:[1,0,1]
	v_lshl_add_u64 v[196:197], v[196:197], 2, s[90:91]
	global_store_dwordx4 v[196:197], v[136:139], off
	s_nop 1
	v_add_u32_e32 v138, 0x80, v206
	v_lshlrev_b32_e32 v136, 1, v138
	v_mov_b32_e32 v137, v159
	v_lshlrev_b32_e32 v233, 11, v138
	v_lshl_add_u64 v[196:197], v[136:137], 2, s[2:3]
	v_add_u32_e32 v136, v233, v158
	v_lshl_add_u64 v[136:137], v[136:137], 2, s[88:89]
	global_load_dwordx2 v[204:205], v[196:197], off
	v_add_u32_e32 v198, v233, v231
	global_load_dwordx4 v[136:139], v[136:137], off
	v_mov_b32_e32 v199, v159
	v_add_u32_e32 v207, 0x90, v206
	v_lshl_add_u64 v[198:199], v[198:199], 2, s[88:89]
	v_lshlrev_b32_e32 v234, 11, v207
	global_load_dwordx4 v[208:211], v[198:199], off
	v_add_u32_e32 v212, v234, v158
	v_mov_b32_e32 v213, v159
	v_lshl_add_u64 v[212:213], v[212:213], 2, s[88:89]
	global_load_dwordx4 v[212:215], v[212:213], off
	v_lshlrev_b32_e32 v198, 1, v207
	v_mov_b32_e32 v199, v159
	v_lshl_add_u64 v[198:199], v[198:199], 2, s[2:3]
	global_load_dwordx2 v[238:239], v[198:199], off
	v_add_u32_e32 v216, v234, v231
	v_mov_b32_e32 v217, v159
	v_lshl_add_u64 v[216:217], v[216:217], 2, s[88:89]
	global_load_dwordx4 v[216:219], v[216:217], off
	v_add_u32_e32 v240, 0x40000, v194
	v_mov_b32_e32 v241, v159
	v_lshl_add_u64 v[240:241], v[240:241], 2, s[90:91]
	s_waitcnt vmcnt(0)
;     template <bool LN, int BJ, int LO, int HI> DI void batch(const f32x4 (&acc)[2][2][4][2], unsigned row0, unsigned col0, const f32x4 (&gv)[2], const f32x4 (&bv)[2]) const {
;     ...
;         for (int i = LO; i < HI; ++i) { const int ai = i >> 3, m = (i >> 1) & 3, n = i & 1; const unsigned row = row0 + ai * HALF + m * 16;
;             if (n == 0) { mean[(i - LO) >> 1] = 0.f; rstd[(i - LO) >> 1] = 1.f;
;                 if (LN) { const float2 st = *(const float2*)(stats + row * 2u); mean[(i - LO) >> 1] = st.x; rstd[(i - LO) >> 1] = st.y; } }
;             r[i - LO] = *(const f32x4*)(src + (row * (unsigned)DM + col0 + BJ * HALF + n * 16)); }
; #pragma unroll
;         for (int i = LO; i < HI; ++i) { const int ai = i >> 3, m = (i >> 1) & 3, n = i & 1; const unsigned row = row0 + ai * HALF + m * 16;
;             *(f32x4*)(Y + (row * (unsigned)DM + col0 + BJ * HALF + n * 16)) = acc[ai][BJ][m][n] + ((r[i - LO] - mean[(i - LO) >> 1]) * rstd[(i - LO) >> 1]) * gv[n] + bv[n]; }
	v_sub_f32_e32 v137, v137, v204
	v_sub_f32_e32 v136, v136, v204
	v_sub_f32_e32 v139, v139, v204
	v_sub_f32_e32 v138, v138, v204
	v_pk_mul_f32 v[138:139], v[204:205], v[138:139] op_sel:[1,0]
	v_pk_mul_f32 v[136:137], v[204:205], v[136:137] op_sel:[1,0]
	v_pk_fma_f32 v[138:139], v[152:153], v[138:139], v[94:95]
	v_pk_fma_f32 v[136:137], v[154:155], v[136:137], v[92:93]
	v_pk_fma_f32 v[138:139], v[134:135], s[78:79], v[138:139] op_sel_hi:[1,0,1]
	v_pk_fma_f32 v[136:137], v[132:133], s[78:79], v[136:137] op_sel_hi:[1,0,1]
	global_store_dwordx4 v[240:241], v[136:139], off
	s_nop 1
	v_sub_f32_e32 v137, v209, v204
	v_sub_f32_e32 v136, v208, v204
	v_sub_f32_e32 v139, v211, v204
	v_sub_f32_e32 v138, v210, v204
	v_pk_mul_f32 v[138:139], v[204:205], v[138:139] op_sel:[1,0]
	v_pk_mul_f32 v[136:137], v[204:205], v[136:137] op_sel:[1,0]
	v_pk_fma_f32 v[138:139], v[148:149], v[138:139], v[90:91]
	v_pk_fma_f32 v[136:137], v[150:151], v[136:137], v[88:89]
	v_add_u32_e32 v204, 0x40010, v194
	v_mov_b32_e32 v205, v159
	v_pk_fma_f32 v[138:139], v[130:131], s[78:79], v[138:139] op_sel_hi:[1,0,1]
	v_pk_fma_f32 v[136:137], v[128:129], s[78:79], v[136:137] op_sel_hi:[1,0,1]
	v_lshl_add_u64 v[204:205], v[204:205], 2, s[90:91]
	global_store_dwordx4 v[204:205], v[136:139], off
	v_add_u32_e32 v204, 0x48000, v194
	v_mov_b32_e32 v205, v159
	v_sub_f32_e32 v137, v213, v238
	v_sub_f32_e32 v136, v212, v238
	v_sub_f32_e32 v139, v215, v238
	v_sub_f32_e32 v138, v214, v238
	v_pk_mul_f32 v[138:139], v[238:239], v[138:139] op_sel:[1,0]
	v_pk_mul_f32 v[136:137], v[238:239], v[136:137] op_sel:[1,0]
	v_pk_fma_f32 v[138:139], v[152:153], v[138:139], v[86:87]
	v_pk_fma_f32 v[136:137], v[154:155], v[136:137], v[84:85]
	v_pk_fma_f32 v[138:139], v[134:135], s[78:79], v[138:139] op_sel_hi:[1,0,1]
	v_pk_fma_f32 v[136:137], v[132:133], s[78:79], v[136:137] op_sel_hi:[1,0,1]
	v_lshl_add_u64 v[204:205], v[204:205], 2, s[90:91]
	global_store_dwordx4 v[204:205], v[136:139], off
	v_add_u32_e32 v204, 0x48010, v194
	v_mov_b32_e32 v205, v159
	v_sub_f32_e32 v137, v217, v238
	v_sub_f32_e32 v136, v216, v238
	v_sub_f32_e32 v139, v219, v238
	v_sub_f32_e32 v138, v218, v238
	v_pk_mul_f32 v[138:139], v[238:239], v[138:139] op_sel:[1,0]
	v_pk_mul_f32 v[136:137], v[238:239], v[136:137] op_sel:[1,0]
	v_pk_fma_f32 v[138:139], v[148:149], v[138:139], v[82:83]
	v_pk_fma_f32 v[136:137], v[150:151], v[136:137], v[80:81]
	v_pk_fma_f32 v[138:139], v[130:131], s[78:79], v[138:139] op_sel_hi:[1,0,1]
	v_pk_fma_f32 v[136:137], v[128:129], s[78:79], v[136:137] op_sel_hi:[1,0,1]
	v_lshl_add_u64 v[204:205], v[204:205], 2, s[90:91]
	global_store_dwordx4 v[204:205], v[136:139], off
	s_nop 1
	v_add_u32_e32 v138, 0xa0, v206
	v_lshlrev_b32_e32 v136, 1, v138
	v_mov_b32_e32 v137, v159
	v_lshlrev_b32_e32 v237, 11, v138
	v_lshl_add_u64 v[204:205], v[136:137], 2, s[2:3]
	v_add_u32_e32 v136, v237, v158
	v_lshl_add_u64 v[136:137], v[136:137], 2, s[88:89]
	global_load_dwordx2 v[240:241], v[204:205], off
	v_add_u32_e32 v208, v237, v231
	global_load_dwordx4 v[136:139], v[136:137], off
	v_mov_b32_e32 v209, v159
	v_lshl_add_u64 v[208:209], v[208:209], 2, s[88:89]
	global_load_dwordx4 v[212:215], v[208:209], off
	v_add_u32_e32 v208, 0xb0, v206
	v_lshlrev_b32_e32 v206, 1, v208
	v_mov_b32_e32 v207, v159
	v_lshlrev_b32_e32 v238, 11, v208
	v_lshl_add_u64 v[210:211], v[206:207], 2, s[2:3]
	v_add_u32_e32 v206, v238, v158
	v_lshl_add_u64 v[206:207], v[206:207], 2, s[88:89]
	global_load_dwordx2 v[242:243], v[210:211], off
	v_add_u32_e32 v216, v238, v231
	global_load_dwordx4 v[206:209], v[206:207], off
	v_mov_b32_e32 v217, v159
	v_lshl_add_u64 v[216:217], v[216:217], 2, s[88:89]
	global_load_dwordx4 v[216:219], v[216:217], off
	v_add_u32_e32 v244, 0x50000, v194
	v_mov_b32_e32 v245, v159
	v_lshl_add_u64 v[244:245], v[244:245], 2, s[90:91]
	s_waitcnt vmcnt(0)
	v_sub_f32_e32 v137, v137, v240
	v_sub_f32_e32 v136, v136, v240
	v_sub_f32_e32 v139, v139, v240
	v_sub_f32_e32 v138, v138, v240
	v_pk_mul_f32 v[138:139], v[240:241], v[138:139] op_sel:[1,0]
	v_pk_mul_f32 v[136:137], v[240:241], v[136:137] op_sel:[1,0]
	v_pk_fma_f32 v[138:139], v[152:153], v[138:139], v[78:79]
	v_pk_fma_f32 v[136:137], v[154:155], v[136:137], v[76:77]
	v_pk_fma_f32 v[138:139], v[134:135], s[78:79], v[138:139] op_sel_hi:[1,0,1]
	v_pk_fma_f32 v[136:137], v[132:133], s[78:79], v[136:137] op_sel_hi:[1,0,1]
	global_store_dwordx4 v[244:245], v[136:139], off
	s_nop 1
	v_sub_f32_e32 v137, v213, v240
	v_sub_f32_e32 v136, v212, v240
	v_sub_f32_e32 v139, v215, v240
	v_sub_f32_e32 v138, v214, v240
	v_pk_mul_f32 v[138:139], v[240:241], v[138:139] op_sel:[1,0]
	v_pk_mul_f32 v[136:137], v[240:241], v[136:137] op_sel:[1,0]
	v_pk_fma_f32 v[138:139], v[148:149], v[138:139], v[74:75]
	v_pk_fma_f32 v[136:137], v[150:151], v[136:137], v[72:73]
	v_add_u32_e32 v212, 0x50010, v194
	v_mov_b32_e32 v213, v159
	v_pk_fma_f32 v[138:139], v[130:131], s[78:79], v[138:139] op_sel_hi:[1,0,1]
	v_pk_fma_f32 v[136:137], v[128:129], s[78:79], v[136:137] op_sel_hi:[1,0,1]
	v_lshl_add_u64 v[212:213], v[212:213], 2, s[90:91]
	global_store_dwordx4 v[212:213], v[136:139], off
	s_nop 1
	v_sub_f32_e32 v137, v207, v242
	v_sub_f32_e32 v136, v206, v242
	v_sub_f32_e32 v139, v209, v242
	v_sub_f32_e32 v138, v208, v242
	v_pk_mul_f32 v[136:137], v[242:243], v[136:137] op_sel:[1,0]
	v_pk_mul_f32 v[138:139], v[242:243], v[138:139] op_sel:[1,0]
	v_pk_fma_f32 v[136:137], v[154:155], v[136:137], v[68:69]
	v_pk_fma_f32 v[138:139], v[152:153], v[138:139], v[70:71]
	v_pk_fma_f32 v[132:133], v[132:133], s[78:79], v[136:137] op_sel_hi:[1,0,1]
	v_add_u32_e32 v136, 0x58000, v194
	v_mov_b32_e32 v137, v159
	v_pk_fma_f32 v[134:135], v[134:135], s[78:79], v[138:139] op_sel_hi:[1,0,1]
	v_lshl_add_u64 v[136:137], v[136:137], 2, s[90:91]
	global_store_dwordx4 v[136:137], v[132:135], off
	s_nop 1
	v_sub_f32_e32 v133, v217, v242
	v_sub_f32_e32 v132, v216, v242
	v_sub_f32_e32 v135, v219, v242
	v_sub_f32_e32 v134, v218, v242
	v_pk_mul_f32 v[132:133], v[242:243], v[132:133] op_sel:[1,0]
	v_pk_mul_f32 v[134:135], v[242:243], v[134:135] op_sel:[1,0]
	v_pk_fma_f32 v[132:133], v[150:151], v[132:133], v[64:65]
	v_pk_fma_f32 v[134:135], v[148:149], v[134:135], v[66:67]
	v_pk_fma_f32 v[128:129], v[128:129], s[78:79], v[132:133] op_sel_hi:[1,0,1]
	v_add_u32_e32 v132, 0x58010, v194
	v_mov_b32_e32 v133, v159
	v_pk_fma_f32 v[130:131], v[130:131], s[78:79], v[134:135] op_sel_hi:[1,0,1]
	v_lshl_add_u64 v[132:133], v[132:133], 2, s[90:91]
	global_store_dwordx4 v[132:133], v[128:131], off
	global_load_dwordx4 v[128:131], v[140:141], off offset:512
	v_add_u32_e32 v136, v232, v230
	v_mov_b32_e32 v137, v159
	v_lshl_add_u64 v[136:137], v[136:137], 2, s[88:89]
	s_waitcnt vmcnt(0)
;     template <bool LN, int BJ, int LO, int HI> DI void batch(const f32x4 (&acc)[2][2][4][2], unsigned row0, unsigned col0, const f32x4 (&gv)[2], const f32x4 (&bv)[2]) const {
;     ...
;         for (int i = LO; i < HI; ++i) { const int ai = i >> 3, m = (i >> 1) & 3, n = i & 1; const unsigned row = row0 + ai * HALF + m * 16;
;             if (n == 0) { mean[(i - LO) >> 1] = 0.f; rstd[(i - LO) >> 1] = 1.f;
;                 if (LN) { const float2 st = *(const float2*)(stats + row * 2u); mean[(i - LO) >> 1] = st.x; rstd[(i - LO) >> 1] = st.y; } }
;             r[i - LO] = *(const f32x4*)(src + (row * (unsigned)DM + col0 + BJ * HALF + n * 16)); }
; #pragma unroll
;         for (int i = LO; i < HI; ++i) { const int ai = i >> 3, m = (i >> 1) & 3, n = i & 1; const unsigned row = row0 + ai * HALF + m * 16;
;             *(f32x4*)(Y + (row * (unsigned)DM + col0 + BJ * HALF + n * 16)) = acc[ai][BJ][m][n] + ((r[i - LO] - mean[(i - LO) >> 1]) * rstd[(i - LO) >> 1]) * gv[n] + bv[n]; }
;     template <bool LN, int BJ> DI void load_gb(unsigned col0, f32x4 (&gv)[2], f32x4 (&bv)[2]) const {
; #pragma unroll
;         for (int n = 0; n < 2; ++n) {
;             if (LN) { gv[n] = *(const f32x4*)(gam + col0 + BJ * HALF + n * 16) * ALPHA; bv[n] = *(const f32x4*)(bet + col0 + BJ * HALF + n * 16) * ALPHA; }
;             else { gv[n] = (f32x4){ALPHA, ALPHA, ALPHA, ALPHA}; bv[n] = (f32x4){0.f, 0.f, 0.f, 0.f}; }
;         }
	v_pk_mul_f32 v[212:213], v[130:131], s[78:79] op_sel_hi:[1,0]
	v_pk_mul_f32 v[214:215], v[128:129], s[78:79] op_sel_hi:[1,0]
	global_load_dwordx4 v[132:135], v[142:143], off offset:512
	global_load_dwordx4 v[128:131], v[140:141], off offset:576
	s_waitcnt vmcnt(0)
	v_pk_mul_f32 v[206:207], v[130:131], s[78:79] op_sel_hi:[1,0]
	v_pk_mul_f32 v[208:209], v[128:129], s[78:79] op_sel_hi:[1,0]
	global_load_dwordx4 v[128:131], v[142:143], off offset:576
	global_load_dwordx2 v[220:221], v[144:145], off
	global_load_dwordx4 v[240:243], v[136:137], off
	v_add_u32_e32 v136, v232, v229
	v_mov_b32_e32 v137, v159
	v_lshl_add_u64 v[136:137], v[136:137], 2, s[88:89]
	global_load_dwordx4 v[244:247], v[136:137], off
	global_load_dwordx2 v[218:219], v[146:147], off
	v_add_u32_e32 v136, v195, v230
	v_mov_b32_e32 v137, v159
	v_lshl_add_u64 v[136:137], v[136:137], 2, s[88:89]
	global_load_dwordx4 v[248:251], v[136:137], off
	v_add_u32_e32 v136, v195, v229
	v_mov_b32_e32 v137, v159
	v_lshl_add_u64 v[136:137], v[136:137], 2, s[88:89]
	global_load_dwordx4 v[152:155], v[136:137], off
	global_load_dwordx2 v[216:217], v[200:201], off
	v_add_u32_e32 v136, v236, v230
	v_mov_b32_e32 v137, v159
	v_lshl_add_u64 v[136:137], v[136:137], 2, s[88:89]
	global_load_dwordx4 v[148:151], v[136:137], off
	v_add_u32_e32 v136, v236, v229
	v_mov_b32_e32 v137, v159
	v_lshl_add_u64 v[136:137], v[136:137], 2, s[88:89]
	global_load_dwordx4 v[144:147], v[136:137], off
	global_load_dwordx2 v[200:201], v[202:203], off
	v_add_u32_e32 v136, v235, v230
	v_mov_b32_e32 v137, v159
	v_lshl_add_u64 v[136:137], v[136:137], 2, s[88:89]
	global_load_dwordx4 v[140:143], v[136:137], off
	v_add_u32_e32 v136, v235, v229
	v_mov_b32_e32 v137, v159
	v_lshl_add_u64 v[136:137], v[136:137], 2, s[88:89]
	global_load_dwordx4 v[136:139], v[136:137], off
	v_add_u32_e32 v202, 0x80, v194
	v_mov_b32_e32 v203, v159
	v_lshl_add_u64 v[202:203], v[202:203], 2, s[90:91]
	s_waitcnt vmcnt(0)
	v_sub_f32_e32 v241, v241, v220
	v_sub_f32_e32 v240, v240, v220
	v_sub_f32_e32 v243, v243, v220
	v_sub_f32_e32 v242, v242, v220
	v_pk_mul_f32 v[242:243], v[220:221], v[242:243] op_sel:[1,0]
	v_pk_mul_f32 v[240:241], v[220:221], v[240:241] op_sel:[1,0]
	v_pk_fma_f32 v[242:243], v[212:213], v[242:243], v[62:63]
	v_pk_fma_f32 v[240:241], v[214:215], v[240:241], v[60:61]
	v_pk_fma_f32 v[242:243], v[134:135], s[78:79], v[242:243] op_sel_hi:[1,0,1]
	v_pk_fma_f32 v[240:241], v[132:133], s[78:79], v[240:241] op_sel_hi:[1,0,1]
	global_store_dwordx4 v[202:203], v[240:243], off
	v_sub_f32_e32 v203, v245, v220
	v_sub_f32_e32 v202, v244, v220
	v_sub_f32_e32 v241, v247, v220
	v_sub_f32_e32 v240, v246, v220
	v_pk_mul_f32 v[202:203], v[220:221], v[202:203] op_sel:[1,0]
	v_pk_mul_f32 v[240:241], v[220:221], v[240:241] op_sel:[1,0]
	v_pk_fma_f32 v[202:203], v[208:209], v[202:203], v[56:57]
	v_pk_fma_f32 v[220:221], v[206:207], v[240:241], v[58:59]
	v_pk_fma_f32 v[240:241], v[128:129], s[78:79], v[202:203] op_sel_hi:[1,0,1]
	v_add_u32_e32 v202, 0x90, v194
	v_mov_b32_e32 v203, v159
	v_pk_fma_f32 v[242:243], v[130:131], s[78:79], v[220:221] op_sel_hi:[1,0,1]
	v_lshl_add_u64 v[202:203], v[202:203], 2, s[90:91]
	global_store_dwordx4 v[202:203], v[240:243], off
	v_sub_f32_e32 v203, v249, v218
	v_sub_f32_e32 v202, v248, v218
	v_sub_f32_e32 v221, v251, v218
	v_sub_f32_e32 v220, v250, v218
	v_pk_mul_f32 v[202:203], v[218:219], v[202:203] op_sel:[1,0]
	v_pk_mul_f32 v[220:221], v[218:219], v[220:221] op_sel:[1,0]
	v_pk_fma_f32 v[202:203], v[214:215], v[202:203], v[52:53]
	v_pk_fma_f32 v[220:221], v[212:213], v[220:221], v[54:55]
	v_pk_fma_f32 v[240:241], v[132:133], s[78:79], v[202:203] op_sel_hi:[1,0,1]
	v_add_u32_e32 v202, 0x8080, v194
	v_mov_b32_e32 v203, v159
	v_sub_f32_e32 v153, v153, v218
	v_sub_f32_e32 v152, v152, v218
	v_sub_f32_e32 v155, v155, v218
	v_sub_f32_e32 v154, v154, v218
	v_pk_fma_f32 v[242:243], v[134:135], s[78:79], v[220:221] op_sel_hi:[1,0,1]
	v_lshl_add_u64 v[202:203], v[202:203], 2, s[90:91]
	v_pk_mul_f32 v[154:155], v[218:219], v[154:155] op_sel:[1,0]
	v_pk_mul_f32 v[152:153], v[218:219], v[152:153] op_sel:[1,0]
	global_store_dwordx4 v[202:203], v[240:243], off
	v_pk_fma_f32 v[152:153], v[208:209], v[152:153], v[48:49]
	v_pk_fma_f32 v[154:155], v[206:207], v[154:155], v[50:51]
	v_add_u32_e32 v202, 0x8090, v194
	v_mov_b32_e32 v203, v159
	v_sub_f32_e32 v149, v149, v216
	v_sub_f32_e32 v148, v148, v216
	v_sub_f32_e32 v151, v151, v216
	v_sub_f32_e32 v150, v150, v216
	v_pk_fma_f32 v[154:155], v[130:131], s[78:79], v[154:155] op_sel_hi:[1,0,1]
	v_pk_fma_f32 v[152:153], v[128:129], s[78:79], v[152:153] op_sel_hi:[1,0,1]
	v_lshl_add_u64 v[202:203], v[202:203], 2, s[90:91]
	v_pk_mul_f32 v[150:151], v[216:217], v[150:151] op_sel:[1,0]
	v_pk_mul_f32 v[148:149], v[216:217], v[148:149] op_sel:[1,0]
	global_store_dwordx4 v[202:203], v[152:155], off
	v_pk_fma_f32 v[148:149], v[214:215], v[148:149], v[44:45]
	v_pk_fma_f32 v[150:151], v[212:213], v[150:151], v[46:47]
	v_add_u32_e32 v152, 0x10080, v194
	v_mov_b32_e32 v153, v159
	v_sub_f32_e32 v145, v145, v216
	v_sub_f32_e32 v144, v144, v216
	v_sub_f32_e32 v147, v147, v216
	v_sub_f32_e32 v146, v146, v216
	v_pk_fma_f32 v[150:151], v[134:135], s[78:79], v[150:151] op_sel_hi:[1,0,1]
	v_pk_fma_f32 v[148:149], v[132:133], s[78:79], v[148:149] op_sel_hi:[1,0,1]
	v_lshl_add_u64 v[152:153], v[152:153], 2, s[90:91]
	v_pk_mul_f32 v[146:147], v[216:217], v[146:147] op_sel:[1,0]
	v_pk_mul_f32 v[144:145], v[216:217], v[144:145] op_sel:[1,0]
	global_store_dwordx4 v[152:153], v[148:151], off
	v_pk_fma_f32 v[144:145], v[208:209], v[144:145], v[40:41]
	v_pk_fma_f32 v[146:147], v[206:207], v[146:147], v[42:43]
;     template <bool LN, int BJ, int LO, int HI> DI void batch(const f32x4 (&acc)[2][2][4][2], unsigned row0, unsigned col0, const f32x4 (&gv)[2], const f32x4 (&bv)[2]) const {
;     ...
;         for (int i = LO; i < HI; ++i) { const int ai = i >> 3, m = (i >> 1) & 3, n = i & 1; const unsigned row = row0 + ai * HALF + m * 16;
;             if (n == 0) { mean[(i - LO) >> 1] = 0.f; rstd[(i - LO) >> 1] = 1.f;
;                 if (LN) { const float2 st = *(const float2*)(stats + row * 2u); mean[(i - LO) >> 1] = st.x; rstd[(i - LO) >> 1] = st.y; } }
;             r[i - LO] = *(const f32x4*)(src + (row * (unsigned)DM + col0 + BJ * HALF + n * 16)); }
; #pragma unroll
;         for (int i = LO; i < HI; ++i) { const int ai = i >> 3, m = (i >> 1) & 3, n = i & 1; const unsigned row = row0 + ai * HALF + m * 16;
;             *(f32x4*)(Y + (row * (unsigned)DM + col0 + BJ * HALF + n * 16)) = acc[ai][BJ][m][n] + ((r[i - LO] - mean[(i - LO) >> 1]) * rstd[(i - LO) >> 1]) * gv[n] + bv[n]; }
	v_add_u32_e32 v148, 0x10090, v194
	v_mov_b32_e32 v149, v159
	v_sub_f32_e32 v141, v141, v200
	v_sub_f32_e32 v140, v140, v200
	v_sub_f32_e32 v143, v143, v200
	v_sub_f32_e32 v142, v142, v200
	v_pk_fma_f32 v[146:147], v[130:131], s[78:79], v[146:147] op_sel_hi:[1,0,1]
	v_pk_fma_f32 v[144:145], v[128:129], s[78:79], v[144:145] op_sel_hi:[1,0,1]
	v_lshl_add_u64 v[148:149], v[148:149], 2, s[90:91]
	v_pk_mul_f32 v[142:143], v[200:201], v[142:143] op_sel:[1,0]
	v_pk_mul_f32 v[140:141], v[200:201], v[140:141] op_sel:[1,0]
	global_store_dwordx4 v[148:149], v[144:147], off
	v_pk_fma_f32 v[140:141], v[214:215], v[140:141], v[36:37]
	v_pk_fma_f32 v[142:143], v[212:213], v[142:143], v[38:39]
	v_add_u32_e32 v144, 0x18080, v194
	v_mov_b32_e32 v145, v159
	v_sub_f32_e32 v137, v137, v200
	v_sub_f32_e32 v136, v136, v200
	v_sub_f32_e32 v139, v139, v200
	v_sub_f32_e32 v138, v138, v200
	v_pk_fma_f32 v[142:143], v[134:135], s[78:79], v[142:143] op_sel_hi:[1,0,1]
	v_pk_fma_f32 v[140:141], v[132:133], s[78:79], v[140:141] op_sel_hi:[1,0,1]
	v_lshl_add_u64 v[144:145], v[144:145], 2, s[90:91]
	v_pk_mul_f32 v[138:139], v[200:201], v[138:139] op_sel:[1,0]
	v_pk_mul_f32 v[136:137], v[200:201], v[136:137] op_sel:[1,0]
	global_store_dwordx4 v[144:145], v[140:143], off
	v_pk_fma_f32 v[136:137], v[208:209], v[136:137], v[32:33]
	v_pk_fma_f32 v[138:139], v[206:207], v[138:139], v[34:35]
	v_add_u32_e32 v140, 0x18090, v194
	v_mov_b32_e32 v141, v159
	v_pk_fma_f32 v[138:139], v[130:131], s[78:79], v[138:139] op_sel_hi:[1,0,1]
	v_pk_fma_f32 v[136:137], v[128:129], s[78:79], v[136:137] op_sel_hi:[1,0,1]
	v_lshl_add_u64 v[140:141], v[140:141], 2, s[90:91]
	global_store_dwordx4 v[140:141], v[136:139], off
	s_nop 1
	v_add_u32_e32 v136, v233, v230
	v_mov_b32_e32 v137, v159
	v_lshl_add_u64 v[136:137], v[136:137], 2, s[88:89]
	global_load_dwordx2 v[220:221], v[196:197], off
	global_load_dwordx4 v[216:219], v[136:137], off
	v_add_u32_e32 v136, v233, v229
	v_mov_b32_e32 v137, v159
	v_lshl_add_u64 v[136:137], v[136:137], 2, s[88:89]
	global_load_dwordx4 v[240:243], v[136:137], off
	global_load_dwordx2 v[200:201], v[198:199], off
	v_add_u32_e32 v136, v234, v230
	v_mov_b32_e32 v137, v159
	v_lshl_add_u64 v[136:137], v[136:137], 2, s[88:89]
	global_load_dwordx4 v[244:247], v[136:137], off
	v_add_u32_e32 v136, v234, v229
	v_mov_b32_e32 v137, v159
	v_lshl_add_u64 v[136:137], v[136:137], 2, s[88:89]
	global_load_dwordx4 v[152:155], v[136:137], off
	global_load_dwordx2 v[198:199], v[204:205], off
	v_add_u32_e32 v136, v237, v230
	v_mov_b32_e32 v137, v159
	v_lshl_add_u64 v[136:137], v[136:137], 2, s[88:89]
	global_load_dwordx4 v[148:151], v[136:137], off
	v_add_u32_e32 v136, v237, v229
	v_mov_b32_e32 v137, v159
	v_lshl_add_u64 v[136:137], v[136:137], 2, s[88:89]
	global_load_dwordx4 v[144:147], v[136:137], off
	global_load_dwordx2 v[196:197], v[210:211], off
	v_add_u32_e32 v136, v238, v230
	v_mov_b32_e32 v137, v159
	v_lshl_add_u64 v[136:137], v[136:137], 2, s[88:89]
	global_load_dwordx4 v[140:143], v[136:137], off
	v_add_u32_e32 v136, v238, v229
	v_mov_b32_e32 v137, v159
	v_lshl_add_u64 v[136:137], v[136:137], 2, s[88:89]
	global_load_dwordx4 v[136:139], v[136:137], off
	v_add_u32_e32 v210, 0x40080, v194
	v_mov_b32_e32 v211, v159
	v_lshl_add_u64 v[210:211], v[210:211], 2, s[90:91]
	s_waitcnt vmcnt(0)
;     template <bool LN, int BJ, int LO, int HI> DI void batch(const f32x4 (&acc)[2][2][4][2], unsigned row0, unsigned col0, const f32x4 (&gv)[2], const f32x4 (&bv)[2]) const {
;     ...
;         for (int i = LO; i < HI; ++i) { const int ai = i >> 3, m = (i >> 1) & 3, n = i & 1; const unsigned row = row0 + ai * HALF + m * 16;
;             if (n == 0) { mean[(i - LO) >> 1] = 0.f; rstd[(i - LO) >> 1] = 1.f;
;                 if (LN) { const float2 st = *(const float2*)(stats + row * 2u); mean[(i - LO) >> 1] = st.x; rstd[(i - LO) >> 1] = st.y; } }
;             r[i - LO] = *(const f32x4*)(src + (row * (unsigned)DM + col0 + BJ * HALF + n * 16)); }
; #pragma unroll
;         for (int i = LO; i < HI; ++i) { const int ai = i >> 3, m = (i >> 1) & 3, n = i & 1; const unsigned row = row0 + ai * HALF + m * 16;
;             *(f32x4*)(Y + (row * (unsigned)DM + col0 + BJ * HALF + n * 16)) = acc[ai][BJ][m][n] + ((r[i - LO] - mean[(i - LO) >> 1]) * rstd[(i - LO) >> 1]) * gv[n] + bv[n]; }
	v_sub_f32_e32 v203, v217, v220
	v_sub_f32_e32 v202, v216, v220
	v_sub_f32_e32 v205, v219, v220
	v_sub_f32_e32 v204, v218, v220
	v_pk_mul_f32 v[204:205], v[220:221], v[204:205] op_sel:[1,0]
	v_pk_mul_f32 v[202:203], v[220:221], v[202:203] op_sel:[1,0]
	v_pk_fma_f32 v[204:205], v[212:213], v[204:205], v[30:31]
	v_pk_fma_f32 v[202:203], v[214:215], v[202:203], v[28:29]
	v_pk_fma_f32 v[204:205], v[134:135], s[78:79], v[204:205] op_sel_hi:[1,0,1]
	v_pk_fma_f32 v[202:203], v[132:133], s[78:79], v[202:203] op_sel_hi:[1,0,1]
	global_store_dwordx4 v[210:211], v[202:205], off
	v_add_u32_e32 v210, 0x40090, v194
	v_mov_b32_e32 v211, v159
	v_sub_f32_e32 v203, v241, v220
	v_sub_f32_e32 v202, v240, v220
	v_sub_f32_e32 v205, v243, v220
	v_sub_f32_e32 v204, v242, v220
	v_pk_mul_f32 v[204:205], v[220:221], v[204:205] op_sel:[1,0]
	v_pk_mul_f32 v[202:203], v[220:221], v[202:203] op_sel:[1,0]
	v_pk_fma_f32 v[204:205], v[206:207], v[204:205], v[26:27]
	v_pk_fma_f32 v[202:203], v[208:209], v[202:203], v[24:25]
	v_pk_fma_f32 v[204:205], v[130:131], s[78:79], v[204:205] op_sel_hi:[1,0,1]
	v_pk_fma_f32 v[202:203], v[128:129], s[78:79], v[202:203] op_sel_hi:[1,0,1]
	v_lshl_add_u64 v[210:211], v[210:211], 2, s[90:91]
	global_store_dwordx4 v[210:211], v[202:205], off
	v_sub_f32_e32 v149, v149, v198
	v_sub_f32_e32 v148, v148, v198
	v_sub_f32_e32 v203, v245, v200
	v_sub_f32_e32 v202, v244, v200
	v_sub_f32_e32 v141, v141, v196
	v_sub_f32_e32 v140, v140, v196
	v_sub_f32_e32 v205, v247, v200
	v_sub_f32_e32 v204, v246, v200
	v_pk_mul_f32 v[202:203], v[200:201], v[202:203] op_sel:[1,0]
	v_sub_f32_e32 v151, v151, v198
	v_sub_f32_e32 v150, v150, v198
	v_pk_mul_f32 v[148:149], v[198:199], v[148:149] op_sel:[1,0]
	v_sub_f32_e32 v143, v143, v196
	v_sub_f32_e32 v142, v142, v196
	v_pk_mul_f32 v[140:141], v[196:197], v[140:141] op_sel:[1,0]
	v_pk_mul_f32 v[204:205], v[200:201], v[204:205] op_sel:[1,0]
	v_pk_fma_f32 v[202:203], v[214:215], v[202:203], v[20:21]
	v_sub_f32_e32 v153, v153, v200
	v_sub_f32_e32 v152, v152, v200
	v_sub_f32_e32 v155, v155, v200
	v_sub_f32_e32 v154, v154, v200
	v_pk_mul_f32 v[150:151], v[198:199], v[150:151] op_sel:[1,0]
	v_pk_fma_f32 v[148:149], v[214:215], v[148:149], v[12:13]
	v_pk_mul_f32 v[142:143], v[196:197], v[142:143] op_sel:[1,0]
	v_pk_fma_f32 v[140:141], v[214:215], v[140:141], v[4:5]
	v_pk_fma_f32 v[204:205], v[212:213], v[204:205], v[22:23]
	v_pk_fma_f32 v[202:203], v[132:133], s[78:79], v[202:203] op_sel_hi:[1,0,1]
	v_pk_mul_f32 v[154:155], v[200:201], v[154:155] op_sel:[1,0]
	v_pk_mul_f32 v[152:153], v[200:201], v[152:153] op_sel:[1,0]
	v_pk_fma_f32 v[150:151], v[212:213], v[150:151], v[14:15]
	v_pk_fma_f32 v[148:149], v[132:133], s[78:79], v[148:149] op_sel_hi:[1,0,1]
	v_pk_fma_f32 v[142:143], v[212:213], v[142:143], v[6:7]
	v_pk_fma_f32 v[132:133], v[132:133], s[78:79], v[140:141] op_sel_hi:[1,0,1]
	v_add_u32_e32 v140, 0x58080, v194
	v_mov_b32_e32 v141, v159
	v_pk_fma_f32 v[204:205], v[134:135], s[78:79], v[204:205] op_sel_hi:[1,0,1]
	v_pk_fma_f32 v[152:153], v[208:209], v[152:153], v[16:17]
	v_pk_fma_f32 v[154:155], v[206:207], v[154:155], v[18:19]
	v_add_u32_e32 v200, 0x48090, v194
	v_mov_b32_e32 v201, v159
	v_pk_fma_f32 v[150:151], v[134:135], s[78:79], v[150:151] op_sel_hi:[1,0,1]
	v_pk_fma_f32 v[134:135], v[134:135], s[78:79], v[142:143] op_sel_hi:[1,0,1]
	v_lshl_add_u64 v[140:141], v[140:141], 2, s[90:91]
	v_pk_fma_f32 v[154:155], v[130:131], s[78:79], v[154:155] op_sel_hi:[1,0,1]
	v_pk_fma_f32 v[152:153], v[128:129], s[78:79], v[152:153] op_sel_hi:[1,0,1]
	v_lshl_add_u64 v[200:201], v[200:201], 2, s[90:91]
	v_sub_f32_e32 v145, v145, v198
	v_sub_f32_e32 v144, v144, v198
	global_store_dwordx4 v[140:141], v[132:135], off
	global_store_dwordx4 v[200:201], v[152:155], off
	v_sub_f32_e32 v147, v147, v198
	v_sub_f32_e32 v133, v137, v196
	v_sub_f32_e32 v132, v136, v196
	v_add_u32_e32 v152, 0x50080, v194
	v_mov_b32_e32 v153, v159
	v_sub_f32_e32 v146, v146, v198
	v_pk_mul_f32 v[144:145], v[198:199], v[144:145] op_sel:[1,0]
	v_sub_f32_e32 v135, v139, v196
	v_sub_f32_e32 v134, v138, v196
	v_pk_mul_f32 v[132:133], v[196:197], v[132:133] op_sel:[1,0]
	v_lshl_add_u64 v[152:153], v[152:153], 2, s[90:91]
	v_pk_mul_f32 v[146:147], v[198:199], v[146:147] op_sel:[1,0]
	v_pk_fma_f32 v[144:145], v[208:209], v[144:145], v[8:9]
	v_pk_mul_f32 v[134:135], v[196:197], v[134:135] op_sel:[1,0]
	v_pk_fma_f32 v[132:133], v[208:209], v[132:133], v[0:1]
	v_add_u32_e32 v210, 0x48080, v194
	v_mov_b32_e32 v211, v159
	global_store_dwordx4 v[152:153], v[148:151], off
	v_pk_fma_f32 v[146:147], v[206:207], v[146:147], v[10:11]
	v_pk_fma_f32 v[144:145], v[128:129], s[78:79], v[144:145] op_sel_hi:[1,0,1]
	v_add_u32_e32 v148, 0x50090, v194
	v_mov_b32_e32 v149, v159
	v_pk_fma_f32 v[134:135], v[206:207], v[134:135], v[2:3]
	v_pk_fma_f32 v[128:129], v[128:129], s[78:79], v[132:133] op_sel_hi:[1,0,1]
	v_add_u32_e32 v132, 0x58090, v194
	v_mov_b32_e32 v133, v159
	v_lshl_add_u64 v[210:211], v[210:211], 2, s[90:91]
	v_pk_fma_f32 v[146:147], v[130:131], s[78:79], v[146:147] op_sel_hi:[1,0,1]
	v_lshl_add_u64 v[148:149], v[148:149], 2, s[90:91]
	v_pk_fma_f32 v[130:131], v[130:131], s[78:79], v[134:135] op_sel_hi:[1,0,1]
	v_lshl_add_u64 v[132:133], v[132:133], 2, s[90:91]
	global_store_dwordx4 v[210:211], v[202:205], off
	global_store_dwordx4 v[148:149], v[144:147], off
	global_store_dwordx4 v[132:133], v[128:131], off
	s_mov_b64 s[24:25], 0
	s_branch .LBB0_324
